# G1 forward-substitution: L-row LDS reads software-pipelined 12 deep (counted lgkmcnt) instead of read->lgkmcnt(0)->4 fma
# speedup vs baseline: 1.0156x; 1.0156x over previous
; #define LAS __attribute__((address_space(3)))
; __device__ __forceinline__ bf16_t f2bf(float f) { return (bf16_t)(pk2(f, f) & 0xFFFFu); }
; __device__ NOINL void g1_phase(const LAS Params* lp, int l, LAS unsigned char* lds) {
;     ...
;         if (w < 6) {
;             const int s = w >> 1, dir = w & 1;
;             const LAS float* Ld = (const LAS float*)(lds + s * SLOT + 18432) + dir * 4096;
;             float xv[64];
; #pragma unroll
;             for (int i = 0; i < 64; ++i) {
;                 float s0 = (i == lane) ? 1.f : 0.f, s1 = 0.f, s2 = 0.f, s3 = 0.f;
; #pragma unroll
;                 for (int j4 = 0; j4 < (i + 3) / 4; ++j4) {
;                     const f32x4 lv = *(const LAS f32x4*)(Ld + i * 64 + j4 * 4);
;                     if (j4 * 4 + 0 < i) s0 -= lv[0] * xv[j4 * 4 + 0];
;                     if (j4 * 4 + 1 < i) s1 -= lv[1] * xv[j4 * 4 + 1];
;                     if (j4 * 4 + 2 < i) s2 -= lv[2] * xv[j4 * 4 + 2];
;                     if (j4 * 4 + 3 < i) s3 -= lv[3] * xv[j4 * 4 + 3];
;                 }
;                 xv[i] = (s0 + s1) + (s2 + s3);
;             }
;             bf16_t* Tg = p.Tbuf + ((((size_t)b * 4 + h) * 36 + c3 * 3 + s) * 2 + dir) * 4096;
; #pragma unroll
;             for (int i = 0; i < 64; ++i) Tg[i * 64 + lane] = f2bf(xv[i]);
.LBB0_1065:
	s_waitcnt lgkmcnt(0)
	s_barrier
	s_and_saveexec_b64 s[58:59], vcc
	s_cbranch_execz .LBB0_1044
	ds_read_b128 v[100:103], v28 offset:18688
	ds_read_b128 v[104:107], v28 offset:18944
	ds_read_b128 v[108:111], v28 offset:19200
	ds_read_b128 v[112:115], v28 offset:19456
	ds_read_b128 v[116:119], v28 offset:19712
	ds_read_b128 v[120:123], v28 offset:19728
	ds_read_b128 v[124:127], v28 offset:19968
	ds_read_b128 v[128:131], v28 offset:19984
	ds_read_b128 v[132:135], v28 offset:20224
	ds_read_b128 v[136:139], v28 offset:20240
	ds_read_b128 v[140:143], v28 offset:20480
	ds_read_b128 v[144:147], v28 offset:20496
	s_lshl_b32 s0, s67, 2
	s_or_b32 s0, s0, s68
	v_mad_i64_i32 v[18:19], s[0:1], s0, 36, v[18:19]
	v_mbcnt_lo_u32_b32 v156, -1, 0
	v_mbcnt_hi_u32_b32 v156, -1, v156
	v_lshlrev_b64 v[18:19], 14, v[18:19]
	v_lshl_add_u64 v[18:19], v[16:17], 0, v[18:19]
	v_add_co_u32_e64 v8, s[56:57], s83, v18
	s_nop 1
	v_addc_co_u32_e64 v9, s[56:57], 0, v19, s[56:57]
	global_store_short v[18:19], v95, off
	v_cmp_eq_u32_e64 s[56:57], 1, v156
	s_waitcnt lgkmcnt(11)
	s_nop 0
	v_cndmask_b32_e64 v152, 0, 1.0, s[56:57]
	v_fma_f32 v152, -v31, v100, v152
	ds_read_b128 v[100:103], v28 offset:20736
	v_mov_b32_e32 v32, v152
	v_cvt_pk_bf16_f32 v158, v32, v32
	global_store_short v[18:19], v158, off offset:128
	v_cmp_eq_u32_e64 s[56:57], 2, v156
	s_waitcnt lgkmcnt(11)
	s_nop 0
	v_cndmask_b32_e64 v148, 0, 1.0, s[56:57]
	v_fma_f32 v148, -v31, v104, v148
	v_fma_f32 v149, -v105, v32, 0
	ds_read_b128 v[104:107], v28 offset:20752
	v_add_f32_e32 v33, v148, v149
	v_cvt_pk_bf16_f32 v159, v33, v33
	global_store_short v[18:19], v159, off offset:256
	v_cmp_eq_u32_e64 s[56:57], 3, v156
	s_waitcnt lgkmcnt(11)
	s_nop 0
	v_cndmask_b32_e64 v152, 0, 1.0, s[56:57]
	v_fma_f32 v152, -v31, v108, v152
	v_fma_f32 v153, -v109, v32, 0
	v_fma_f32 v154, -v110, v33, 0
	ds_read_b128 v[108:111], v28 offset:20768
	v_add_f32_e32 v34, v152, v153
	v_add_f32_e32 v34, v34, v154
	v_cvt_pk_bf16_f32 v160, v34, v34
	global_store_short v[18:19], v160, off offset:384
	v_cmp_eq_u32_e64 s[56:57], 4, v156
	s_waitcnt lgkmcnt(11)
	s_nop 0
	v_cndmask_b32_e64 v148, 0, 1.0, s[56:57]
	v_fma_f32 v148, -v31, v112, v148
	v_fma_f32 v149, -v113, v32, 0
	v_fma_f32 v150, -v114, v33, 0
	v_fma_f32 v151, -v115, v34, 0
	ds_read_b128 v[112:115], v28 offset:20992
	v_add_f32_e32 v148, v148, v149
	v_add_f32_e32 v150, v150, v151
	v_add_f32_e32 v35, v148, v150
	v_cvt_pk_bf16_f32 v157, v35, v35
	global_store_short v[18:19], v157, off offset:512
	v_cmp_eq_u32_e64 s[56:57], 5, v156
	s_waitcnt lgkmcnt(11)
	s_nop 0
	v_cndmask_b32_e64 v152, 0, 1.0, s[56:57]
	v_fma_f32 v152, -v31, v116, v152
	v_fma_f32 v153, -v117, v32, 0
	v_fma_f32 v154, -v118, v33, 0
	v_fma_f32 v155, -v119, v34, 0
	ds_read_b128 v[116:119], v28 offset:21008
	s_waitcnt lgkmcnt(11)
	v_fma_f32 v152, -v120, v35, v152
	ds_read_b128 v[120:123], v28 offset:21024
	v_add_f32_e32 v152, v152, v153
	v_add_f32_e32 v154, v154, v155
	v_add_f32_e32 v36, v152, v154
	v_cvt_pk_bf16_f32 v158, v36, v36
	global_store_short v[18:19], v158, off offset:640
	v_cmp_eq_u32_e64 s[56:57], 6, v156
	s_waitcnt lgkmcnt(11)
	s_nop 0
	v_cndmask_b32_e64 v148, 0, 1.0, s[56:57]
	v_fma_f32 v148, -v31, v124, v148
	v_fma_f32 v149, -v125, v32, 0
	v_fma_f32 v150, -v126, v33, 0
	v_fma_f32 v151, -v127, v34, 0
	ds_read_b128 v[124:127], v28 offset:21248
	s_waitcnt lgkmcnt(11)
	v_fma_f32 v148, -v128, v35, v148
	v_fma_f32 v149, -v129, v36, v149
	ds_read_b128 v[128:131], v28 offset:21264
	v_add_f32_e32 v148, v148, v149
	v_add_f32_e32 v150, v150, v151
	v_add_f32_e32 v37, v148, v150
	v_cvt_pk_bf16_f32 v159, v37, v37
	global_store_short v[18:19], v159, off offset:768
	v_cmp_eq_u32_e64 s[56:57], 7, v156
	s_waitcnt lgkmcnt(11)
	s_nop 0
	v_cndmask_b32_e64 v152, 0, 1.0, s[56:57]
	v_fma_f32 v152, -v31, v132, v152
	v_fma_f32 v153, -v133, v32, 0
	v_fma_f32 v154, -v134, v33, 0
	v_fma_f32 v155, -v135, v34, 0
	ds_read_b128 v[132:135], v28 offset:21280
	s_waitcnt lgkmcnt(11)
	v_fma_f32 v152, -v136, v35, v152
	v_fma_f32 v153, -v137, v36, v153
	v_fma_f32 v154, -v138, v37, v154
	ds_read_b128 v[136:139], v28 offset:21504
	v_add_f32_e32 v152, v152, v153
	v_add_f32_e32 v154, v154, v155
	v_add_f32_e32 v38, v152, v154
	v_cvt_pk_bf16_f32 v160, v38, v38
	global_store_short v[18:19], v160, off offset:896
	v_cmp_eq_u32_e64 s[56:57], 8, v156
	s_waitcnt lgkmcnt(11)
	s_nop 0
	v_cndmask_b32_e64 v148, 0, 1.0, s[56:57]
	v_fma_f32 v148, -v31, v140, v148
	v_fma_f32 v149, -v141, v32, 0
	v_fma_f32 v150, -v142, v33, 0
	v_fma_f32 v151, -v143, v34, 0
	ds_read_b128 v[140:143], v28 offset:21520
	s_waitcnt lgkmcnt(11)
	v_fma_f32 v148, -v144, v35, v148
	v_fma_f32 v149, -v145, v36, v149
	v_fma_f32 v150, -v146, v37, v150
	v_fma_f32 v151, -v147, v38, v151
	ds_read_b128 v[144:147], v28 offset:21536
	v_add_f32_e32 v148, v148, v149
	v_add_f32_e32 v150, v150, v151
	v_add_f32_e32 v39, v148, v150
	v_cvt_pk_bf16_f32 v157, v39, v39
	global_store_short v[18:19], v157, off offset:1024
	v_cmp_eq_u32_e64 s[56:57], 9, v156
	s_waitcnt lgkmcnt(11)
	s_nop 0
	v_cndmask_b32_e64 v152, 0, 1.0, s[56:57]
	v_fma_f32 v152, -v31, v100, v152
	v_fma_f32 v153, -v101, v32, 0
	v_fma_f32 v154, -v102, v33, 0
	v_fma_f32 v155, -v103, v34, 0
	ds_read_b128 v[100:103], v28 offset:21760
	s_waitcnt lgkmcnt(11)
	v_fma_f32 v152, -v104, v35, v152
	v_fma_f32 v153, -v105, v36, v153
	v_fma_f32 v154, -v106, v37, v154
	v_fma_f32 v155, -v107, v38, v155
	ds_read_b128 v[104:107], v28 offset:21776
	s_waitcnt lgkmcnt(11)
	v_fma_f32 v152, -v108, v39, v152
	ds_read_b128 v[108:111], v28 offset:21792
	v_add_f32_e32 v152, v152, v153
	v_add_f32_e32 v154, v154, v155
	v_add_f32_e32 v40, v152, v154
	v_cvt_pk_bf16_f32 v158, v40, v40
	global_store_short v[18:19], v158, off offset:1152
	v_cmp_eq_u32_e64 s[56:57], 10, v156
	s_waitcnt lgkmcnt(11)
; #define LAS __attribute__((address_space(3)))
; __device__ __forceinline__ bf16_t f2bf(float f) { return (bf16_t)(pk2(f, f) & 0xFFFFu); }
; __device__ NOINL void g1_phase(const LAS Params* lp, int l, LAS unsigned char* lds) {
;     ...
;             for (int i = 0; i < 64; ++i) {
;                 float s0 = (i == lane) ? 1.f : 0.f, s1 = 0.f, s2 = 0.f, s3 = 0.f;
; #pragma unroll
;                 for (int j4 = 0; j4 < (i + 3) / 4; ++j4) {
;                     const f32x4 lv = *(const LAS f32x4*)(Ld + i * 64 + j4 * 4);
;                     if (j4 * 4 + 0 < i) s0 -= lv[0] * xv[j4 * 4 + 0];
;                     if (j4 * 4 + 1 < i) s1 -= lv[1] * xv[j4 * 4 + 1];
;                     if (j4 * 4 + 2 < i) s2 -= lv[2] * xv[j4 * 4 + 2];
;                     if (j4 * 4 + 3 < i) s3 -= lv[3] * xv[j4 * 4 + 3];
;                 }
;                 xv[i] = (s0 + s1) + (s2 + s3);
;             }
;             bf16_t* Tg = p.Tbuf + ((((size_t)b * 4 + h) * 36 + c3 * 3 + s) * 2 + dir) * 4096;
; #pragma unroll
;             for (int i = 0; i < 64; ++i) Tg[i * 64 + lane] = f2bf(xv[i]);
	s_nop 0
	v_cndmask_b32_e64 v148, 0, 1.0, s[56:57]
	v_fma_f32 v148, -v31, v112, v148
	v_fma_f32 v149, -v113, v32, 0
	v_fma_f32 v150, -v114, v33, 0
	v_fma_f32 v151, -v115, v34, 0
	ds_read_b128 v[112:115], v28 offset:21808
	s_waitcnt lgkmcnt(11)
	v_fma_f32 v148, -v116, v35, v148
	v_fma_f32 v149, -v117, v36, v149
	v_fma_f32 v150, -v118, v37, v150
	v_fma_f32 v151, -v119, v38, v151
	ds_read_b128 v[116:119], v28 offset:22016
	s_waitcnt lgkmcnt(11)
	v_fma_f32 v148, -v120, v39, v148
	v_fma_f32 v149, -v121, v40, v149
	ds_read_b128 v[120:123], v28 offset:22032
	v_add_f32_e32 v148, v148, v149
	v_add_f32_e32 v150, v150, v151
	v_add_f32_e32 v41, v148, v150
	v_cvt_pk_bf16_f32 v159, v41, v41
	global_store_short v[18:19], v159, off offset:1280
	v_cmp_eq_u32_e64 s[56:57], 11, v156
	s_waitcnt lgkmcnt(11)
	s_nop 0
	v_cndmask_b32_e64 v152, 0, 1.0, s[56:57]
	v_fma_f32 v152, -v31, v124, v152
	v_fma_f32 v153, -v125, v32, 0
	v_fma_f32 v154, -v126, v33, 0
	v_fma_f32 v155, -v127, v34, 0
	ds_read_b128 v[124:127], v28 offset:22048
	s_waitcnt lgkmcnt(11)
	v_fma_f32 v152, -v128, v35, v152
	v_fma_f32 v153, -v129, v36, v153
	v_fma_f32 v154, -v130, v37, v154
	v_fma_f32 v155, -v131, v38, v155
	ds_read_b128 v[128:131], v28 offset:22064
	s_waitcnt lgkmcnt(11)
	v_fma_f32 v152, -v132, v39, v152
	v_fma_f32 v153, -v133, v40, v153
	v_fma_f32 v154, -v134, v41, v154
	ds_read_b128 v[132:135], v28 offset:22272
	v_add_f32_e32 v152, v152, v153
	v_add_f32_e32 v154, v154, v155
	v_add_f32_e32 v42, v152, v154
	v_cvt_pk_bf16_f32 v160, v42, v42
	global_store_short v[18:19], v160, off offset:1408
	v_cmp_eq_u32_e64 s[56:57], 12, v156
	s_waitcnt lgkmcnt(11)
	s_nop 0
	v_cndmask_b32_e64 v148, 0, 1.0, s[56:57]
	v_fma_f32 v148, -v31, v136, v148
	v_fma_f32 v149, -v137, v32, 0
	v_fma_f32 v150, -v138, v33, 0
	v_fma_f32 v151, -v139, v34, 0
	ds_read_b128 v[136:139], v28 offset:22288
	s_waitcnt lgkmcnt(11)
	v_fma_f32 v148, -v140, v35, v148
	v_fma_f32 v149, -v141, v36, v149
	v_fma_f32 v150, -v142, v37, v150
	v_fma_f32 v151, -v143, v38, v151
	ds_read_b128 v[140:143], v28 offset:22304
	s_waitcnt lgkmcnt(11)
	v_fma_f32 v148, -v144, v39, v148
	v_fma_f32 v149, -v145, v40, v149
	v_fma_f32 v150, -v146, v41, v150
	v_fma_f32 v151, -v147, v42, v151
	ds_read_b128 v[144:147], v28 offset:22320
	v_add_f32_e32 v148, v148, v149
	v_add_f32_e32 v150, v150, v151
	v_add_f32_e32 v43, v148, v150
	v_cvt_pk_bf16_f32 v157, v43, v43
	global_store_short v[18:19], v157, off offset:1536
	v_cmp_eq_u32_e64 s[56:57], 13, v156
	s_waitcnt lgkmcnt(11)
	s_nop 0
	v_cndmask_b32_e64 v152, 0, 1.0, s[56:57]
	v_fma_f32 v152, -v31, v100, v152
	v_fma_f32 v153, -v101, v32, 0
	v_fma_f32 v154, -v102, v33, 0
	v_fma_f32 v155, -v103, v34, 0
	ds_read_b128 v[100:103], v28 offset:22528
	s_waitcnt lgkmcnt(11)
	v_fma_f32 v152, -v104, v35, v152
	v_fma_f32 v153, -v105, v36, v153
	v_fma_f32 v154, -v106, v37, v154
	v_fma_f32 v155, -v107, v38, v155
	ds_read_b128 v[104:107], v28 offset:22544
	s_waitcnt lgkmcnt(11)
	v_fma_f32 v152, -v108, v39, v152
	v_fma_f32 v153, -v109, v40, v153
	v_fma_f32 v154, -v110, v41, v154
	v_fma_f32 v155, -v111, v42, v155
	ds_read_b128 v[108:111], v28 offset:22560
	s_waitcnt lgkmcnt(11)
	v_fma_f32 v152, -v112, v43, v152
	ds_read_b128 v[112:115], v28 offset:22576
	v_add_f32_e32 v152, v152, v153
	v_add_f32_e32 v154, v154, v155
	v_add_f32_e32 v44, v152, v154
	v_cvt_pk_bf16_f32 v158, v44, v44
	global_store_short v[18:19], v158, off offset:1664
	v_cmp_eq_u32_e64 s[56:57], 14, v156
	s_waitcnt lgkmcnt(11)
	s_nop 0
	v_cndmask_b32_e64 v148, 0, 1.0, s[56:57]
	v_fma_f32 v148, -v31, v116, v148
	v_fma_f32 v149, -v117, v32, 0
	v_fma_f32 v150, -v118, v33, 0
	v_fma_f32 v151, -v119, v34, 0
	ds_read_b128 v[116:119], v28 offset:22784
	s_waitcnt lgkmcnt(11)
	v_fma_f32 v148, -v120, v35, v148
	v_fma_f32 v149, -v121, v36, v149
	v_fma_f32 v150, -v122, v37, v150
	v_fma_f32 v151, -v123, v38, v151
	ds_read_b128 v[120:123], v28 offset:22800
	s_waitcnt lgkmcnt(11)
	v_fma_f32 v148, -v124, v39, v148
	v_fma_f32 v149, -v125, v40, v149
	v_fma_f32 v150, -v126, v41, v150
	v_fma_f32 v151, -v127, v42, v151
	ds_read_b128 v[124:127], v28 offset:22816
	s_waitcnt lgkmcnt(11)
	v_fma_f32 v148, -v128, v43, v148
	v_fma_f32 v149, -v129, v44, v149
	ds_read_b128 v[128:131], v28 offset:22832
	v_add_f32_e32 v148, v148, v149
	v_add_f32_e32 v150, v150, v151
	v_add_f32_e32 v45, v148, v150
	v_cvt_pk_bf16_f32 v159, v45, v45
	global_store_short v[18:19], v159, off offset:1792
	v_cmp_eq_u32_e64 s[56:57], 15, v156
	s_waitcnt lgkmcnt(11)
	s_nop 0
	v_cndmask_b32_e64 v152, 0, 1.0, s[56:57]
	v_fma_f32 v152, -v31, v132, v152
	v_fma_f32 v153, -v133, v32, 0
	v_fma_f32 v154, -v134, v33, 0
	v_fma_f32 v155, -v135, v34, 0
	ds_read_b128 v[132:135], v28 offset:22848
	s_waitcnt lgkmcnt(11)
	v_fma_f32 v152, -v136, v35, v152
	v_fma_f32 v153, -v137, v36, v153
	v_fma_f32 v154, -v138, v37, v154
	v_fma_f32 v155, -v139, v38, v155
	ds_read_b128 v[136:139], v28 offset:23040
	s_waitcnt lgkmcnt(11)
	v_fma_f32 v152, -v140, v39, v152
	v_fma_f32 v153, -v141, v40, v153
	v_fma_f32 v154, -v142, v41, v154
	v_fma_f32 v155, -v143, v42, v155
	ds_read_b128 v[140:143], v28 offset:23056
	s_waitcnt lgkmcnt(11)
	v_fma_f32 v152, -v144, v43, v152
	v_fma_f32 v153, -v145, v44, v153
	v_fma_f32 v154, -v146, v45, v154
	ds_read_b128 v[144:147], v28 offset:23072
	v_add_f32_e32 v152, v152, v153
	v_add_f32_e32 v154, v154, v155
	v_add_f32_e32 v46, v152, v154
	v_cvt_pk_bf16_f32 v160, v46, v46
	global_store_short v[18:19], v160, off offset:1920
	v_cmp_eq_u32_e64 s[56:57], 16, v156
	s_waitcnt lgkmcnt(11)
	s_nop 0
	v_cndmask_b32_e64 v148, 0, 1.0, s[56:57]
	v_fma_f32 v148, -v31, v100, v148
	v_fma_f32 v149, -v101, v32, 0
	v_fma_f32 v150, -v102, v33, 0
	v_fma_f32 v151, -v103, v34, 0
	ds_read_b128 v[100:103], v28 offset:23088
	s_waitcnt lgkmcnt(11)
; #define LAS __attribute__((address_space(3)))
; __device__ __forceinline__ bf16_t f2bf(float f) { return (bf16_t)(pk2(f, f) & 0xFFFFu); }
; __device__ NOINL void g1_phase(const LAS Params* lp, int l, LAS unsigned char* lds) {
;     ...
;             for (int i = 0; i < 64; ++i) {
;                 float s0 = (i == lane) ? 1.f : 0.f, s1 = 0.f, s2 = 0.f, s3 = 0.f;
; #pragma unroll
;                 for (int j4 = 0; j4 < (i + 3) / 4; ++j4) {
;                     const f32x4 lv = *(const LAS f32x4*)(Ld + i * 64 + j4 * 4);
;                     if (j4 * 4 + 0 < i) s0 -= lv[0] * xv[j4 * 4 + 0];
;                     if (j4 * 4 + 1 < i) s1 -= lv[1] * xv[j4 * 4 + 1];
;                     if (j4 * 4 + 2 < i) s2 -= lv[2] * xv[j4 * 4 + 2];
;                     if (j4 * 4 + 3 < i) s3 -= lv[3] * xv[j4 * 4 + 3];
;                 }
;                 xv[i] = (s0 + s1) + (s2 + s3);
;             }
;             bf16_t* Tg = p.Tbuf + ((((size_t)b * 4 + h) * 36 + c3 * 3 + s) * 2 + dir) * 4096;
; #pragma unroll
;             for (int i = 0; i < 64; ++i) Tg[i * 64 + lane] = f2bf(xv[i]);
	v_fma_f32 v148, -v104, v35, v148
	v_fma_f32 v149, -v105, v36, v149
	v_fma_f32 v150, -v106, v37, v150
	v_fma_f32 v151, -v107, v38, v151
	ds_read_b128 v[104:107], v28 offset:23104
	s_waitcnt lgkmcnt(11)
	v_fma_f32 v148, -v108, v39, v148
	v_fma_f32 v149, -v109, v40, v149
	v_fma_f32 v150, -v110, v41, v150
	v_fma_f32 v151, -v111, v42, v151
	ds_read_b128 v[108:111], v28 offset:23296
	s_waitcnt lgkmcnt(11)
	v_fma_f32 v148, -v112, v43, v148
	v_fma_f32 v149, -v113, v44, v149
	v_fma_f32 v150, -v114, v45, v150
	v_fma_f32 v151, -v115, v46, v151
	ds_read_b128 v[112:115], v28 offset:23312
	v_add_f32_e32 v148, v148, v149
	v_add_f32_e32 v150, v150, v151
	v_add_f32_e32 v47, v148, v150
	v_cvt_pk_bf16_f32 v157, v47, v47
	global_store_short v[18:19], v157, off offset:2048
	v_cmp_eq_u32_e64 s[56:57], 17, v156
	s_waitcnt lgkmcnt(11)
	s_nop 0
	v_cndmask_b32_e64 v152, 0, 1.0, s[56:57]
	v_fma_f32 v152, -v31, v116, v152
	v_fma_f32 v153, -v117, v32, 0
	v_fma_f32 v154, -v118, v33, 0
	v_fma_f32 v155, -v119, v34, 0
	ds_read_b128 v[116:119], v28 offset:23328
	s_waitcnt lgkmcnt(11)
	v_fma_f32 v152, -v120, v35, v152
	v_fma_f32 v153, -v121, v36, v153
	v_fma_f32 v154, -v122, v37, v154
	v_fma_f32 v155, -v123, v38, v155
	ds_read_b128 v[120:123], v28 offset:23344
	s_waitcnt lgkmcnt(11)
	v_fma_f32 v152, -v124, v39, v152
	v_fma_f32 v153, -v125, v40, v153
	v_fma_f32 v154, -v126, v41, v154
	v_fma_f32 v155, -v127, v42, v155
	ds_read_b128 v[124:127], v28 offset:23360
	s_waitcnt lgkmcnt(11)
	v_fma_f32 v152, -v128, v43, v152
	v_fma_f32 v153, -v129, v44, v153
	v_fma_f32 v154, -v130, v45, v154
	v_fma_f32 v155, -v131, v46, v155
	ds_read_b128 v[128:131], v28 offset:23552
	s_waitcnt lgkmcnt(11)
	v_fma_f32 v152, -v132, v47, v152
	ds_read_b128 v[132:135], v28 offset:23568
	v_add_f32_e32 v152, v152, v153
	v_add_f32_e32 v154, v154, v155
	v_add_f32_e32 v48, v152, v154
	v_cvt_pk_bf16_f32 v158, v48, v48
	global_store_short v[18:19], v158, off offset:2176
	v_cmp_eq_u32_e64 s[56:57], 18, v156
	s_waitcnt lgkmcnt(11)
	s_nop 0
	v_cndmask_b32_e64 v148, 0, 1.0, s[56:57]
	v_fma_f32 v148, -v31, v136, v148
	v_fma_f32 v149, -v137, v32, 0
	v_fma_f32 v150, -v138, v33, 0
	v_fma_f32 v151, -v139, v34, 0
	ds_read_b128 v[136:139], v28 offset:23584
	s_waitcnt lgkmcnt(11)
	v_fma_f32 v148, -v140, v35, v148
	v_fma_f32 v149, -v141, v36, v149
	v_fma_f32 v150, -v142, v37, v150
	v_fma_f32 v151, -v143, v38, v151
	ds_read_b128 v[140:143], v28 offset:23600
	s_waitcnt lgkmcnt(11)
	v_fma_f32 v148, -v144, v39, v148
	v_fma_f32 v149, -v145, v40, v149
	v_fma_f32 v150, -v146, v41, v150
	v_fma_f32 v151, -v147, v42, v151
	ds_read_b128 v[144:147], v28 offset:23616
	s_waitcnt lgkmcnt(11)
	v_fma_f32 v148, -v100, v43, v148
	v_fma_f32 v149, -v101, v44, v149
	v_fma_f32 v150, -v102, v45, v150
	v_fma_f32 v151, -v103, v46, v151
	ds_read_b128 v[100:103], v28 offset:23808
	s_waitcnt lgkmcnt(11)
	v_fma_f32 v148, -v104, v47, v148
	v_fma_f32 v149, -v105, v48, v149
	ds_read_b128 v[104:107], v28 offset:23824
	v_add_f32_e32 v148, v148, v149
	v_add_f32_e32 v150, v150, v151
	v_add_f32_e32 v49, v148, v150
	v_cvt_pk_bf16_f32 v159, v49, v49
	global_store_short v[18:19], v159, off offset:2304
	v_cmp_eq_u32_e64 s[56:57], 19, v156
	s_waitcnt lgkmcnt(11)
	s_nop 0
	v_cndmask_b32_e64 v152, 0, 1.0, s[56:57]
	v_fma_f32 v152, -v31, v108, v152
	v_fma_f32 v153, -v109, v32, 0
	v_fma_f32 v154, -v110, v33, 0
	v_fma_f32 v155, -v111, v34, 0
	ds_read_b128 v[108:111], v28 offset:23840
	s_waitcnt lgkmcnt(11)
	v_fma_f32 v152, -v112, v35, v152
	v_fma_f32 v153, -v113, v36, v153
	v_fma_f32 v154, -v114, v37, v154
	v_fma_f32 v155, -v115, v38, v155
	ds_read_b128 v[112:115], v28 offset:23856
	s_waitcnt lgkmcnt(11)
	v_fma_f32 v152, -v116, v39, v152
	v_fma_f32 v153, -v117, v40, v153
	v_fma_f32 v154, -v118, v41, v154
	v_fma_f32 v155, -v119, v42, v155
	ds_read_b128 v[116:119], v28 offset:23872
	s_waitcnt lgkmcnt(11)
	v_fma_f32 v152, -v120, v43, v152
	v_fma_f32 v153, -v121, v44, v153
	v_fma_f32 v154, -v122, v45, v154
	v_fma_f32 v155, -v123, v46, v155
	ds_read_b128 v[120:123], v28 offset:23888
	s_waitcnt lgkmcnt(11)
	v_fma_f32 v152, -v124, v47, v152
	v_fma_f32 v153, -v125, v48, v153
	v_fma_f32 v154, -v126, v49, v154
	ds_read_b128 v[124:127], v28 offset:24064
	v_add_f32_e32 v152, v152, v153
	v_add_f32_e32 v154, v154, v155
	v_add_f32_e32 v50, v152, v154
	v_cvt_pk_bf16_f32 v160, v50, v50
	global_store_short v[18:19], v160, off offset:2432
	v_cmp_eq_u32_e64 s[56:57], 20, v156
	s_waitcnt lgkmcnt(11)
	s_nop 0
	v_cndmask_b32_e64 v148, 0, 1.0, s[56:57]
	v_fma_f32 v148, -v31, v128, v148
	v_fma_f32 v149, -v129, v32, 0
	v_fma_f32 v150, -v130, v33, 0
	v_fma_f32 v151, -v131, v34, 0
	ds_read_b128 v[128:131], v28 offset:24080
	s_waitcnt lgkmcnt(11)
	v_fma_f32 v148, -v132, v35, v148
	v_fma_f32 v149, -v133, v36, v149
	v_fma_f32 v150, -v134, v37, v150
	v_fma_f32 v151, -v135, v38, v151
	ds_read_b128 v[132:135], v28 offset:24096
	s_waitcnt lgkmcnt(11)
	v_fma_f32 v148, -v136, v39, v148
	v_fma_f32 v149, -v137, v40, v149
	v_fma_f32 v150, -v138, v41, v150
	v_fma_f32 v151, -v139, v42, v151
	ds_read_b128 v[136:139], v28 offset:24112
	s_waitcnt lgkmcnt(11)
	v_fma_f32 v148, -v140, v43, v148
	v_fma_f32 v149, -v141, v44, v149
	v_fma_f32 v150, -v142, v45, v150
	v_fma_f32 v151, -v143, v46, v151
	ds_read_b128 v[140:143], v28 offset:24128
	s_waitcnt lgkmcnt(11)
	v_fma_f32 v148, -v144, v47, v148
	v_fma_f32 v149, -v145, v48, v149
	v_fma_f32 v150, -v146, v49, v150
	v_fma_f32 v151, -v147, v50, v151
	ds_read_b128 v[144:147], v28 offset:24144
	v_add_f32_e32 v148, v148, v149
	v_add_f32_e32 v150, v150, v151
	v_add_f32_e32 v51, v148, v150
	v_cvt_pk_bf16_f32 v157, v51, v51
	global_store_short v[18:19], v157, off offset:2560
	v_cmp_eq_u32_e64 s[56:57], 21, v156
	s_waitcnt lgkmcnt(11)
; #define LAS __attribute__((address_space(3)))
; __device__ __forceinline__ bf16_t f2bf(float f) { return (bf16_t)(pk2(f, f) & 0xFFFFu); }
; __device__ NOINL void g1_phase(const LAS Params* lp, int l, LAS unsigned char* lds) {
;     ...
;             for (int i = 0; i < 64; ++i) {
;                 float s0 = (i == lane) ? 1.f : 0.f, s1 = 0.f, s2 = 0.f, s3 = 0.f;
; #pragma unroll
;                 for (int j4 = 0; j4 < (i + 3) / 4; ++j4) {
;                     const f32x4 lv = *(const LAS f32x4*)(Ld + i * 64 + j4 * 4);
;                     if (j4 * 4 + 0 < i) s0 -= lv[0] * xv[j4 * 4 + 0];
;                     if (j4 * 4 + 1 < i) s1 -= lv[1] * xv[j4 * 4 + 1];
;                     if (j4 * 4 + 2 < i) s2 -= lv[2] * xv[j4 * 4 + 2];
;                     if (j4 * 4 + 3 < i) s3 -= lv[3] * xv[j4 * 4 + 3];
;                 }
;                 xv[i] = (s0 + s1) + (s2 + s3);
;             }
;             bf16_t* Tg = p.Tbuf + ((((size_t)b * 4 + h) * 36 + c3 * 3 + s) * 2 + dir) * 4096;
; #pragma unroll
;             for (int i = 0; i < 64; ++i) Tg[i * 64 + lane] = f2bf(xv[i]);
	s_nop 0
	v_cndmask_b32_e64 v152, 0, 1.0, s[56:57]
	v_fma_f32 v152, -v31, v100, v152
	v_fma_f32 v153, -v101, v32, 0
	v_fma_f32 v154, -v102, v33, 0
	v_fma_f32 v155, -v103, v34, 0
	ds_read_b128 v[100:103], v28 offset:24320
	s_waitcnt lgkmcnt(11)
	v_fma_f32 v152, -v104, v35, v152
	v_fma_f32 v153, -v105, v36, v153
	v_fma_f32 v154, -v106, v37, v154
	v_fma_f32 v155, -v107, v38, v155
	ds_read_b128 v[104:107], v28 offset:24336
	s_waitcnt lgkmcnt(11)
	v_fma_f32 v152, -v108, v39, v152
	v_fma_f32 v153, -v109, v40, v153
	v_fma_f32 v154, -v110, v41, v154
	v_fma_f32 v155, -v111, v42, v155
	ds_read_b128 v[108:111], v28 offset:24352
	s_waitcnt lgkmcnt(11)
	v_fma_f32 v152, -v112, v43, v152
	v_fma_f32 v153, -v113, v44, v153
	v_fma_f32 v154, -v114, v45, v154
	v_fma_f32 v155, -v115, v46, v155
	ds_read_b128 v[112:115], v28 offset:24368
	s_waitcnt lgkmcnt(11)
	v_fma_f32 v152, -v116, v47, v152
	v_fma_f32 v153, -v117, v48, v153
	v_fma_f32 v154, -v118, v49, v154
	v_fma_f32 v155, -v119, v50, v155
	ds_read_b128 v[116:119], v28 offset:24384
	s_waitcnt lgkmcnt(11)
	v_fma_f32 v152, -v120, v51, v152
	ds_read_b128 v[120:123], v28 offset:24400
	v_add_f32_e32 v152, v152, v153
	v_add_f32_e32 v154, v154, v155
	v_add_f32_e32 v52, v152, v154
	v_cvt_pk_bf16_f32 v158, v52, v52
	global_store_short v[18:19], v158, off offset:2688
	v_cmp_eq_u32_e64 s[56:57], 22, v156
	s_waitcnt lgkmcnt(11)
	s_nop 0
	v_cndmask_b32_e64 v148, 0, 1.0, s[56:57]
	v_fma_f32 v148, -v31, v124, v148
	v_fma_f32 v149, -v125, v32, 0
	v_fma_f32 v150, -v126, v33, 0
	v_fma_f32 v151, -v127, v34, 0
	ds_read_b128 v[124:127], v28 offset:24576
	s_waitcnt lgkmcnt(11)
	v_fma_f32 v148, -v128, v35, v148
	v_fma_f32 v149, -v129, v36, v149
	v_fma_f32 v150, -v130, v37, v150
	v_fma_f32 v151, -v131, v38, v151
	ds_read_b128 v[128:131], v28 offset:24592
	s_waitcnt lgkmcnt(11)
	v_fma_f32 v148, -v132, v39, v148
	v_fma_f32 v149, -v133, v40, v149
	v_fma_f32 v150, -v134, v41, v150
	v_fma_f32 v151, -v135, v42, v151
	ds_read_b128 v[132:135], v28 offset:24608
	s_waitcnt lgkmcnt(11)
	v_fma_f32 v148, -v136, v43, v148
	v_fma_f32 v149, -v137, v44, v149
	v_fma_f32 v150, -v138, v45, v150
	v_fma_f32 v151, -v139, v46, v151
	ds_read_b128 v[136:139], v28 offset:24624
	s_waitcnt lgkmcnt(11)
	v_fma_f32 v148, -v140, v47, v148
	v_fma_f32 v149, -v141, v48, v149
	v_fma_f32 v150, -v142, v49, v150
	v_fma_f32 v151, -v143, v50, v151
	ds_read_b128 v[140:143], v28 offset:24640
	s_waitcnt lgkmcnt(11)
	v_fma_f32 v148, -v144, v51, v148
	v_fma_f32 v149, -v145, v52, v149
	ds_read_b128 v[144:147], v28 offset:24656
	v_add_f32_e32 v148, v148, v149
	v_add_f32_e32 v150, v150, v151
	v_add_f32_e32 v53, v148, v150
	v_cvt_pk_bf16_f32 v159, v53, v53
	global_store_short v[18:19], v159, off offset:2816
	v_cmp_eq_u32_e64 s[56:57], 23, v156
	s_waitcnt lgkmcnt(11)
	s_nop 0
	v_cndmask_b32_e64 v152, 0, 1.0, s[56:57]
	v_fma_f32 v152, -v31, v100, v152
	v_fma_f32 v153, -v101, v32, 0
	v_fma_f32 v154, -v102, v33, 0
	v_fma_f32 v155, -v103, v34, 0
	ds_read_b128 v[100:103], v28 offset:24832
	s_waitcnt lgkmcnt(11)
	v_fma_f32 v152, -v104, v35, v152
	v_fma_f32 v153, -v105, v36, v153
	v_fma_f32 v154, -v106, v37, v154
	v_fma_f32 v155, -v107, v38, v155
	ds_read_b128 v[104:107], v28 offset:24848
	s_waitcnt lgkmcnt(11)
	v_fma_f32 v152, -v108, v39, v152
	v_fma_f32 v153, -v109, v40, v153
	v_fma_f32 v154, -v110, v41, v154
	v_fma_f32 v155, -v111, v42, v155
	ds_read_b128 v[108:111], v28 offset:24864
	s_waitcnt lgkmcnt(11)
	v_fma_f32 v152, -v112, v43, v152
	v_fma_f32 v153, -v113, v44, v153
	v_fma_f32 v154, -v114, v45, v154
	v_fma_f32 v155, -v115, v46, v155
	ds_read_b128 v[112:115], v28 offset:24880
	s_waitcnt lgkmcnt(11)
	v_fma_f32 v152, -v116, v47, v152
	v_fma_f32 v153, -v117, v48, v153
	v_fma_f32 v154, -v118, v49, v154
	v_fma_f32 v155, -v119, v50, v155
	ds_read_b128 v[116:119], v28 offset:24896
	s_waitcnt lgkmcnt(11)
	v_fma_f32 v152, -v120, v51, v152
	v_fma_f32 v153, -v121, v52, v153
	v_fma_f32 v154, -v122, v53, v154
	ds_read_b128 v[120:123], v28 offset:24912
	v_add_f32_e32 v152, v152, v153
	v_add_f32_e32 v154, v154, v155
	v_add_f32_e32 v54, v152, v154
	v_cvt_pk_bf16_f32 v160, v54, v54
	global_store_short v[18:19], v160, off offset:2944
	v_cmp_eq_u32_e64 s[56:57], 24, v156
	s_waitcnt lgkmcnt(11)
	s_nop 0
	v_cndmask_b32_e64 v148, 0, 1.0, s[56:57]
	v_fma_f32 v148, -v31, v124, v148
	v_fma_f32 v149, -v125, v32, 0
	v_fma_f32 v150, -v126, v33, 0
	v_fma_f32 v151, -v127, v34, 0
	ds_read_b128 v[124:127], v28 offset:24928
	s_waitcnt lgkmcnt(11)
	v_fma_f32 v148, -v128, v35, v148
	v_fma_f32 v149, -v129, v36, v149
	v_fma_f32 v150, -v130, v37, v150
	v_fma_f32 v151, -v131, v38, v151
	ds_read_b128 v[128:131], v28 offset:25088
	s_waitcnt lgkmcnt(11)
	v_fma_f32 v148, -v132, v39, v148
	v_fma_f32 v149, -v133, v40, v149
	v_fma_f32 v150, -v134, v41, v150
	v_fma_f32 v151, -v135, v42, v151
	ds_read_b128 v[132:135], v28 offset:25104
	s_waitcnt lgkmcnt(11)
	v_fma_f32 v148, -v136, v43, v148
	v_fma_f32 v149, -v137, v44, v149
	v_fma_f32 v150, -v138, v45, v150
	v_fma_f32 v151, -v139, v46, v151
	ds_read_b128 v[136:139], v28 offset:25120
	s_waitcnt lgkmcnt(11)
	v_fma_f32 v148, -v140, v47, v148
	v_fma_f32 v149, -v141, v48, v149
	v_fma_f32 v150, -v142, v49, v150
	v_fma_f32 v151, -v143, v50, v151
	ds_read_b128 v[140:143], v28 offset:25136
	s_waitcnt lgkmcnt(11)
	v_fma_f32 v148, -v144, v51, v148
	v_fma_f32 v149, -v145, v52, v149
	v_fma_f32 v150, -v146, v53, v150
	v_fma_f32 v151, -v147, v54, v151
	ds_read_b128 v[144:147], v28 offset:25152
	v_add_f32_e32 v148, v148, v149
	v_add_f32_e32 v150, v150, v151
	v_add_f32_e32 v55, v148, v150
	v_cvt_pk_bf16_f32 v157, v55, v55
	global_store_short v[18:19], v157, off offset:3072
	v_cmp_eq_u32_e64 s[56:57], 25, v156
	s_waitcnt lgkmcnt(11)
; #define LAS __attribute__((address_space(3)))
; __device__ __forceinline__ bf16_t f2bf(float f) { return (bf16_t)(pk2(f, f) & 0xFFFFu); }
; __device__ NOINL void g1_phase(const LAS Params* lp, int l, LAS unsigned char* lds) {
;     ...
;             for (int i = 0; i < 64; ++i) {
;                 float s0 = (i == lane) ? 1.f : 0.f, s1 = 0.f, s2 = 0.f, s3 = 0.f;
; #pragma unroll
;                 for (int j4 = 0; j4 < (i + 3) / 4; ++j4) {
;                     const f32x4 lv = *(const LAS f32x4*)(Ld + i * 64 + j4 * 4);
;                     if (j4 * 4 + 0 < i) s0 -= lv[0] * xv[j4 * 4 + 0];
;                     if (j4 * 4 + 1 < i) s1 -= lv[1] * xv[j4 * 4 + 1];
;                     if (j4 * 4 + 2 < i) s2 -= lv[2] * xv[j4 * 4 + 2];
;                     if (j4 * 4 + 3 < i) s3 -= lv[3] * xv[j4 * 4 + 3];
;                 }
;                 xv[i] = (s0 + s1) + (s2 + s3);
;             }
;             bf16_t* Tg = p.Tbuf + ((((size_t)b * 4 + h) * 36 + c3 * 3 + s) * 2 + dir) * 4096;
; #pragma unroll
;             for (int i = 0; i < 64; ++i) Tg[i * 64 + lane] = f2bf(xv[i]);
	s_nop 0
	v_cndmask_b32_e64 v152, 0, 1.0, s[56:57]
	v_fma_f32 v152, -v31, v100, v152
	v_fma_f32 v153, -v101, v32, 0
	v_fma_f32 v154, -v102, v33, 0
	v_fma_f32 v155, -v103, v34, 0
	ds_read_b128 v[100:103], v28 offset:25168
	s_waitcnt lgkmcnt(11)
	v_fma_f32 v152, -v104, v35, v152
	v_fma_f32 v153, -v105, v36, v153
	v_fma_f32 v154, -v106, v37, v154
	v_fma_f32 v155, -v107, v38, v155
	ds_read_b128 v[104:107], v28 offset:25184
	s_waitcnt lgkmcnt(11)
	v_fma_f32 v152, -v108, v39, v152
	v_fma_f32 v153, -v109, v40, v153
	v_fma_f32 v154, -v110, v41, v154
	v_fma_f32 v155, -v111, v42, v155
	ds_read_b128 v[108:111], v28 offset:25344
	s_waitcnt lgkmcnt(11)
	v_fma_f32 v152, -v112, v43, v152
	v_fma_f32 v153, -v113, v44, v153
	v_fma_f32 v154, -v114, v45, v154
	v_fma_f32 v155, -v115, v46, v155
	ds_read_b128 v[112:115], v28 offset:25360
	s_waitcnt lgkmcnt(11)
	v_fma_f32 v152, -v116, v47, v152
	v_fma_f32 v153, -v117, v48, v153
	v_fma_f32 v154, -v118, v49, v154
	v_fma_f32 v155, -v119, v50, v155
	ds_read_b128 v[116:119], v28 offset:25376
	s_waitcnt lgkmcnt(11)
	v_fma_f32 v152, -v120, v51, v152
	v_fma_f32 v153, -v121, v52, v153
	v_fma_f32 v154, -v122, v53, v154
	v_fma_f32 v155, -v123, v54, v155
	ds_read_b128 v[120:123], v28 offset:25392
	s_waitcnt lgkmcnt(11)
	v_fma_f32 v152, -v124, v55, v152
	ds_read_b128 v[124:127], v28 offset:25408
	v_add_f32_e32 v152, v152, v153
	v_add_f32_e32 v154, v154, v155
	v_add_f32_e32 v56, v152, v154
	v_cvt_pk_bf16_f32 v158, v56, v56
	global_store_short v[18:19], v158, off offset:3200
	v_cmp_eq_u32_e64 s[56:57], 26, v156
	s_waitcnt lgkmcnt(11)
	s_nop 0
	v_cndmask_b32_e64 v148, 0, 1.0, s[56:57]
	v_fma_f32 v148, -v31, v128, v148
	v_fma_f32 v149, -v129, v32, 0
	v_fma_f32 v150, -v130, v33, 0
	v_fma_f32 v151, -v131, v34, 0
	ds_read_b128 v[128:131], v28 offset:25424
	s_waitcnt lgkmcnt(11)
	v_fma_f32 v148, -v132, v35, v148
	v_fma_f32 v149, -v133, v36, v149
	v_fma_f32 v150, -v134, v37, v150
	v_fma_f32 v151, -v135, v38, v151
	ds_read_b128 v[132:135], v28 offset:25440
	s_waitcnt lgkmcnt(11)
	v_fma_f32 v148, -v136, v39, v148
	v_fma_f32 v149, -v137, v40, v149
	v_fma_f32 v150, -v138, v41, v150
	v_fma_f32 v151, -v139, v42, v151
	ds_read_b128 v[136:139], v28 offset:25600
	s_waitcnt lgkmcnt(11)
	v_fma_f32 v148, -v140, v43, v148
	v_fma_f32 v149, -v141, v44, v149
	v_fma_f32 v150, -v142, v45, v150
	v_fma_f32 v151, -v143, v46, v151
	ds_read_b128 v[140:143], v28 offset:25616
	s_waitcnt lgkmcnt(11)
	v_fma_f32 v148, -v144, v47, v148
	v_fma_f32 v149, -v145, v48, v149
	v_fma_f32 v150, -v146, v49, v150
	v_fma_f32 v151, -v147, v50, v151
	ds_read_b128 v[144:147], v28 offset:25632
	s_waitcnt lgkmcnt(11)
	v_fma_f32 v148, -v100, v51, v148
	v_fma_f32 v149, -v101, v52, v149
	v_fma_f32 v150, -v102, v53, v150
	v_fma_f32 v151, -v103, v54, v151
	ds_read_b128 v[100:103], v28 offset:25648
	s_waitcnt lgkmcnt(11)
	v_fma_f32 v148, -v104, v55, v148
	v_fma_f32 v149, -v105, v56, v149
	ds_read_b128 v[104:107], v28 offset:25664
	v_add_f32_e32 v148, v148, v149
	v_add_f32_e32 v150, v150, v151
	v_add_f32_e32 v57, v148, v150
	v_cvt_pk_bf16_f32 v159, v57, v57
	global_store_short v[18:19], v159, off offset:3328
	v_cmp_eq_u32_e64 s[56:57], 27, v156
	s_waitcnt lgkmcnt(11)
	s_nop 0
	v_cndmask_b32_e64 v152, 0, 1.0, s[56:57]
	v_fma_f32 v152, -v31, v108, v152
	v_fma_f32 v153, -v109, v32, 0
	v_fma_f32 v154, -v110, v33, 0
	v_fma_f32 v155, -v111, v34, 0
	ds_read_b128 v[108:111], v28 offset:25680
	s_waitcnt lgkmcnt(11)
	v_fma_f32 v152, -v112, v35, v152
	v_fma_f32 v153, -v113, v36, v153
	v_fma_f32 v154, -v114, v37, v154
	v_fma_f32 v155, -v115, v38, v155
	ds_read_b128 v[112:115], v28 offset:25696
	s_waitcnt lgkmcnt(11)
	v_fma_f32 v152, -v116, v39, v152
	v_fma_f32 v153, -v117, v40, v153
	v_fma_f32 v154, -v118, v41, v154
	v_fma_f32 v155, -v119, v42, v155
	ds_read_b128 v[116:119], v28 offset:25856
	s_waitcnt lgkmcnt(11)
	v_fma_f32 v152, -v120, v43, v152
	v_fma_f32 v153, -v121, v44, v153
	v_fma_f32 v154, -v122, v45, v154
	v_fma_f32 v155, -v123, v46, v155
	ds_read_b128 v[120:123], v28 offset:25872
	s_waitcnt lgkmcnt(11)
	v_fma_f32 v152, -v124, v47, v152
	v_fma_f32 v153, -v125, v48, v153
	v_fma_f32 v154, -v126, v49, v154
	v_fma_f32 v155, -v127, v50, v155
	ds_read_b128 v[124:127], v28 offset:25888
	s_waitcnt lgkmcnt(11)
	v_fma_f32 v152, -v128, v51, v152
	v_fma_f32 v153, -v129, v52, v153
	v_fma_f32 v154, -v130, v53, v154
	v_fma_f32 v155, -v131, v54, v155
	ds_read_b128 v[128:131], v28 offset:25904
	s_waitcnt lgkmcnt(11)
	v_fma_f32 v152, -v132, v55, v152
	v_fma_f32 v153, -v133, v56, v153
	v_fma_f32 v154, -v134, v57, v154
	ds_read_b128 v[132:135], v28 offset:25920
	v_add_f32_e32 v152, v152, v153
	v_add_f32_e32 v154, v154, v155
	v_add_f32_e32 v58, v152, v154
	v_cvt_pk_bf16_f32 v160, v58, v58
	global_store_short v[18:19], v160, off offset:3456
	v_cmp_eq_u32_e64 s[56:57], 28, v156
	s_waitcnt lgkmcnt(11)
	s_nop 0
	v_cndmask_b32_e64 v148, 0, 1.0, s[56:57]
	v_fma_f32 v148, -v31, v136, v148
	v_fma_f32 v149, -v137, v32, 0
	v_fma_f32 v150, -v138, v33, 0
	v_fma_f32 v151, -v139, v34, 0
	ds_read_b128 v[136:139], v28 offset:25936
	s_waitcnt lgkmcnt(11)
	v_fma_f32 v148, -v140, v35, v148
	v_fma_f32 v149, -v141, v36, v149
	v_fma_f32 v150, -v142, v37, v150
	v_fma_f32 v151, -v143, v38, v151
	ds_read_b128 v[140:143], v28 offset:25952
	s_waitcnt lgkmcnt(11)
	v_fma_f32 v148, -v144, v39, v148
	v_fma_f32 v149, -v145, v40, v149
	v_fma_f32 v150, -v146, v41, v150
	v_fma_f32 v151, -v147, v42, v151
	ds_read_b128 v[144:147], v28 offset:25968
	s_waitcnt lgkmcnt(11)
	v_fma_f32 v148, -v100, v43, v148
	v_fma_f32 v149, -v101, v44, v149
	v_fma_f32 v150, -v102, v45, v150
	v_fma_f32 v151, -v103, v46, v151
	ds_read_b128 v[100:103], v28 offset:26112
	s_waitcnt lgkmcnt(11)
; #define LAS __attribute__((address_space(3)))
; __device__ __forceinline__ bf16_t f2bf(float f) { return (bf16_t)(pk2(f, f) & 0xFFFFu); }
; __device__ NOINL void g1_phase(const LAS Params* lp, int l, LAS unsigned char* lds) {
;     ...
;             for (int i = 0; i < 64; ++i) {
;                 float s0 = (i == lane) ? 1.f : 0.f, s1 = 0.f, s2 = 0.f, s3 = 0.f;
; #pragma unroll
;                 for (int j4 = 0; j4 < (i + 3) / 4; ++j4) {
;                     const f32x4 lv = *(const LAS f32x4*)(Ld + i * 64 + j4 * 4);
;                     if (j4 * 4 + 0 < i) s0 -= lv[0] * xv[j4 * 4 + 0];
;                     if (j4 * 4 + 1 < i) s1 -= lv[1] * xv[j4 * 4 + 1];
;                     if (j4 * 4 + 2 < i) s2 -= lv[2] * xv[j4 * 4 + 2];
;                     if (j4 * 4 + 3 < i) s3 -= lv[3] * xv[j4 * 4 + 3];
;                 }
;                 xv[i] = (s0 + s1) + (s2 + s3);
;             }
;             bf16_t* Tg = p.Tbuf + ((((size_t)b * 4 + h) * 36 + c3 * 3 + s) * 2 + dir) * 4096;
; #pragma unroll
;             for (int i = 0; i < 64; ++i) Tg[i * 64 + lane] = f2bf(xv[i]);
	v_fma_f32 v148, -v104, v47, v148
	v_fma_f32 v149, -v105, v48, v149
	v_fma_f32 v150, -v106, v49, v150
	v_fma_f32 v151, -v107, v50, v151
	ds_read_b128 v[104:107], v28 offset:26128
	s_waitcnt lgkmcnt(11)
	v_fma_f32 v148, -v108, v51, v148
	v_fma_f32 v149, -v109, v52, v149
	v_fma_f32 v150, -v110, v53, v150
	v_fma_f32 v151, -v111, v54, v151
	ds_read_b128 v[108:111], v28 offset:26144
	s_waitcnt lgkmcnt(11)
	v_fma_f32 v148, -v112, v55, v148
	v_fma_f32 v149, -v113, v56, v149
	v_fma_f32 v150, -v114, v57, v150
	v_fma_f32 v151, -v115, v58, v151
	ds_read_b128 v[112:115], v28 offset:26160
	v_add_f32_e32 v148, v148, v149
	v_add_f32_e32 v150, v150, v151
	v_add_f32_e32 v59, v148, v150
	v_cvt_pk_bf16_f32 v157, v59, v59
	global_store_short v[18:19], v157, off offset:3584
	v_cmp_eq_u32_e64 s[56:57], 29, v156
	s_waitcnt lgkmcnt(11)
	s_nop 0
	v_cndmask_b32_e64 v152, 0, 1.0, s[56:57]
	v_fma_f32 v152, -v31, v116, v152
	v_fma_f32 v153, -v117, v32, 0
	v_fma_f32 v154, -v118, v33, 0
	v_fma_f32 v155, -v119, v34, 0
	ds_read_b128 v[116:119], v28 offset:26176
	s_waitcnt lgkmcnt(11)
	v_fma_f32 v152, -v120, v35, v152
	v_fma_f32 v153, -v121, v36, v153
	v_fma_f32 v154, -v122, v37, v154
	v_fma_f32 v155, -v123, v38, v155
	ds_read_b128 v[120:123], v28 offset:26192
	s_waitcnt lgkmcnt(11)
	v_fma_f32 v152, -v124, v39, v152
	v_fma_f32 v153, -v125, v40, v153
	v_fma_f32 v154, -v126, v41, v154
	v_fma_f32 v155, -v127, v42, v155
	ds_read_b128 v[124:127], v28 offset:26208
	s_waitcnt lgkmcnt(11)
	v_fma_f32 v152, -v128, v43, v152
	v_fma_f32 v153, -v129, v44, v153
	v_fma_f32 v154, -v130, v45, v154
	v_fma_f32 v155, -v131, v46, v155
	ds_read_b128 v[128:131], v28 offset:26224
	s_waitcnt lgkmcnt(11)
	v_fma_f32 v152, -v132, v47, v152
	v_fma_f32 v153, -v133, v48, v153
	v_fma_f32 v154, -v134, v49, v154
	v_fma_f32 v155, -v135, v50, v155
	ds_read_b128 v[132:135], v28 offset:26368
	s_waitcnt lgkmcnt(11)
	v_fma_f32 v152, -v136, v51, v152
	v_fma_f32 v153, -v137, v52, v153
	v_fma_f32 v154, -v138, v53, v154
	v_fma_f32 v155, -v139, v54, v155
	ds_read_b128 v[136:139], v28 offset:26384
	s_waitcnt lgkmcnt(11)
	v_fma_f32 v152, -v140, v55, v152
	v_fma_f32 v153, -v141, v56, v153
	v_fma_f32 v154, -v142, v57, v154
	v_fma_f32 v155, -v143, v58, v155
	ds_read_b128 v[140:143], v28 offset:26400
	s_waitcnt lgkmcnt(11)
	v_fma_f32 v152, -v144, v59, v152
	ds_read_b128 v[144:147], v28 offset:26416
	v_add_f32_e32 v152, v152, v153
	v_add_f32_e32 v154, v154, v155
	v_add_f32_e32 v60, v152, v154
	v_cvt_pk_bf16_f32 v158, v60, v60
	global_store_short v[18:19], v158, off offset:3712
	v_cmp_eq_u32_e64 s[56:57], 30, v156
	s_waitcnt lgkmcnt(11)
	s_nop 0
	v_cndmask_b32_e64 v148, 0, 1.0, s[56:57]
	v_fma_f32 v148, -v31, v100, v148
	v_fma_f32 v149, -v101, v32, 0
	v_fma_f32 v150, -v102, v33, 0
	v_fma_f32 v151, -v103, v34, 0
	ds_read_b128 v[100:103], v28 offset:26432
	s_waitcnt lgkmcnt(11)
	v_fma_f32 v148, -v104, v35, v148
	v_fma_f32 v149, -v105, v36, v149
	v_fma_f32 v150, -v106, v37, v150
	v_fma_f32 v151, -v107, v38, v151
	ds_read_b128 v[104:107], v28 offset:26448
	s_waitcnt lgkmcnt(11)
	v_fma_f32 v148, -v108, v39, v148
	v_fma_f32 v149, -v109, v40, v149
	v_fma_f32 v150, -v110, v41, v150
	v_fma_f32 v151, -v111, v42, v151
	ds_read_b128 v[108:111], v28 offset:26464
	s_waitcnt lgkmcnt(11)
	v_fma_f32 v148, -v112, v43, v148
	v_fma_f32 v149, -v113, v44, v149
	v_fma_f32 v150, -v114, v45, v150
	v_fma_f32 v151, -v115, v46, v151
	ds_read_b128 v[112:115], v28 offset:26480
	s_waitcnt lgkmcnt(11)
	v_fma_f32 v148, -v116, v47, v148
	v_fma_f32 v149, -v117, v48, v149
	v_fma_f32 v150, -v118, v49, v150
	v_fma_f32 v151, -v119, v50, v151
	ds_read_b128 v[116:119], v28 offset:26624
	s_waitcnt lgkmcnt(11)
	v_fma_f32 v148, -v120, v51, v148
	v_fma_f32 v149, -v121, v52, v149
	v_fma_f32 v150, -v122, v53, v150
	v_fma_f32 v151, -v123, v54, v151
	ds_read_b128 v[120:123], v28 offset:26640
	s_waitcnt lgkmcnt(11)
	v_fma_f32 v148, -v124, v55, v148
	v_fma_f32 v149, -v125, v56, v149
	v_fma_f32 v150, -v126, v57, v150
	v_fma_f32 v151, -v127, v58, v151
	ds_read_b128 v[124:127], v28 offset:26656
	s_waitcnt lgkmcnt(11)
	v_fma_f32 v148, -v128, v59, v148
	v_fma_f32 v149, -v129, v60, v149
	ds_read_b128 v[128:131], v28 offset:26672
	v_add_f32_e32 v148, v148, v149
	v_add_f32_e32 v150, v150, v151
	v_add_f32_e32 v61, v148, v150
	v_cvt_pk_bf16_f32 v159, v61, v61
	global_store_short v[18:19], v159, off offset:3840
	v_cmp_eq_u32_e64 s[56:57], 31, v156
	s_waitcnt lgkmcnt(11)
	s_nop 0
	v_cndmask_b32_e64 v152, 0, 1.0, s[56:57]
	v_fma_f32 v152, -v31, v132, v152
	v_fma_f32 v153, -v133, v32, 0
	v_fma_f32 v154, -v134, v33, 0
	v_fma_f32 v155, -v135, v34, 0
	ds_read_b128 v[132:135], v28 offset:26688
	s_waitcnt lgkmcnt(11)
	v_fma_f32 v152, -v136, v35, v152
	v_fma_f32 v153, -v137, v36, v153
	v_fma_f32 v154, -v138, v37, v154
	v_fma_f32 v155, -v139, v38, v155
	ds_read_b128 v[136:139], v28 offset:26704
	s_waitcnt lgkmcnt(11)
	v_fma_f32 v152, -v140, v39, v152
	v_fma_f32 v153, -v141, v40, v153
	v_fma_f32 v154, -v142, v41, v154
	v_fma_f32 v155, -v143, v42, v155
	ds_read_b128 v[140:143], v28 offset:26720
	s_waitcnt lgkmcnt(11)
	v_fma_f32 v152, -v144, v43, v152
	v_fma_f32 v153, -v145, v44, v153
	v_fma_f32 v154, -v146, v45, v154
	v_fma_f32 v155, -v147, v46, v155
	ds_read_b128 v[144:147], v28 offset:26736
	s_waitcnt lgkmcnt(11)
	v_fma_f32 v152, -v100, v47, v152
	v_fma_f32 v153, -v101, v48, v153
	v_fma_f32 v154, -v102, v49, v154
	v_fma_f32 v155, -v103, v50, v155
	ds_read_b128 v[100:103], v28 offset:26880
	s_waitcnt lgkmcnt(11)
	v_fma_f32 v152, -v104, v51, v152
	v_fma_f32 v153, -v105, v52, v153
	v_fma_f32 v154, -v106, v53, v154
	v_fma_f32 v155, -v107, v54, v155
	ds_read_b128 v[104:107], v28 offset:26896
	s_waitcnt lgkmcnt(11)
; #define LAS __attribute__((address_space(3)))
; __device__ __forceinline__ bf16_t f2bf(float f) { return (bf16_t)(pk2(f, f) & 0xFFFFu); }
; __device__ NOINL void g1_phase(const LAS Params* lp, int l, LAS unsigned char* lds) {
;     ...
;             for (int i = 0; i < 64; ++i) {
;                 float s0 = (i == lane) ? 1.f : 0.f, s1 = 0.f, s2 = 0.f, s3 = 0.f;
; #pragma unroll
;                 for (int j4 = 0; j4 < (i + 3) / 4; ++j4) {
;                     const f32x4 lv = *(const LAS f32x4*)(Ld + i * 64 + j4 * 4);
;                     if (j4 * 4 + 0 < i) s0 -= lv[0] * xv[j4 * 4 + 0];
;                     if (j4 * 4 + 1 < i) s1 -= lv[1] * xv[j4 * 4 + 1];
;                     if (j4 * 4 + 2 < i) s2 -= lv[2] * xv[j4 * 4 + 2];
;                     if (j4 * 4 + 3 < i) s3 -= lv[3] * xv[j4 * 4 + 3];
;                 }
;                 xv[i] = (s0 + s1) + (s2 + s3);
;             }
;             bf16_t* Tg = p.Tbuf + ((((size_t)b * 4 + h) * 36 + c3 * 3 + s) * 2 + dir) * 4096;
; #pragma unroll
;             for (int i = 0; i < 64; ++i) Tg[i * 64 + lane] = f2bf(xv[i]);
	v_fma_f32 v152, -v108, v55, v152
	v_fma_f32 v153, -v109, v56, v153
	v_fma_f32 v154, -v110, v57, v154
	v_fma_f32 v155, -v111, v58, v155
	ds_read_b128 v[108:111], v28 offset:26912
	s_waitcnt lgkmcnt(11)
	v_fma_f32 v152, -v112, v59, v152
	v_fma_f32 v153, -v113, v60, v153
	v_fma_f32 v154, -v114, v61, v154
	ds_read_b128 v[112:115], v28 offset:26928
	v_add_f32_e32 v152, v152, v153
	v_add_f32_e32 v154, v154, v155
	v_add_f32_e32 v62, v152, v154
	v_cvt_pk_bf16_f32 v160, v62, v62
	global_store_short v[18:19], v160, off offset:3968
	v_cmp_eq_u32_e64 s[56:57], 32, v156
	s_waitcnt lgkmcnt(11)
	s_nop 0
	v_cndmask_b32_e64 v148, 0, 1.0, s[56:57]
	v_fma_f32 v148, -v31, v116, v148
	v_fma_f32 v149, -v117, v32, 0
	v_fma_f32 v150, -v118, v33, 0
	v_fma_f32 v151, -v119, v34, 0
	ds_read_b128 v[116:119], v28 offset:26944
	s_waitcnt lgkmcnt(11)
	v_fma_f32 v148, -v120, v35, v148
	v_fma_f32 v149, -v121, v36, v149
	v_fma_f32 v150, -v122, v37, v150
	v_fma_f32 v151, -v123, v38, v151
	ds_read_b128 v[120:123], v28 offset:26960
	s_waitcnt lgkmcnt(11)
	v_fma_f32 v148, -v124, v39, v148
	v_fma_f32 v149, -v125, v40, v149
	v_fma_f32 v150, -v126, v41, v150
	v_fma_f32 v151, -v127, v42, v151
	ds_read_b128 v[124:127], v28 offset:26976
	s_waitcnt lgkmcnt(11)
	v_fma_f32 v148, -v128, v43, v148
	v_fma_f32 v149, -v129, v44, v149
	v_fma_f32 v150, -v130, v45, v150
	v_fma_f32 v151, -v131, v46, v151
	ds_read_b128 v[128:131], v28 offset:26992
	s_waitcnt lgkmcnt(11)
	v_fma_f32 v148, -v132, v47, v148
	v_fma_f32 v149, -v133, v48, v149
	v_fma_f32 v150, -v134, v49, v150
	v_fma_f32 v151, -v135, v50, v151
	ds_read_b128 v[132:135], v28 offset:27008
	s_waitcnt lgkmcnt(11)
	v_fma_f32 v148, -v136, v51, v148
	v_fma_f32 v149, -v137, v52, v149
	v_fma_f32 v150, -v138, v53, v150
	v_fma_f32 v151, -v139, v54, v151
	ds_read_b128 v[136:139], v28 offset:27136
	s_waitcnt lgkmcnt(11)
	v_fma_f32 v148, -v140, v55, v148
	v_fma_f32 v149, -v141, v56, v149
	v_fma_f32 v150, -v142, v57, v150
	v_fma_f32 v151, -v143, v58, v151
	ds_read_b128 v[140:143], v28 offset:27152
	s_waitcnt lgkmcnt(11)
	v_fma_f32 v148, -v144, v59, v148
	v_fma_f32 v149, -v145, v60, v149
	v_fma_f32 v150, -v146, v61, v150
	v_fma_f32 v151, -v147, v62, v151
	ds_read_b128 v[144:147], v28 offset:27168
	v_add_f32_e32 v148, v148, v149
	v_add_f32_e32 v150, v150, v151
	v_add_f32_e32 v63, v148, v150
	v_cvt_pk_bf16_f32 v157, v63, v63
	global_store_short v[8:9], v157, off
	v_cmp_eq_u32_e64 s[56:57], 33, v156
	s_waitcnt lgkmcnt(11)
	s_nop 0
	v_cndmask_b32_e64 v152, 0, 1.0, s[56:57]
	v_fma_f32 v152, -v31, v100, v152
	v_fma_f32 v153, -v101, v32, 0
	v_fma_f32 v154, -v102, v33, 0
	v_fma_f32 v155, -v103, v34, 0
	ds_read_b128 v[100:103], v28 offset:27184
	s_waitcnt lgkmcnt(11)
	v_fma_f32 v152, -v104, v35, v152
	v_fma_f32 v153, -v105, v36, v153
	v_fma_f32 v154, -v106, v37, v154
	v_fma_f32 v155, -v107, v38, v155
	ds_read_b128 v[104:107], v28 offset:27200
	s_waitcnt lgkmcnt(11)
	v_fma_f32 v152, -v108, v39, v152
	v_fma_f32 v153, -v109, v40, v153
	v_fma_f32 v154, -v110, v41, v154
	v_fma_f32 v155, -v111, v42, v155
	ds_read_b128 v[108:111], v28 offset:27216
	s_waitcnt lgkmcnt(11)
	v_fma_f32 v152, -v112, v43, v152
	v_fma_f32 v153, -v113, v44, v153
	v_fma_f32 v154, -v114, v45, v154
	v_fma_f32 v155, -v115, v46, v155
	ds_read_b128 v[112:115], v28 offset:27232
	s_waitcnt lgkmcnt(11)
	v_fma_f32 v152, -v116, v47, v152
	v_fma_f32 v153, -v117, v48, v153
	v_fma_f32 v154, -v118, v49, v154
	v_fma_f32 v155, -v119, v50, v155
	ds_read_b128 v[116:119], v28 offset:27248
	s_waitcnt lgkmcnt(11)
	v_fma_f32 v152, -v120, v51, v152
	v_fma_f32 v153, -v121, v52, v153
	v_fma_f32 v154, -v122, v53, v154
	v_fma_f32 v155, -v123, v54, v155
	ds_read_b128 v[120:123], v28 offset:27264
	s_waitcnt lgkmcnt(11)
	v_fma_f32 v152, -v124, v55, v152
	v_fma_f32 v153, -v125, v56, v153
	v_fma_f32 v154, -v126, v57, v154
	v_fma_f32 v155, -v127, v58, v155
	ds_read_b128 v[124:127], v28 offset:27392
	s_waitcnt lgkmcnt(11)
	v_fma_f32 v152, -v128, v59, v152
	v_fma_f32 v153, -v129, v60, v153
	v_fma_f32 v154, -v130, v61, v154
	v_fma_f32 v155, -v131, v62, v155
	ds_read_b128 v[128:131], v28 offset:27408
	s_waitcnt lgkmcnt(11)
	v_fma_f32 v152, -v132, v63, v152
	ds_read_b128 v[132:135], v28 offset:27424
	v_add_f32_e32 v152, v152, v153
	v_add_f32_e32 v154, v154, v155
	v_add_f32_e32 v64, v152, v154
	v_cvt_pk_bf16_f32 v158, v64, v64
	global_store_short v[8:9], v158, off offset:128
	v_cmp_eq_u32_e64 s[56:57], 34, v156
	s_waitcnt lgkmcnt(11)
	s_nop 0
	v_cndmask_b32_e64 v148, 0, 1.0, s[56:57]
	v_fma_f32 v148, -v31, v136, v148
	v_fma_f32 v149, -v137, v32, 0
	v_fma_f32 v150, -v138, v33, 0
	v_fma_f32 v151, -v139, v34, 0
	ds_read_b128 v[136:139], v28 offset:27440
	s_waitcnt lgkmcnt(11)
	v_fma_f32 v148, -v140, v35, v148
	v_fma_f32 v149, -v141, v36, v149
	v_fma_f32 v150, -v142, v37, v150
	v_fma_f32 v151, -v143, v38, v151
	ds_read_b128 v[140:143], v28 offset:27456
	s_waitcnt lgkmcnt(11)
	v_fma_f32 v148, -v144, v39, v148
	v_fma_f32 v149, -v145, v40, v149
	v_fma_f32 v150, -v146, v41, v150
	v_fma_f32 v151, -v147, v42, v151
	ds_read_b128 v[144:147], v28 offset:27472
	s_waitcnt lgkmcnt(11)
	v_fma_f32 v148, -v100, v43, v148
	v_fma_f32 v149, -v101, v44, v149
	v_fma_f32 v150, -v102, v45, v150
	v_fma_f32 v151, -v103, v46, v151
	ds_read_b128 v[100:103], v28 offset:27488
	s_waitcnt lgkmcnt(11)
	v_fma_f32 v148, -v104, v47, v148
	v_fma_f32 v149, -v105, v48, v149
	v_fma_f32 v150, -v106, v49, v150
	v_fma_f32 v151, -v107, v50, v151
	ds_read_b128 v[104:107], v28 offset:27504
	s_waitcnt lgkmcnt(11)
	v_fma_f32 v148, -v108, v51, v148
	v_fma_f32 v149, -v109, v52, v149
	v_fma_f32 v150, -v110, v53, v150
	v_fma_f32 v151, -v111, v54, v151
	ds_read_b128 v[108:111], v28 offset:27520
	s_waitcnt lgkmcnt(11)
; #define LAS __attribute__((address_space(3)))
; __device__ __forceinline__ bf16_t f2bf(float f) { return (bf16_t)(pk2(f, f) & 0xFFFFu); }
; __device__ NOINL void g1_phase(const LAS Params* lp, int l, LAS unsigned char* lds) {
;     ...
;             for (int i = 0; i < 64; ++i) {
;                 float s0 = (i == lane) ? 1.f : 0.f, s1 = 0.f, s2 = 0.f, s3 = 0.f;
; #pragma unroll
;                 for (int j4 = 0; j4 < (i + 3) / 4; ++j4) {
;                     const f32x4 lv = *(const LAS f32x4*)(Ld + i * 64 + j4 * 4);
;                     if (j4 * 4 + 0 < i) s0 -= lv[0] * xv[j4 * 4 + 0];
;                     if (j4 * 4 + 1 < i) s1 -= lv[1] * xv[j4 * 4 + 1];
;                     if (j4 * 4 + 2 < i) s2 -= lv[2] * xv[j4 * 4 + 2];
;                     if (j4 * 4 + 3 < i) s3 -= lv[3] * xv[j4 * 4 + 3];
;                 }
;                 xv[i] = (s0 + s1) + (s2 + s3);
;             }
;             bf16_t* Tg = p.Tbuf + ((((size_t)b * 4 + h) * 36 + c3 * 3 + s) * 2 + dir) * 4096;
; #pragma unroll
;             for (int i = 0; i < 64; ++i) Tg[i * 64 + lane] = f2bf(xv[i]);
	v_fma_f32 v148, -v112, v55, v148
	v_fma_f32 v149, -v113, v56, v149
	v_fma_f32 v150, -v114, v57, v150
	v_fma_f32 v151, -v115, v58, v151
	ds_read_b128 v[112:115], v28 offset:27648
	s_waitcnt lgkmcnt(11)
	v_fma_f32 v148, -v116, v59, v148
	v_fma_f32 v149, -v117, v60, v149
	v_fma_f32 v150, -v118, v61, v150
	v_fma_f32 v151, -v119, v62, v151
	ds_read_b128 v[116:119], v28 offset:27664
	s_waitcnt lgkmcnt(11)
	v_fma_f32 v148, -v120, v63, v148
	v_fma_f32 v149, -v121, v64, v149
	ds_read_b128 v[120:123], v28 offset:27680
	v_add_f32_e32 v148, v148, v149
	v_add_f32_e32 v150, v150, v151
	v_add_f32_e32 v65, v148, v150
	v_cvt_pk_bf16_f32 v159, v65, v65
	global_store_short v[8:9], v159, off offset:256
	v_cmp_eq_u32_e64 s[56:57], 35, v156
	s_waitcnt lgkmcnt(11)
	s_nop 0
	v_cndmask_b32_e64 v152, 0, 1.0, s[56:57]
	v_fma_f32 v152, -v31, v124, v152
	v_fma_f32 v153, -v125, v32, 0
	v_fma_f32 v154, -v126, v33, 0
	v_fma_f32 v155, -v127, v34, 0
	ds_read_b128 v[124:127], v28 offset:27696
	s_waitcnt lgkmcnt(11)
	v_fma_f32 v152, -v128, v35, v152
	v_fma_f32 v153, -v129, v36, v153
	v_fma_f32 v154, -v130, v37, v154
	v_fma_f32 v155, -v131, v38, v155
	ds_read_b128 v[128:131], v28 offset:27712
	s_waitcnt lgkmcnt(11)
	v_fma_f32 v152, -v132, v39, v152
	v_fma_f32 v153, -v133, v40, v153
	v_fma_f32 v154, -v134, v41, v154
	v_fma_f32 v155, -v135, v42, v155
	ds_read_b128 v[132:135], v28 offset:27728
	s_waitcnt lgkmcnt(11)
	v_fma_f32 v152, -v136, v43, v152
	v_fma_f32 v153, -v137, v44, v153
	v_fma_f32 v154, -v138, v45, v154
	v_fma_f32 v155, -v139, v46, v155
	ds_read_b128 v[136:139], v28 offset:27744
	s_waitcnt lgkmcnt(11)
	v_fma_f32 v152, -v140, v47, v152
	v_fma_f32 v153, -v141, v48, v153
	v_fma_f32 v154, -v142, v49, v154
	v_fma_f32 v155, -v143, v50, v155
	ds_read_b128 v[140:143], v28 offset:27760
	s_waitcnt lgkmcnt(11)
	v_fma_f32 v152, -v144, v51, v152
	v_fma_f32 v153, -v145, v52, v153
	v_fma_f32 v154, -v146, v53, v154
	v_fma_f32 v155, -v147, v54, v155
	ds_read_b128 v[144:147], v28 offset:27776
	s_waitcnt lgkmcnt(11)
	v_fma_f32 v152, -v100, v55, v152
	v_fma_f32 v153, -v101, v56, v153
	v_fma_f32 v154, -v102, v57, v154
	v_fma_f32 v155, -v103, v58, v155
	ds_read_b128 v[100:103], v28 offset:27904
	s_waitcnt lgkmcnt(11)
	v_fma_f32 v152, -v104, v59, v152
	v_fma_f32 v153, -v105, v60, v153
	v_fma_f32 v154, -v106, v61, v154
	v_fma_f32 v155, -v107, v62, v155
	ds_read_b128 v[104:107], v28 offset:27920
	s_waitcnt lgkmcnt(11)
	v_fma_f32 v152, -v108, v63, v152
	v_fma_f32 v153, -v109, v64, v153
	v_fma_f32 v154, -v110, v65, v154
	ds_read_b128 v[108:111], v28 offset:27936
	v_add_f32_e32 v152, v152, v153
	v_add_f32_e32 v154, v154, v155
	v_add_f32_e32 v66, v152, v154
	v_cvt_pk_bf16_f32 v160, v66, v66
	global_store_short v[8:9], v160, off offset:384
	v_cmp_eq_u32_e64 s[56:57], 36, v156
	s_waitcnt lgkmcnt(11)
	s_nop 0
	v_cndmask_b32_e64 v148, 0, 1.0, s[56:57]
	v_fma_f32 v148, -v31, v112, v148
	v_fma_f32 v149, -v113, v32, 0
	v_fma_f32 v150, -v114, v33, 0
	v_fma_f32 v151, -v115, v34, 0
	ds_read_b128 v[112:115], v28 offset:27952
	s_waitcnt lgkmcnt(11)
	v_fma_f32 v148, -v116, v35, v148
	v_fma_f32 v149, -v117, v36, v149
	v_fma_f32 v150, -v118, v37, v150
	v_fma_f32 v151, -v119, v38, v151
	ds_read_b128 v[116:119], v28 offset:27968
	s_waitcnt lgkmcnt(11)
	v_fma_f32 v148, -v120, v39, v148
	v_fma_f32 v149, -v121, v40, v149
	v_fma_f32 v150, -v122, v41, v150
	v_fma_f32 v151, -v123, v42, v151
	ds_read_b128 v[120:123], v28 offset:27984
	s_waitcnt lgkmcnt(11)
	v_fma_f32 v148, -v124, v43, v148
	v_fma_f32 v149, -v125, v44, v149
	v_fma_f32 v150, -v126, v45, v150
	v_fma_f32 v151, -v127, v46, v151
	ds_read_b128 v[124:127], v28 offset:28000
	s_waitcnt lgkmcnt(11)
	v_fma_f32 v148, -v128, v47, v148
	v_fma_f32 v149, -v129, v48, v149
	v_fma_f32 v150, -v130, v49, v150
	v_fma_f32 v151, -v131, v50, v151
	ds_read_b128 v[128:131], v28 offset:28016
	s_waitcnt lgkmcnt(11)
	v_fma_f32 v148, -v132, v51, v148
	v_fma_f32 v149, -v133, v52, v149
	v_fma_f32 v150, -v134, v53, v150
	v_fma_f32 v151, -v135, v54, v151
	ds_read_b128 v[132:135], v28 offset:28032
	s_waitcnt lgkmcnt(11)
	v_fma_f32 v148, -v136, v55, v148
	v_fma_f32 v149, -v137, v56, v149
	v_fma_f32 v150, -v138, v57, v150
	v_fma_f32 v151, -v139, v58, v151
	ds_read_b128 v[136:139], v28 offset:28048
	s_waitcnt lgkmcnt(11)
	v_fma_f32 v148, -v140, v59, v148
	v_fma_f32 v149, -v141, v60, v149
	v_fma_f32 v150, -v142, v61, v150
	v_fma_f32 v151, -v143, v62, v151
	ds_read_b128 v[140:143], v28 offset:28160
	s_waitcnt lgkmcnt(11)
	v_fma_f32 v148, -v144, v63, v148
	v_fma_f32 v149, -v145, v64, v149
	v_fma_f32 v150, -v146, v65, v150
	v_fma_f32 v151, -v147, v66, v151
	ds_read_b128 v[144:147], v28 offset:28176
	v_add_f32_e32 v148, v148, v149
	v_add_f32_e32 v150, v150, v151
	v_add_f32_e32 v67, v148, v150
	v_cvt_pk_bf16_f32 v157, v67, v67
	global_store_short v[8:9], v157, off offset:512
	v_cmp_eq_u32_e64 s[56:57], 37, v156
	s_waitcnt lgkmcnt(11)
	s_nop 0
	v_cndmask_b32_e64 v152, 0, 1.0, s[56:57]
	v_fma_f32 v152, -v31, v100, v152
	v_fma_f32 v153, -v101, v32, 0
	v_fma_f32 v154, -v102, v33, 0
	v_fma_f32 v155, -v103, v34, 0
	ds_read_b128 v[100:103], v28 offset:28192
	s_waitcnt lgkmcnt(11)
	v_fma_f32 v152, -v104, v35, v152
	v_fma_f32 v153, -v105, v36, v153
	v_fma_f32 v154, -v106, v37, v154
	v_fma_f32 v155, -v107, v38, v155
	ds_read_b128 v[104:107], v28 offset:28208
	s_waitcnt lgkmcnt(11)
	v_fma_f32 v152, -v108, v39, v152
	v_fma_f32 v153, -v109, v40, v153
	v_fma_f32 v154, -v110, v41, v154
	v_fma_f32 v155, -v111, v42, v155
	ds_read_b128 v[108:111], v28 offset:28224
	s_waitcnt lgkmcnt(11)
	v_fma_f32 v152, -v112, v43, v152
	v_fma_f32 v153, -v113, v44, v153
	v_fma_f32 v154, -v114, v45, v154
	v_fma_f32 v155, -v115, v46, v155
	ds_read_b128 v[112:115], v28 offset:28240
	s_waitcnt lgkmcnt(11)
; #define LAS __attribute__((address_space(3)))
; __device__ __forceinline__ bf16_t f2bf(float f) { return (bf16_t)(pk2(f, f) & 0xFFFFu); }
; __device__ NOINL void g1_phase(const LAS Params* lp, int l, LAS unsigned char* lds) {
;     ...
;             for (int i = 0; i < 64; ++i) {
;                 float s0 = (i == lane) ? 1.f : 0.f, s1 = 0.f, s2 = 0.f, s3 = 0.f;
; #pragma unroll
;                 for (int j4 = 0; j4 < (i + 3) / 4; ++j4) {
;                     const f32x4 lv = *(const LAS f32x4*)(Ld + i * 64 + j4 * 4);
;                     if (j4 * 4 + 0 < i) s0 -= lv[0] * xv[j4 * 4 + 0];
;                     if (j4 * 4 + 1 < i) s1 -= lv[1] * xv[j4 * 4 + 1];
;                     if (j4 * 4 + 2 < i) s2 -= lv[2] * xv[j4 * 4 + 2];
;                     if (j4 * 4 + 3 < i) s3 -= lv[3] * xv[j4 * 4 + 3];
;                 }
;                 xv[i] = (s0 + s1) + (s2 + s3);
;             }
;             bf16_t* Tg = p.Tbuf + ((((size_t)b * 4 + h) * 36 + c3 * 3 + s) * 2 + dir) * 4096;
; #pragma unroll
;             for (int i = 0; i < 64; ++i) Tg[i * 64 + lane] = f2bf(xv[i]);
	v_fma_f32 v152, -v116, v47, v152
	v_fma_f32 v153, -v117, v48, v153
	v_fma_f32 v154, -v118, v49, v154
	v_fma_f32 v155, -v119, v50, v155
	ds_read_b128 v[116:119], v28 offset:28256
	s_waitcnt lgkmcnt(11)
	v_fma_f32 v152, -v120, v51, v152
	v_fma_f32 v153, -v121, v52, v153
	v_fma_f32 v154, -v122, v53, v154
	v_fma_f32 v155, -v123, v54, v155
	ds_read_b128 v[120:123], v28 offset:28272
	s_waitcnt lgkmcnt(11)
	v_fma_f32 v152, -v124, v55, v152
	v_fma_f32 v153, -v125, v56, v153
	v_fma_f32 v154, -v126, v57, v154
	v_fma_f32 v155, -v127, v58, v155
	ds_read_b128 v[124:127], v28 offset:28288
	s_waitcnt lgkmcnt(11)
	v_fma_f32 v152, -v128, v59, v152
	v_fma_f32 v153, -v129, v60, v153
	v_fma_f32 v154, -v130, v61, v154
	v_fma_f32 v155, -v131, v62, v155
	ds_read_b128 v[128:131], v28 offset:28304
	s_waitcnt lgkmcnt(11)
	v_fma_f32 v152, -v132, v63, v152
	v_fma_f32 v153, -v133, v64, v153
	v_fma_f32 v154, -v134, v65, v154
	v_fma_f32 v155, -v135, v66, v155
	ds_read_b128 v[132:135], v28 offset:28416
	s_waitcnt lgkmcnt(11)
	v_fma_f32 v152, -v136, v67, v152
	ds_read_b128 v[136:139], v28 offset:28432
	v_add_f32_e32 v152, v152, v153
	v_add_f32_e32 v154, v154, v155
	v_add_f32_e32 v68, v152, v154
	v_cvt_pk_bf16_f32 v158, v68, v68
	global_store_short v[8:9], v158, off offset:640
	v_cmp_eq_u32_e64 s[56:57], 38, v156
	s_waitcnt lgkmcnt(11)
	s_nop 0
	v_cndmask_b32_e64 v148, 0, 1.0, s[56:57]
	v_fma_f32 v148, -v31, v140, v148
	v_fma_f32 v149, -v141, v32, 0
	v_fma_f32 v150, -v142, v33, 0
	v_fma_f32 v151, -v143, v34, 0
	ds_read_b128 v[140:143], v28 offset:28448
	s_waitcnt lgkmcnt(11)
	v_fma_f32 v148, -v144, v35, v148
	v_fma_f32 v149, -v145, v36, v149
	v_fma_f32 v150, -v146, v37, v150
	v_fma_f32 v151, -v147, v38, v151
	ds_read_b128 v[144:147], v28 offset:28464
	s_waitcnt lgkmcnt(11)
	v_fma_f32 v148, -v100, v39, v148
	v_fma_f32 v149, -v101, v40, v149
	v_fma_f32 v150, -v102, v41, v150
	v_fma_f32 v151, -v103, v42, v151
	ds_read_b128 v[100:103], v28 offset:28480
	s_waitcnt lgkmcnt(11)
	v_fma_f32 v148, -v104, v43, v148
	v_fma_f32 v149, -v105, v44, v149
	v_fma_f32 v150, -v106, v45, v150
	v_fma_f32 v151, -v107, v46, v151
	ds_read_b128 v[104:107], v28 offset:28496
	s_waitcnt lgkmcnt(11)
	v_fma_f32 v148, -v108, v47, v148
	v_fma_f32 v149, -v109, v48, v149
	v_fma_f32 v150, -v110, v49, v150
	v_fma_f32 v151, -v111, v50, v151
	ds_read_b128 v[108:111], v28 offset:28512
	s_waitcnt lgkmcnt(11)
	v_fma_f32 v148, -v112, v51, v148
	v_fma_f32 v149, -v113, v52, v149
	v_fma_f32 v150, -v114, v53, v150
	v_fma_f32 v151, -v115, v54, v151
	ds_read_b128 v[112:115], v28 offset:28528
	s_waitcnt lgkmcnt(11)
	v_fma_f32 v148, -v116, v55, v148
	v_fma_f32 v149, -v117, v56, v149
	v_fma_f32 v150, -v118, v57, v150
	v_fma_f32 v151, -v119, v58, v151
	ds_read_b128 v[116:119], v28 offset:28544
	s_waitcnt lgkmcnt(11)
	v_fma_f32 v148, -v120, v59, v148
	v_fma_f32 v149, -v121, v60, v149
	v_fma_f32 v150, -v122, v61, v150
	v_fma_f32 v151, -v123, v62, v151
	ds_read_b128 v[120:123], v28 offset:28560
	s_waitcnt lgkmcnt(11)
	v_fma_f32 v148, -v124, v63, v148
	v_fma_f32 v149, -v125, v64, v149
	v_fma_f32 v150, -v126, v65, v150
	v_fma_f32 v151, -v127, v66, v151
	ds_read_b128 v[124:127], v28 offset:28672
	s_waitcnt lgkmcnt(11)
	v_fma_f32 v148, -v128, v67, v148
	v_fma_f32 v149, -v129, v68, v149
	ds_read_b128 v[128:131], v28 offset:28688
	v_add_f32_e32 v148, v148, v149
	v_add_f32_e32 v150, v150, v151
	v_add_f32_e32 v69, v148, v150
	v_cvt_pk_bf16_f32 v159, v69, v69
	global_store_short v[8:9], v159, off offset:768
	v_cmp_eq_u32_e64 s[56:57], 39, v156
	s_waitcnt lgkmcnt(11)
	s_nop 0
	v_cndmask_b32_e64 v152, 0, 1.0, s[56:57]
	v_fma_f32 v152, -v31, v132, v152
	v_fma_f32 v153, -v133, v32, 0
	v_fma_f32 v154, -v134, v33, 0
	v_fma_f32 v155, -v135, v34, 0
	ds_read_b128 v[132:135], v28 offset:28704
	s_waitcnt lgkmcnt(11)
	v_fma_f32 v152, -v136, v35, v152
	v_fma_f32 v153, -v137, v36, v153
	v_fma_f32 v154, -v138, v37, v154
	v_fma_f32 v155, -v139, v38, v155
	ds_read_b128 v[136:139], v28 offset:28720
	s_waitcnt lgkmcnt(11)
	v_fma_f32 v152, -v140, v39, v152
	v_fma_f32 v153, -v141, v40, v153
	v_fma_f32 v154, -v142, v41, v154
	v_fma_f32 v155, -v143, v42, v155
	ds_read_b128 v[140:143], v28 offset:28736
	s_waitcnt lgkmcnt(11)
	v_fma_f32 v152, -v144, v43, v152
	v_fma_f32 v153, -v145, v44, v153
	v_fma_f32 v154, -v146, v45, v154
	v_fma_f32 v155, -v147, v46, v155
	ds_read_b128 v[144:147], v28 offset:28752
	s_waitcnt lgkmcnt(11)
	v_fma_f32 v152, -v100, v47, v152
	v_fma_f32 v153, -v101, v48, v153
	v_fma_f32 v154, -v102, v49, v154
	v_fma_f32 v155, -v103, v50, v155
	ds_read_b128 v[100:103], v28 offset:28768
	s_waitcnt lgkmcnt(11)
	v_fma_f32 v152, -v104, v51, v152
	v_fma_f32 v153, -v105, v52, v153
	v_fma_f32 v154, -v106, v53, v154
	v_fma_f32 v155, -v107, v54, v155
	ds_read_b128 v[104:107], v28 offset:28784
	s_waitcnt lgkmcnt(11)
	v_fma_f32 v152, -v108, v55, v152
	v_fma_f32 v153, -v109, v56, v153
	v_fma_f32 v154, -v110, v57, v154
	v_fma_f32 v155, -v111, v58, v155
	ds_read_b128 v[108:111], v28 offset:28800
	s_waitcnt lgkmcnt(11)
	v_fma_f32 v152, -v112, v59, v152
	v_fma_f32 v153, -v113, v60, v153
	v_fma_f32 v154, -v114, v61, v154
	v_fma_f32 v155, -v115, v62, v155
	ds_read_b128 v[112:115], v28 offset:28816
	s_waitcnt lgkmcnt(11)
	v_fma_f32 v152, -v116, v63, v152
	v_fma_f32 v153, -v117, v64, v153
	v_fma_f32 v154, -v118, v65, v154
	v_fma_f32 v155, -v119, v66, v155
	ds_read_b128 v[116:119], v28 offset:28928
	s_waitcnt lgkmcnt(11)
	v_fma_f32 v152, -v120, v67, v152
	v_fma_f32 v153, -v121, v68, v153
	v_fma_f32 v154, -v122, v69, v154
	ds_read_b128 v[120:123], v28 offset:28944
	v_add_f32_e32 v152, v152, v153
	v_add_f32_e32 v154, v154, v155
	v_add_f32_e32 v70, v152, v154
	v_cvt_pk_bf16_f32 v160, v70, v70
	global_store_short v[8:9], v160, off offset:896
	v_cmp_eq_u32_e64 s[56:57], 40, v156
	s_waitcnt lgkmcnt(11)
; #define LAS __attribute__((address_space(3)))
; __device__ __forceinline__ bf16_t f2bf(float f) { return (bf16_t)(pk2(f, f) & 0xFFFFu); }
; __device__ NOINL void g1_phase(const LAS Params* lp, int l, LAS unsigned char* lds) {
;     ...
;             for (int i = 0; i < 64; ++i) {
;                 float s0 = (i == lane) ? 1.f : 0.f, s1 = 0.f, s2 = 0.f, s3 = 0.f;
; #pragma unroll
;                 for (int j4 = 0; j4 < (i + 3) / 4; ++j4) {
;                     const f32x4 lv = *(const LAS f32x4*)(Ld + i * 64 + j4 * 4);
;                     if (j4 * 4 + 0 < i) s0 -= lv[0] * xv[j4 * 4 + 0];
;                     if (j4 * 4 + 1 < i) s1 -= lv[1] * xv[j4 * 4 + 1];
;                     if (j4 * 4 + 2 < i) s2 -= lv[2] * xv[j4 * 4 + 2];
;                     if (j4 * 4 + 3 < i) s3 -= lv[3] * xv[j4 * 4 + 3];
;                 }
;                 xv[i] = (s0 + s1) + (s2 + s3);
;             }
;             bf16_t* Tg = p.Tbuf + ((((size_t)b * 4 + h) * 36 + c3 * 3 + s) * 2 + dir) * 4096;
; #pragma unroll
;             for (int i = 0; i < 64; ++i) Tg[i * 64 + lane] = f2bf(xv[i]);
	s_nop 0
	v_cndmask_b32_e64 v148, 0, 1.0, s[56:57]
	v_fma_f32 v148, -v31, v124, v148
	v_fma_f32 v149, -v125, v32, 0
	v_fma_f32 v150, -v126, v33, 0
	v_fma_f32 v151, -v127, v34, 0
	ds_read_b128 v[124:127], v28 offset:28960
	s_waitcnt lgkmcnt(11)
	v_fma_f32 v148, -v128, v35, v148
	v_fma_f32 v149, -v129, v36, v149
	v_fma_f32 v150, -v130, v37, v150
	v_fma_f32 v151, -v131, v38, v151
	ds_read_b128 v[128:131], v28 offset:28976
	s_waitcnt lgkmcnt(11)
	v_fma_f32 v148, -v132, v39, v148
	v_fma_f32 v149, -v133, v40, v149
	v_fma_f32 v150, -v134, v41, v150
	v_fma_f32 v151, -v135, v42, v151
	ds_read_b128 v[132:135], v28 offset:28992
	s_waitcnt lgkmcnt(11)
	v_fma_f32 v148, -v136, v43, v148
	v_fma_f32 v149, -v137, v44, v149
	v_fma_f32 v150, -v138, v45, v150
	v_fma_f32 v151, -v139, v46, v151
	ds_read_b128 v[136:139], v28 offset:29008
	s_waitcnt lgkmcnt(11)
	v_fma_f32 v148, -v140, v47, v148
	v_fma_f32 v149, -v141, v48, v149
	v_fma_f32 v150, -v142, v49, v150
	v_fma_f32 v151, -v143, v50, v151
	ds_read_b128 v[140:143], v28 offset:29024
	s_waitcnt lgkmcnt(11)
	v_fma_f32 v148, -v144, v51, v148
	v_fma_f32 v149, -v145, v52, v149
	v_fma_f32 v150, -v146, v53, v150
	v_fma_f32 v151, -v147, v54, v151
	ds_read_b128 v[144:147], v28 offset:29040
	s_waitcnt lgkmcnt(11)
	v_fma_f32 v148, -v100, v55, v148
	v_fma_f32 v149, -v101, v56, v149
	v_fma_f32 v150, -v102, v57, v150
	v_fma_f32 v151, -v103, v58, v151
	ds_read_b128 v[100:103], v28 offset:29056
	s_waitcnt lgkmcnt(11)
	v_fma_f32 v148, -v104, v59, v148
	v_fma_f32 v149, -v105, v60, v149
	v_fma_f32 v150, -v106, v61, v150
	v_fma_f32 v151, -v107, v62, v151
	ds_read_b128 v[104:107], v28 offset:29072
	s_waitcnt lgkmcnt(11)
	v_fma_f32 v148, -v108, v63, v148
	v_fma_f32 v149, -v109, v64, v149
	v_fma_f32 v150, -v110, v65, v150
	v_fma_f32 v151, -v111, v66, v151
	ds_read_b128 v[108:111], v28 offset:29088
	s_waitcnt lgkmcnt(11)
	v_fma_f32 v148, -v112, v67, v148
	v_fma_f32 v149, -v113, v68, v149
	v_fma_f32 v150, -v114, v69, v150
	v_fma_f32 v151, -v115, v70, v151
	ds_read_b128 v[112:115], v28 offset:29184
	v_add_f32_e32 v148, v148, v149
	v_add_f32_e32 v150, v150, v151
	v_add_f32_e32 v71, v148, v150
	v_cvt_pk_bf16_f32 v157, v71, v71
	global_store_short v[8:9], v157, off offset:1024
	v_cmp_eq_u32_e64 s[56:57], 41, v156
	s_waitcnt lgkmcnt(11)
	s_nop 0
	v_cndmask_b32_e64 v152, 0, 1.0, s[56:57]
	v_fma_f32 v152, -v31, v116, v152
	v_fma_f32 v153, -v117, v32, 0
	v_fma_f32 v154, -v118, v33, 0
	v_fma_f32 v155, -v119, v34, 0
	ds_read_b128 v[116:119], v28 offset:29200
	s_waitcnt lgkmcnt(11)
	v_fma_f32 v152, -v120, v35, v152
	v_fma_f32 v153, -v121, v36, v153
	v_fma_f32 v154, -v122, v37, v154
	v_fma_f32 v155, -v123, v38, v155
	ds_read_b128 v[120:123], v28 offset:29216
	s_waitcnt lgkmcnt(11)
	v_fma_f32 v152, -v124, v39, v152
	v_fma_f32 v153, -v125, v40, v153
	v_fma_f32 v154, -v126, v41, v154
	v_fma_f32 v155, -v127, v42, v155
	ds_read_b128 v[124:127], v28 offset:29232
	s_waitcnt lgkmcnt(11)
	v_fma_f32 v152, -v128, v43, v152
	v_fma_f32 v153, -v129, v44, v153
	v_fma_f32 v154, -v130, v45, v154
	v_fma_f32 v155, -v131, v46, v155
	ds_read_b128 v[128:131], v28 offset:29248
	s_waitcnt lgkmcnt(11)
	v_fma_f32 v152, -v132, v47, v152
	v_fma_f32 v153, -v133, v48, v153
	v_fma_f32 v154, -v134, v49, v154
	v_fma_f32 v155, -v135, v50, v155
	ds_read_b128 v[132:135], v28 offset:29264
	s_waitcnt lgkmcnt(11)
	v_fma_f32 v152, -v136, v51, v152
	v_fma_f32 v153, -v137, v52, v153
	v_fma_f32 v154, -v138, v53, v154
	v_fma_f32 v155, -v139, v54, v155
	ds_read_b128 v[136:139], v28 offset:29280
	s_waitcnt lgkmcnt(11)
	v_fma_f32 v152, -v140, v55, v152
	v_fma_f32 v153, -v141, v56, v153
	v_fma_f32 v154, -v142, v57, v154
	v_fma_f32 v155, -v143, v58, v155
	ds_read_b128 v[140:143], v28 offset:29296
	s_waitcnt lgkmcnt(11)
	v_fma_f32 v152, -v144, v59, v152
	v_fma_f32 v153, -v145, v60, v153
	v_fma_f32 v154, -v146, v61, v154
	v_fma_f32 v155, -v147, v62, v155
	ds_read_b128 v[144:147], v28 offset:29312
	s_waitcnt lgkmcnt(11)
	v_fma_f32 v152, -v100, v63, v152
	v_fma_f32 v153, -v101, v64, v153
	v_fma_f32 v154, -v102, v65, v154
	v_fma_f32 v155, -v103, v66, v155
	ds_read_b128 v[100:103], v28 offset:29328
	s_waitcnt lgkmcnt(11)
	v_fma_f32 v152, -v104, v67, v152
	v_fma_f32 v153, -v105, v68, v153
	v_fma_f32 v154, -v106, v69, v154
	v_fma_f32 v155, -v107, v70, v155
	ds_read_b128 v[104:107], v28 offset:29344
	s_waitcnt lgkmcnt(11)
	v_fma_f32 v152, -v108, v71, v152
	ds_read_b128 v[108:111], v28 offset:29440
	v_add_f32_e32 v152, v152, v153
	v_add_f32_e32 v154, v154, v155
	v_add_f32_e32 v72, v152, v154
	v_cvt_pk_bf16_f32 v158, v72, v72
	global_store_short v[8:9], v158, off offset:1152
	v_cmp_eq_u32_e64 s[56:57], 42, v156
	s_waitcnt lgkmcnt(11)
	s_nop 0
	v_cndmask_b32_e64 v148, 0, 1.0, s[56:57]
	v_fma_f32 v148, -v31, v112, v148
	v_fma_f32 v149, -v113, v32, 0
	v_fma_f32 v150, -v114, v33, 0
	v_fma_f32 v151, -v115, v34, 0
	ds_read_b128 v[112:115], v28 offset:29456
	s_waitcnt lgkmcnt(11)
	v_fma_f32 v148, -v116, v35, v148
	v_fma_f32 v149, -v117, v36, v149
	v_fma_f32 v150, -v118, v37, v150
	v_fma_f32 v151, -v119, v38, v151
	ds_read_b128 v[116:119], v28 offset:29472
	s_waitcnt lgkmcnt(11)
	v_fma_f32 v148, -v120, v39, v148
	v_fma_f32 v149, -v121, v40, v149
	v_fma_f32 v150, -v122, v41, v150
	v_fma_f32 v151, -v123, v42, v151
	ds_read_b128 v[120:123], v28 offset:29488
	s_waitcnt lgkmcnt(11)
	v_fma_f32 v148, -v124, v43, v148
	v_fma_f32 v149, -v125, v44, v149
	v_fma_f32 v150, -v126, v45, v150
	v_fma_f32 v151, -v127, v46, v151
	ds_read_b128 v[124:127], v28 offset:29504
	s_waitcnt lgkmcnt(11)
	v_fma_f32 v148, -v128, v47, v148
	v_fma_f32 v149, -v129, v48, v149
	v_fma_f32 v150, -v130, v49, v150
	v_fma_f32 v151, -v131, v50, v151
	ds_read_b128 v[128:131], v28 offset:29520
	s_waitcnt lgkmcnt(11)
; #define LAS __attribute__((address_space(3)))
; __device__ __forceinline__ bf16_t f2bf(float f) { return (bf16_t)(pk2(f, f) & 0xFFFFu); }
; __device__ NOINL void g1_phase(const LAS Params* lp, int l, LAS unsigned char* lds) {
;     ...
;             for (int i = 0; i < 64; ++i) {
;                 float s0 = (i == lane) ? 1.f : 0.f, s1 = 0.f, s2 = 0.f, s3 = 0.f;
; #pragma unroll
;                 for (int j4 = 0; j4 < (i + 3) / 4; ++j4) {
;                     const f32x4 lv = *(const LAS f32x4*)(Ld + i * 64 + j4 * 4);
;                     if (j4 * 4 + 0 < i) s0 -= lv[0] * xv[j4 * 4 + 0];
;                     if (j4 * 4 + 1 < i) s1 -= lv[1] * xv[j4 * 4 + 1];
;                     if (j4 * 4 + 2 < i) s2 -= lv[2] * xv[j4 * 4 + 2];
;                     if (j4 * 4 + 3 < i) s3 -= lv[3] * xv[j4 * 4 + 3];
;                 }
;                 xv[i] = (s0 + s1) + (s2 + s3);
;             }
;             bf16_t* Tg = p.Tbuf + ((((size_t)b * 4 + h) * 36 + c3 * 3 + s) * 2 + dir) * 4096;
; #pragma unroll
;             for (int i = 0; i < 64; ++i) Tg[i * 64 + lane] = f2bf(xv[i]);
	v_fma_f32 v148, -v132, v51, v148
	v_fma_f32 v149, -v133, v52, v149
	v_fma_f32 v150, -v134, v53, v150
	v_fma_f32 v151, -v135, v54, v151
	ds_read_b128 v[132:135], v28 offset:29536
	s_waitcnt lgkmcnt(11)
	v_fma_f32 v148, -v136, v55, v148
	v_fma_f32 v149, -v137, v56, v149
	v_fma_f32 v150, -v138, v57, v150
	v_fma_f32 v151, -v139, v58, v151
	ds_read_b128 v[136:139], v28 offset:29552
	s_waitcnt lgkmcnt(11)
	v_fma_f32 v148, -v140, v59, v148
	v_fma_f32 v149, -v141, v60, v149
	v_fma_f32 v150, -v142, v61, v150
	v_fma_f32 v151, -v143, v62, v151
	ds_read_b128 v[140:143], v28 offset:29568
	s_waitcnt lgkmcnt(11)
	v_fma_f32 v148, -v144, v63, v148
	v_fma_f32 v149, -v145, v64, v149
	v_fma_f32 v150, -v146, v65, v150
	v_fma_f32 v151, -v147, v66, v151
	ds_read_b128 v[144:147], v28 offset:29584
	s_waitcnt lgkmcnt(11)
	v_fma_f32 v148, -v100, v67, v148
	v_fma_f32 v149, -v101, v68, v149
	v_fma_f32 v150, -v102, v69, v150
	v_fma_f32 v151, -v103, v70, v151
	ds_read_b128 v[100:103], v28 offset:29600
	s_waitcnt lgkmcnt(11)
	v_fma_f32 v148, -v104, v71, v148
	v_fma_f32 v149, -v105, v72, v149
	ds_read_b128 v[104:107], v28 offset:29696
	v_add_f32_e32 v148, v148, v149
	v_add_f32_e32 v150, v150, v151
	v_add_f32_e32 v73, v148, v150
	v_cvt_pk_bf16_f32 v159, v73, v73
	global_store_short v[8:9], v159, off offset:1280
	v_cmp_eq_u32_e64 s[56:57], 43, v156
	s_waitcnt lgkmcnt(11)
	s_nop 0
	v_cndmask_b32_e64 v152, 0, 1.0, s[56:57]
	v_fma_f32 v152, -v31, v108, v152
	v_fma_f32 v153, -v109, v32, 0
	v_fma_f32 v154, -v110, v33, 0
	v_fma_f32 v155, -v111, v34, 0
	ds_read_b128 v[108:111], v28 offset:29712
	s_waitcnt lgkmcnt(11)
	v_fma_f32 v152, -v112, v35, v152
	v_fma_f32 v153, -v113, v36, v153
	v_fma_f32 v154, -v114, v37, v154
	v_fma_f32 v155, -v115, v38, v155
	ds_read_b128 v[112:115], v28 offset:29728
	s_waitcnt lgkmcnt(11)
	v_fma_f32 v152, -v116, v39, v152
	v_fma_f32 v153, -v117, v40, v153
	v_fma_f32 v154, -v118, v41, v154
	v_fma_f32 v155, -v119, v42, v155
	ds_read_b128 v[116:119], v28 offset:29744
	s_waitcnt lgkmcnt(11)
	v_fma_f32 v152, -v120, v43, v152
	v_fma_f32 v153, -v121, v44, v153
	v_fma_f32 v154, -v122, v45, v154
	v_fma_f32 v155, -v123, v46, v155
	ds_read_b128 v[120:123], v28 offset:29760
	s_waitcnt lgkmcnt(11)
	v_fma_f32 v152, -v124, v47, v152
	v_fma_f32 v153, -v125, v48, v153
	v_fma_f32 v154, -v126, v49, v154
	v_fma_f32 v155, -v127, v50, v155
	ds_read_b128 v[124:127], v28 offset:29776
	s_waitcnt lgkmcnt(11)
	v_fma_f32 v152, -v128, v51, v152
	v_fma_f32 v153, -v129, v52, v153
	v_fma_f32 v154, -v130, v53, v154
	v_fma_f32 v155, -v131, v54, v155
	ds_read_b128 v[128:131], v28 offset:29792
	s_waitcnt lgkmcnt(11)
	v_fma_f32 v152, -v132, v55, v152
	v_fma_f32 v153, -v133, v56, v153
	v_fma_f32 v154, -v134, v57, v154
	v_fma_f32 v155, -v135, v58, v155
	ds_read_b128 v[132:135], v28 offset:29808
	s_waitcnt lgkmcnt(11)
	v_fma_f32 v152, -v136, v59, v152
	v_fma_f32 v153, -v137, v60, v153
	v_fma_f32 v154, -v138, v61, v154
	v_fma_f32 v155, -v139, v62, v155
	ds_read_b128 v[136:139], v28 offset:29824
	s_waitcnt lgkmcnt(11)
	v_fma_f32 v152, -v140, v63, v152
	v_fma_f32 v153, -v141, v64, v153
	v_fma_f32 v154, -v142, v65, v154
	v_fma_f32 v155, -v143, v66, v155
	ds_read_b128 v[140:143], v28 offset:29840
	s_waitcnt lgkmcnt(11)
	v_fma_f32 v152, -v144, v67, v152
	v_fma_f32 v153, -v145, v68, v153
	v_fma_f32 v154, -v146, v69, v154
	v_fma_f32 v155, -v147, v70, v155
	ds_read_b128 v[144:147], v28 offset:29856
	s_waitcnt lgkmcnt(11)
	v_fma_f32 v152, -v100, v71, v152
	v_fma_f32 v153, -v101, v72, v153
	v_fma_f32 v154, -v102, v73, v154
	ds_read_b128 v[100:103], v28 offset:29952
	v_add_f32_e32 v152, v152, v153
	v_add_f32_e32 v154, v154, v155
	v_add_f32_e32 v74, v152, v154
	v_cvt_pk_bf16_f32 v160, v74, v74
	global_store_short v[8:9], v160, off offset:1408
	v_cmp_eq_u32_e64 s[56:57], 44, v156
	s_waitcnt lgkmcnt(11)
	s_nop 0
	v_cndmask_b32_e64 v148, 0, 1.0, s[56:57]
	v_fma_f32 v148, -v31, v104, v148
	v_fma_f32 v149, -v105, v32, 0
	v_fma_f32 v150, -v106, v33, 0
	v_fma_f32 v151, -v107, v34, 0
	ds_read_b128 v[104:107], v28 offset:29968
	s_waitcnt lgkmcnt(11)
	v_fma_f32 v148, -v108, v35, v148
	v_fma_f32 v149, -v109, v36, v149
	v_fma_f32 v150, -v110, v37, v150
	v_fma_f32 v151, -v111, v38, v151
	ds_read_b128 v[108:111], v28 offset:29984
	s_waitcnt lgkmcnt(11)
	v_fma_f32 v148, -v112, v39, v148
	v_fma_f32 v149, -v113, v40, v149
	v_fma_f32 v150, -v114, v41, v150
	v_fma_f32 v151, -v115, v42, v151
	ds_read_b128 v[112:115], v28 offset:30000
	s_waitcnt lgkmcnt(11)
	v_fma_f32 v148, -v116, v43, v148
	v_fma_f32 v149, -v117, v44, v149
	v_fma_f32 v150, -v118, v45, v150
	v_fma_f32 v151, -v119, v46, v151
	ds_read_b128 v[116:119], v28 offset:30016
	s_waitcnt lgkmcnt(11)
	v_fma_f32 v148, -v120, v47, v148
	v_fma_f32 v149, -v121, v48, v149
	v_fma_f32 v150, -v122, v49, v150
	v_fma_f32 v151, -v123, v50, v151
	ds_read_b128 v[120:123], v28 offset:30032
	s_waitcnt lgkmcnt(11)
	v_fma_f32 v148, -v124, v51, v148
	v_fma_f32 v149, -v125, v52, v149
	v_fma_f32 v150, -v126, v53, v150
	v_fma_f32 v151, -v127, v54, v151
	ds_read_b128 v[124:127], v28 offset:30048
	s_waitcnt lgkmcnt(11)
	v_fma_f32 v148, -v128, v55, v148
	v_fma_f32 v149, -v129, v56, v149
	v_fma_f32 v150, -v130, v57, v150
	v_fma_f32 v151, -v131, v58, v151
	ds_read_b128 v[128:131], v28 offset:30064
	s_waitcnt lgkmcnt(11)
	v_fma_f32 v148, -v132, v59, v148
	v_fma_f32 v149, -v133, v60, v149
	v_fma_f32 v150, -v134, v61, v150
	v_fma_f32 v151, -v135, v62, v151
	ds_read_b128 v[132:135], v28 offset:30080
	s_waitcnt lgkmcnt(11)
	v_fma_f32 v148, -v136, v63, v148
	v_fma_f32 v149, -v137, v64, v149
	v_fma_f32 v150, -v138, v65, v150
	v_fma_f32 v151, -v139, v66, v151
	ds_read_b128 v[136:139], v28 offset:30096
	s_waitcnt lgkmcnt(11)
; #define LAS __attribute__((address_space(3)))
; __device__ __forceinline__ bf16_t f2bf(float f) { return (bf16_t)(pk2(f, f) & 0xFFFFu); }
; __device__ NOINL void g1_phase(const LAS Params* lp, int l, LAS unsigned char* lds) {
;     ...
;             for (int i = 0; i < 64; ++i) {
;                 float s0 = (i == lane) ? 1.f : 0.f, s1 = 0.f, s2 = 0.f, s3 = 0.f;
; #pragma unroll
;                 for (int j4 = 0; j4 < (i + 3) / 4; ++j4) {
;                     const f32x4 lv = *(const LAS f32x4*)(Ld + i * 64 + j4 * 4);
;                     if (j4 * 4 + 0 < i) s0 -= lv[0] * xv[j4 * 4 + 0];
;                     if (j4 * 4 + 1 < i) s1 -= lv[1] * xv[j4 * 4 + 1];
;                     if (j4 * 4 + 2 < i) s2 -= lv[2] * xv[j4 * 4 + 2];
;                     if (j4 * 4 + 3 < i) s3 -= lv[3] * xv[j4 * 4 + 3];
;                 }
;                 xv[i] = (s0 + s1) + (s2 + s3);
;             }
;             bf16_t* Tg = p.Tbuf + ((((size_t)b * 4 + h) * 36 + c3 * 3 + s) * 2 + dir) * 4096;
; #pragma unroll
;             for (int i = 0; i < 64; ++i) Tg[i * 64 + lane] = f2bf(xv[i]);
	v_fma_f32 v148, -v140, v67, v148
	v_fma_f32 v149, -v141, v68, v149
	v_fma_f32 v150, -v142, v69, v150
	v_fma_f32 v151, -v143, v70, v151
	ds_read_b128 v[140:143], v28 offset:30112
	s_waitcnt lgkmcnt(11)
	v_fma_f32 v148, -v144, v71, v148
	v_fma_f32 v149, -v145, v72, v149
	v_fma_f32 v150, -v146, v73, v150
	v_fma_f32 v151, -v147, v74, v151
	ds_read_b128 v[144:147], v28 offset:30128
	v_add_f32_e32 v148, v148, v149
	v_add_f32_e32 v150, v150, v151
	v_add_f32_e32 v75, v148, v150
	v_cvt_pk_bf16_f32 v157, v75, v75
	global_store_short v[8:9], v157, off offset:1536
	v_cmp_eq_u32_e64 s[56:57], 45, v156
	s_waitcnt lgkmcnt(11)
	s_nop 0
	v_cndmask_b32_e64 v152, 0, 1.0, s[56:57]
	v_fma_f32 v152, -v31, v100, v152
	v_fma_f32 v153, -v101, v32, 0
	v_fma_f32 v154, -v102, v33, 0
	v_fma_f32 v155, -v103, v34, 0
	ds_read_b128 v[100:103], v28 offset:30208
	s_waitcnt lgkmcnt(11)
	v_fma_f32 v152, -v104, v35, v152
	v_fma_f32 v153, -v105, v36, v153
	v_fma_f32 v154, -v106, v37, v154
	v_fma_f32 v155, -v107, v38, v155
	ds_read_b128 v[104:107], v28 offset:30224
	s_waitcnt lgkmcnt(11)
	v_fma_f32 v152, -v108, v39, v152
	v_fma_f32 v153, -v109, v40, v153
	v_fma_f32 v154, -v110, v41, v154
	v_fma_f32 v155, -v111, v42, v155
	ds_read_b128 v[108:111], v28 offset:30240
	s_waitcnt lgkmcnt(11)
	v_fma_f32 v152, -v112, v43, v152
	v_fma_f32 v153, -v113, v44, v153
	v_fma_f32 v154, -v114, v45, v154
	v_fma_f32 v155, -v115, v46, v155
	ds_read_b128 v[112:115], v28 offset:30256
	s_waitcnt lgkmcnt(11)
	v_fma_f32 v152, -v116, v47, v152
	v_fma_f32 v153, -v117, v48, v153
	v_fma_f32 v154, -v118, v49, v154
	v_fma_f32 v155, -v119, v50, v155
	ds_read_b128 v[116:119], v28 offset:30272
	s_waitcnt lgkmcnt(11)
	v_fma_f32 v152, -v120, v51, v152
	v_fma_f32 v153, -v121, v52, v153
	v_fma_f32 v154, -v122, v53, v154
	v_fma_f32 v155, -v123, v54, v155
	ds_read_b128 v[120:123], v28 offset:30288
	s_waitcnt lgkmcnt(11)
	v_fma_f32 v152, -v124, v55, v152
	v_fma_f32 v153, -v125, v56, v153
	v_fma_f32 v154, -v126, v57, v154
	v_fma_f32 v155, -v127, v58, v155
	ds_read_b128 v[124:127], v28 offset:30304
	s_waitcnt lgkmcnt(11)
	v_fma_f32 v152, -v128, v59, v152
	v_fma_f32 v153, -v129, v60, v153
	v_fma_f32 v154, -v130, v61, v154
	v_fma_f32 v155, -v131, v62, v155
	ds_read_b128 v[128:131], v28 offset:30320
	s_waitcnt lgkmcnt(11)
	v_fma_f32 v152, -v132, v63, v152
	v_fma_f32 v153, -v133, v64, v153
	v_fma_f32 v154, -v134, v65, v154
	v_fma_f32 v155, -v135, v66, v155
	ds_read_b128 v[132:135], v28 offset:30336
	s_waitcnt lgkmcnt(11)
	v_fma_f32 v152, -v136, v67, v152
	v_fma_f32 v153, -v137, v68, v153
	v_fma_f32 v154, -v138, v69, v154
	v_fma_f32 v155, -v139, v70, v155
	ds_read_b128 v[136:139], v28 offset:30352
	s_waitcnt lgkmcnt(11)
	v_fma_f32 v152, -v140, v71, v152
	v_fma_f32 v153, -v141, v72, v153
	v_fma_f32 v154, -v142, v73, v154
	v_fma_f32 v155, -v143, v74, v155
	ds_read_b128 v[140:143], v28 offset:30368
	s_waitcnt lgkmcnt(11)
	v_fma_f32 v152, -v144, v75, v152
	ds_read_b128 v[144:147], v28 offset:30384
	v_add_f32_e32 v152, v152, v153
	v_add_f32_e32 v154, v154, v155
	v_add_f32_e32 v76, v152, v154
	v_cvt_pk_bf16_f32 v158, v76, v76
	global_store_short v[8:9], v158, off offset:1664
	v_cmp_eq_u32_e64 s[56:57], 46, v156
	s_waitcnt lgkmcnt(11)
	s_nop 0
	v_cndmask_b32_e64 v148, 0, 1.0, s[56:57]
	v_fma_f32 v148, -v31, v100, v148
	v_fma_f32 v149, -v101, v32, 0
	v_fma_f32 v150, -v102, v33, 0
	v_fma_f32 v151, -v103, v34, 0
	ds_read_b128 v[100:103], v28 offset:30464
	s_waitcnt lgkmcnt(11)
	v_fma_f32 v148, -v104, v35, v148
	v_fma_f32 v149, -v105, v36, v149
	v_fma_f32 v150, -v106, v37, v150
	v_fma_f32 v151, -v107, v38, v151
	ds_read_b128 v[104:107], v28 offset:30480
	s_waitcnt lgkmcnt(11)
	v_fma_f32 v148, -v108, v39, v148
	v_fma_f32 v149, -v109, v40, v149
	v_fma_f32 v150, -v110, v41, v150
	v_fma_f32 v151, -v111, v42, v151
	ds_read_b128 v[108:111], v28 offset:30496
	s_waitcnt lgkmcnt(11)
	v_fma_f32 v148, -v112, v43, v148
	v_fma_f32 v149, -v113, v44, v149
	v_fma_f32 v150, -v114, v45, v150
	v_fma_f32 v151, -v115, v46, v151
	ds_read_b128 v[112:115], v28 offset:30512
	s_waitcnt lgkmcnt(11)
	v_fma_f32 v148, -v116, v47, v148
	v_fma_f32 v149, -v117, v48, v149
	v_fma_f32 v150, -v118, v49, v150
	v_fma_f32 v151, -v119, v50, v151
	ds_read_b128 v[116:119], v28 offset:30528
	s_waitcnt lgkmcnt(11)
	v_fma_f32 v148, -v120, v51, v148
	v_fma_f32 v149, -v121, v52, v149
	v_fma_f32 v150, -v122, v53, v150
	v_fma_f32 v151, -v123, v54, v151
	ds_read_b128 v[120:123], v28 offset:30544
	s_waitcnt lgkmcnt(11)
	v_fma_f32 v148, -v124, v55, v148
	v_fma_f32 v149, -v125, v56, v149
	v_fma_f32 v150, -v126, v57, v150
	v_fma_f32 v151, -v127, v58, v151
	ds_read_b128 v[124:127], v28 offset:30560
	s_waitcnt lgkmcnt(11)
	v_fma_f32 v148, -v128, v59, v148
	v_fma_f32 v149, -v129, v60, v149
	v_fma_f32 v150, -v130, v61, v150
	v_fma_f32 v151, -v131, v62, v151
	ds_read_b128 v[128:131], v28 offset:30576
	s_waitcnt lgkmcnt(11)
	v_fma_f32 v148, -v132, v63, v148
	v_fma_f32 v149, -v133, v64, v149
	v_fma_f32 v150, -v134, v65, v150
	v_fma_f32 v151, -v135, v66, v151
	ds_read_b128 v[132:135], v28 offset:30592
	s_waitcnt lgkmcnt(11)
	v_fma_f32 v148, -v136, v67, v148
	v_fma_f32 v149, -v137, v68, v149
	v_fma_f32 v150, -v138, v69, v150
	v_fma_f32 v151, -v139, v70, v151
	ds_read_b128 v[136:139], v28 offset:30608
	s_waitcnt lgkmcnt(11)
	v_fma_f32 v148, -v140, v71, v148
	v_fma_f32 v149, -v141, v72, v149
	v_fma_f32 v150, -v142, v73, v150
	v_fma_f32 v151, -v143, v74, v151
	ds_read_b128 v[140:143], v28 offset:30624
	s_waitcnt lgkmcnt(11)
	v_fma_f32 v148, -v144, v75, v148
	v_fma_f32 v149, -v145, v76, v149
	ds_read_b128 v[144:147], v28 offset:30640
	v_add_f32_e32 v148, v148, v149
	v_add_f32_e32 v150, v150, v151
	v_add_f32_e32 v77, v148, v150
	v_cvt_pk_bf16_f32 v159, v77, v77
	global_store_short v[8:9], v159, off offset:1792
	v_cmp_eq_u32_e64 s[56:57], 47, v156
	s_waitcnt lgkmcnt(11)
; #define LAS __attribute__((address_space(3)))
; __device__ __forceinline__ bf16_t f2bf(float f) { return (bf16_t)(pk2(f, f) & 0xFFFFu); }
; __device__ NOINL void g1_phase(const LAS Params* lp, int l, LAS unsigned char* lds) {
;     ...
;             for (int i = 0; i < 64; ++i) {
;                 float s0 = (i == lane) ? 1.f : 0.f, s1 = 0.f, s2 = 0.f, s3 = 0.f;
; #pragma unroll
;                 for (int j4 = 0; j4 < (i + 3) / 4; ++j4) {
;                     const f32x4 lv = *(const LAS f32x4*)(Ld + i * 64 + j4 * 4);
;                     if (j4 * 4 + 0 < i) s0 -= lv[0] * xv[j4 * 4 + 0];
;                     if (j4 * 4 + 1 < i) s1 -= lv[1] * xv[j4 * 4 + 1];
;                     if (j4 * 4 + 2 < i) s2 -= lv[2] * xv[j4 * 4 + 2];
;                     if (j4 * 4 + 3 < i) s3 -= lv[3] * xv[j4 * 4 + 3];
;                 }
;                 xv[i] = (s0 + s1) + (s2 + s3);
;             }
;             bf16_t* Tg = p.Tbuf + ((((size_t)b * 4 + h) * 36 + c3 * 3 + s) * 2 + dir) * 4096;
; #pragma unroll
;             for (int i = 0; i < 64; ++i) Tg[i * 64 + lane] = f2bf(xv[i]);
	s_nop 0
	v_cndmask_b32_e64 v152, 0, 1.0, s[56:57]
	v_fma_f32 v152, -v31, v100, v152
	v_fma_f32 v153, -v101, v32, 0
	v_fma_f32 v154, -v102, v33, 0
	v_fma_f32 v155, -v103, v34, 0
	ds_read_b128 v[100:103], v28 offset:30720
	s_waitcnt lgkmcnt(11)
	v_fma_f32 v152, -v104, v35, v152
	v_fma_f32 v153, -v105, v36, v153
	v_fma_f32 v154, -v106, v37, v154
	v_fma_f32 v155, -v107, v38, v155
	ds_read_b128 v[104:107], v28 offset:30736
	s_waitcnt lgkmcnt(11)
	v_fma_f32 v152, -v108, v39, v152
	v_fma_f32 v153, -v109, v40, v153
	v_fma_f32 v154, -v110, v41, v154
	v_fma_f32 v155, -v111, v42, v155
	ds_read_b128 v[108:111], v28 offset:30752
	s_waitcnt lgkmcnt(11)
	v_fma_f32 v152, -v112, v43, v152
	v_fma_f32 v153, -v113, v44, v153
	v_fma_f32 v154, -v114, v45, v154
	v_fma_f32 v155, -v115, v46, v155
	ds_read_b128 v[112:115], v28 offset:30768
	s_waitcnt lgkmcnt(11)
	v_fma_f32 v152, -v116, v47, v152
	v_fma_f32 v153, -v117, v48, v153
	v_fma_f32 v154, -v118, v49, v154
	v_fma_f32 v155, -v119, v50, v155
	ds_read_b128 v[116:119], v28 offset:30784
	s_waitcnt lgkmcnt(11)
	v_fma_f32 v152, -v120, v51, v152
	v_fma_f32 v153, -v121, v52, v153
	v_fma_f32 v154, -v122, v53, v154
	v_fma_f32 v155, -v123, v54, v155
	ds_read_b128 v[120:123], v28 offset:30800
	s_waitcnt lgkmcnt(11)
	v_fma_f32 v152, -v124, v55, v152
	v_fma_f32 v153, -v125, v56, v153
	v_fma_f32 v154, -v126, v57, v154
	v_fma_f32 v155, -v127, v58, v155
	ds_read_b128 v[124:127], v28 offset:30816
	s_waitcnt lgkmcnt(11)
	v_fma_f32 v152, -v128, v59, v152
	v_fma_f32 v153, -v129, v60, v153
	v_fma_f32 v154, -v130, v61, v154
	v_fma_f32 v155, -v131, v62, v155
	ds_read_b128 v[128:131], v28 offset:30832
	s_waitcnt lgkmcnt(11)
	v_fma_f32 v152, -v132, v63, v152
	v_fma_f32 v153, -v133, v64, v153
	v_fma_f32 v154, -v134, v65, v154
	v_fma_f32 v155, -v135, v66, v155
	ds_read_b128 v[132:135], v28 offset:30848
	s_waitcnt lgkmcnt(11)
	v_fma_f32 v152, -v136, v67, v152
	v_fma_f32 v153, -v137, v68, v153
	v_fma_f32 v154, -v138, v69, v154
	v_fma_f32 v155, -v139, v70, v155
	ds_read_b128 v[136:139], v28 offset:30864
	s_waitcnt lgkmcnt(11)
	v_fma_f32 v152, -v140, v71, v152
	v_fma_f32 v153, -v141, v72, v153
	v_fma_f32 v154, -v142, v73, v154
	v_fma_f32 v155, -v143, v74, v155
	ds_read_b128 v[140:143], v28 offset:30880
	s_waitcnt lgkmcnt(11)
	v_fma_f32 v152, -v144, v75, v152
	v_fma_f32 v153, -v145, v76, v153
	v_fma_f32 v154, -v146, v77, v154
	ds_read_b128 v[144:147], v28 offset:30896
	v_add_f32_e32 v152, v152, v153
	v_add_f32_e32 v154, v154, v155
	v_add_f32_e32 v78, v152, v154
	v_cvt_pk_bf16_f32 v160, v78, v78
	global_store_short v[8:9], v160, off offset:1920
	v_cmp_eq_u32_e64 s[56:57], 48, v156
	s_waitcnt lgkmcnt(11)
	s_nop 0
	v_cndmask_b32_e64 v148, 0, 1.0, s[56:57]
	v_fma_f32 v148, -v31, v100, v148
	v_fma_f32 v149, -v101, v32, 0
	v_fma_f32 v150, -v102, v33, 0
	v_fma_f32 v151, -v103, v34, 0
	ds_read_b128 v[100:103], v28 offset:30976
	s_waitcnt lgkmcnt(11)
	v_fma_f32 v148, -v104, v35, v148
	v_fma_f32 v149, -v105, v36, v149
	v_fma_f32 v150, -v106, v37, v150
	v_fma_f32 v151, -v107, v38, v151
	ds_read_b128 v[104:107], v28 offset:30992
	s_waitcnt lgkmcnt(11)
	v_fma_f32 v148, -v108, v39, v148
	v_fma_f32 v149, -v109, v40, v149
	v_fma_f32 v150, -v110, v41, v150
	v_fma_f32 v151, -v111, v42, v151
	ds_read_b128 v[108:111], v28 offset:31008
	s_waitcnt lgkmcnt(11)
	v_fma_f32 v148, -v112, v43, v148
	v_fma_f32 v149, -v113, v44, v149
	v_fma_f32 v150, -v114, v45, v150
	v_fma_f32 v151, -v115, v46, v151
	ds_read_b128 v[112:115], v28 offset:31024
	s_waitcnt lgkmcnt(11)
	v_fma_f32 v148, -v116, v47, v148
	v_fma_f32 v149, -v117, v48, v149
	v_fma_f32 v150, -v118, v49, v150
	v_fma_f32 v151, -v119, v50, v151
	ds_read_b128 v[116:119], v28 offset:31040
	s_waitcnt lgkmcnt(11)
	v_fma_f32 v148, -v120, v51, v148
	v_fma_f32 v149, -v121, v52, v149
	v_fma_f32 v150, -v122, v53, v150
	v_fma_f32 v151, -v123, v54, v151
	ds_read_b128 v[120:123], v28 offset:31056
	s_waitcnt lgkmcnt(11)
	v_fma_f32 v148, -v124, v55, v148
	v_fma_f32 v149, -v125, v56, v149
	v_fma_f32 v150, -v126, v57, v150
	v_fma_f32 v151, -v127, v58, v151
	ds_read_b128 v[124:127], v28 offset:31072
	s_waitcnt lgkmcnt(11)
	v_fma_f32 v148, -v128, v59, v148
	v_fma_f32 v149, -v129, v60, v149
	v_fma_f32 v150, -v130, v61, v150
	v_fma_f32 v151, -v131, v62, v151
	ds_read_b128 v[128:131], v28 offset:31088
	s_waitcnt lgkmcnt(11)
	v_fma_f32 v148, -v132, v63, v148
	v_fma_f32 v149, -v133, v64, v149
	v_fma_f32 v150, -v134, v65, v150
	v_fma_f32 v151, -v135, v66, v151
	ds_read_b128 v[132:135], v28 offset:31104
	s_waitcnt lgkmcnt(11)
	v_fma_f32 v148, -v136, v67, v148
	v_fma_f32 v149, -v137, v68, v149
	v_fma_f32 v150, -v138, v69, v150
	v_fma_f32 v151, -v139, v70, v151
	ds_read_b128 v[136:139], v28 offset:31120
	s_waitcnt lgkmcnt(11)
	v_fma_f32 v148, -v140, v71, v148
	v_fma_f32 v149, -v141, v72, v149
	v_fma_f32 v150, -v142, v73, v150
	v_fma_f32 v151, -v143, v74, v151
	ds_read_b128 v[140:143], v28 offset:31136
	s_waitcnt lgkmcnt(11)
	v_fma_f32 v148, -v144, v75, v148
	v_fma_f32 v149, -v145, v76, v149
	v_fma_f32 v150, -v146, v77, v150
	v_fma_f32 v151, -v147, v78, v151
	ds_read_b128 v[144:147], v28 offset:31152
	v_add_f32_e32 v148, v148, v149
	v_add_f32_e32 v150, v150, v151
	v_add_f32_e32 v79, v148, v150
	v_cvt_pk_bf16_f32 v157, v79, v79
	global_store_short v[8:9], v157, off offset:2048
	v_cmp_eq_u32_e64 s[56:57], 49, v156
	s_waitcnt lgkmcnt(11)
	s_nop 0
	v_cndmask_b32_e64 v152, 0, 1.0, s[56:57]
	v_fma_f32 v152, -v31, v100, v152
	v_fma_f32 v153, -v101, v32, 0
	v_fma_f32 v154, -v102, v33, 0
	v_fma_f32 v155, -v103, v34, 0
	ds_read_b128 v[100:103], v28 offset:31168
	s_waitcnt lgkmcnt(11)
; #define LAS __attribute__((address_space(3)))
; __device__ __forceinline__ bf16_t f2bf(float f) { return (bf16_t)(pk2(f, f) & 0xFFFFu); }
; __device__ NOINL void g1_phase(const LAS Params* lp, int l, LAS unsigned char* lds) {
;     ...
;             for (int i = 0; i < 64; ++i) {
;                 float s0 = (i == lane) ? 1.f : 0.f, s1 = 0.f, s2 = 0.f, s3 = 0.f;
; #pragma unroll
;                 for (int j4 = 0; j4 < (i + 3) / 4; ++j4) {
;                     const f32x4 lv = *(const LAS f32x4*)(Ld + i * 64 + j4 * 4);
;                     if (j4 * 4 + 0 < i) s0 -= lv[0] * xv[j4 * 4 + 0];
;                     if (j4 * 4 + 1 < i) s1 -= lv[1] * xv[j4 * 4 + 1];
;                     if (j4 * 4 + 2 < i) s2 -= lv[2] * xv[j4 * 4 + 2];
;                     if (j4 * 4 + 3 < i) s3 -= lv[3] * xv[j4 * 4 + 3];
;                 }
;                 xv[i] = (s0 + s1) + (s2 + s3);
;             }
;             bf16_t* Tg = p.Tbuf + ((((size_t)b * 4 + h) * 36 + c3 * 3 + s) * 2 + dir) * 4096;
; #pragma unroll
;             for (int i = 0; i < 64; ++i) Tg[i * 64 + lane] = f2bf(xv[i]);
	v_fma_f32 v152, -v104, v35, v152
	v_fma_f32 v153, -v105, v36, v153
	v_fma_f32 v154, -v106, v37, v154
	v_fma_f32 v155, -v107, v38, v155
	ds_read_b128 v[104:107], v28 offset:31232
	s_waitcnt lgkmcnt(11)
	v_fma_f32 v152, -v108, v39, v152
	v_fma_f32 v153, -v109, v40, v153
	v_fma_f32 v154, -v110, v41, v154
	v_fma_f32 v155, -v111, v42, v155
	ds_read_b128 v[108:111], v28 offset:31248
	s_waitcnt lgkmcnt(11)
	v_fma_f32 v152, -v112, v43, v152
	v_fma_f32 v153, -v113, v44, v153
	v_fma_f32 v154, -v114, v45, v154
	v_fma_f32 v155, -v115, v46, v155
	ds_read_b128 v[112:115], v28 offset:31264
	s_waitcnt lgkmcnt(11)
	v_fma_f32 v152, -v116, v47, v152
	v_fma_f32 v153, -v117, v48, v153
	v_fma_f32 v154, -v118, v49, v154
	v_fma_f32 v155, -v119, v50, v155
	ds_read_b128 v[116:119], v28 offset:31280
	s_waitcnt lgkmcnt(11)
	v_fma_f32 v152, -v120, v51, v152
	v_fma_f32 v153, -v121, v52, v153
	v_fma_f32 v154, -v122, v53, v154
	v_fma_f32 v155, -v123, v54, v155
	ds_read_b128 v[120:123], v28 offset:31296
	s_waitcnt lgkmcnt(11)
	v_fma_f32 v152, -v124, v55, v152
	v_fma_f32 v153, -v125, v56, v153
	v_fma_f32 v154, -v126, v57, v154
	v_fma_f32 v155, -v127, v58, v155
	ds_read_b128 v[124:127], v28 offset:31312
	s_waitcnt lgkmcnt(11)
	v_fma_f32 v152, -v128, v59, v152
	v_fma_f32 v153, -v129, v60, v153
	v_fma_f32 v154, -v130, v61, v154
	v_fma_f32 v155, -v131, v62, v155
	ds_read_b128 v[128:131], v28 offset:31328
	s_waitcnt lgkmcnt(11)
	v_fma_f32 v152, -v132, v63, v152
	v_fma_f32 v153, -v133, v64, v153
	v_fma_f32 v154, -v134, v65, v154
	v_fma_f32 v155, -v135, v66, v155
	ds_read_b128 v[132:135], v28 offset:31344
	s_waitcnt lgkmcnt(11)
	v_fma_f32 v152, -v136, v67, v152
	v_fma_f32 v153, -v137, v68, v153
	v_fma_f32 v154, -v138, v69, v154
	v_fma_f32 v155, -v139, v70, v155
	ds_read_b128 v[136:139], v28 offset:31360
	s_waitcnt lgkmcnt(11)
	v_fma_f32 v152, -v140, v71, v152
	v_fma_f32 v153, -v141, v72, v153
	v_fma_f32 v154, -v142, v73, v154
	v_fma_f32 v155, -v143, v74, v155
	ds_read_b128 v[140:143], v28 offset:31376
	s_waitcnt lgkmcnt(11)
	v_fma_f32 v152, -v144, v75, v152
	v_fma_f32 v153, -v145, v76, v153
	v_fma_f32 v154, -v146, v77, v154
	v_fma_f32 v155, -v147, v78, v155
	ds_read_b128 v[144:147], v28 offset:31392
	s_waitcnt lgkmcnt(11)
	v_fma_f32 v152, -v100, v79, v152
	ds_read_b128 v[100:103], v28 offset:31408
	v_add_f32_e32 v152, v152, v153
	v_add_f32_e32 v154, v154, v155
	v_add_f32_e32 v80, v152, v154
	v_cvt_pk_bf16_f32 v158, v80, v80
	global_store_short v[8:9], v158, off offset:2176
	v_cmp_eq_u32_e64 s[56:57], 50, v156
	s_waitcnt lgkmcnt(11)
	s_nop 0
	v_cndmask_b32_e64 v148, 0, 1.0, s[56:57]
	v_fma_f32 v148, -v31, v104, v148
	v_fma_f32 v149, -v105, v32, 0
	v_fma_f32 v150, -v106, v33, 0
	v_fma_f32 v151, -v107, v34, 0
	ds_read_b128 v[104:107], v28 offset:31424
	s_waitcnt lgkmcnt(11)
	v_fma_f32 v148, -v108, v35, v148
	v_fma_f32 v149, -v109, v36, v149
	v_fma_f32 v150, -v110, v37, v150
	v_fma_f32 v151, -v111, v38, v151
	ds_read_b128 v[108:111], v28 offset:31488
	s_waitcnt lgkmcnt(11)
	v_fma_f32 v148, -v112, v39, v148
	v_fma_f32 v149, -v113, v40, v149
	v_fma_f32 v150, -v114, v41, v150
	v_fma_f32 v151, -v115, v42, v151
	ds_read_b128 v[112:115], v28 offset:31504
	s_waitcnt lgkmcnt(11)
	v_fma_f32 v148, -v116, v43, v148
	v_fma_f32 v149, -v117, v44, v149
	v_fma_f32 v150, -v118, v45, v150
	v_fma_f32 v151, -v119, v46, v151
	ds_read_b128 v[116:119], v28 offset:31520
	s_waitcnt lgkmcnt(11)
	v_fma_f32 v148, -v120, v47, v148
	v_fma_f32 v149, -v121, v48, v149
	v_fma_f32 v150, -v122, v49, v150
	v_fma_f32 v151, -v123, v50, v151
	ds_read_b128 v[120:123], v28 offset:31536
	s_waitcnt lgkmcnt(11)
	v_fma_f32 v148, -v124, v51, v148
	v_fma_f32 v149, -v125, v52, v149
	v_fma_f32 v150, -v126, v53, v150
	v_fma_f32 v151, -v127, v54, v151
	ds_read_b128 v[124:127], v28 offset:31552
	s_waitcnt lgkmcnt(11)
	v_fma_f32 v148, -v128, v55, v148
	v_fma_f32 v149, -v129, v56, v149
	v_fma_f32 v150, -v130, v57, v150
	v_fma_f32 v151, -v131, v58, v151
	ds_read_b128 v[128:131], v28 offset:31568
	s_waitcnt lgkmcnt(11)
	v_fma_f32 v148, -v132, v59, v148
	v_fma_f32 v149, -v133, v60, v149
	v_fma_f32 v150, -v134, v61, v150
	v_fma_f32 v151, -v135, v62, v151
	ds_read_b128 v[132:135], v28 offset:31584
	s_waitcnt lgkmcnt(11)
	v_fma_f32 v148, -v136, v63, v148
	v_fma_f32 v149, -v137, v64, v149
	v_fma_f32 v150, -v138, v65, v150
	v_fma_f32 v151, -v139, v66, v151
	ds_read_b128 v[136:139], v28 offset:31600
	s_waitcnt lgkmcnt(11)
	v_fma_f32 v148, -v140, v67, v148
	v_fma_f32 v149, -v141, v68, v149
	v_fma_f32 v150, -v142, v69, v150
	v_fma_f32 v151, -v143, v70, v151
	ds_read_b128 v[140:143], v28 offset:31616
	s_waitcnt lgkmcnt(11)
	v_fma_f32 v148, -v144, v71, v148
	v_fma_f32 v149, -v145, v72, v149
	v_fma_f32 v150, -v146, v73, v150
	v_fma_f32 v151, -v147, v74, v151
	ds_read_b128 v[144:147], v28 offset:31632
	s_waitcnt lgkmcnt(11)
	v_fma_f32 v148, -v100, v75, v148
	v_fma_f32 v149, -v101, v76, v149
	v_fma_f32 v150, -v102, v77, v150
	v_fma_f32 v151, -v103, v78, v151
	ds_read_b128 v[100:103], v28 offset:31648
	s_waitcnt lgkmcnt(11)
	v_fma_f32 v148, -v104, v79, v148
	v_fma_f32 v149, -v105, v80, v149
	ds_read_b128 v[104:107], v28 offset:31664
	v_add_f32_e32 v148, v148, v149
	v_add_f32_e32 v150, v150, v151
	v_add_f32_e32 v81, v148, v150
	v_cvt_pk_bf16_f32 v159, v81, v81
	global_store_short v[8:9], v159, off offset:2304
	v_cmp_eq_u32_e64 s[56:57], 51, v156
	s_waitcnt lgkmcnt(11)
	s_nop 0
	v_cndmask_b32_e64 v152, 0, 1.0, s[56:57]
	v_fma_f32 v152, -v31, v108, v152
	v_fma_f32 v153, -v109, v32, 0
	v_fma_f32 v154, -v110, v33, 0
	v_fma_f32 v155, -v111, v34, 0
	ds_read_b128 v[108:111], v28 offset:31680
	s_waitcnt lgkmcnt(11)
; #define LAS __attribute__((address_space(3)))
; __device__ __forceinline__ bf16_t f2bf(float f) { return (bf16_t)(pk2(f, f) & 0xFFFFu); }
; __device__ NOINL void g1_phase(const LAS Params* lp, int l, LAS unsigned char* lds) {
;     ...
;             for (int i = 0; i < 64; ++i) {
;                 float s0 = (i == lane) ? 1.f : 0.f, s1 = 0.f, s2 = 0.f, s3 = 0.f;
; #pragma unroll
;                 for (int j4 = 0; j4 < (i + 3) / 4; ++j4) {
;                     const f32x4 lv = *(const LAS f32x4*)(Ld + i * 64 + j4 * 4);
;                     if (j4 * 4 + 0 < i) s0 -= lv[0] * xv[j4 * 4 + 0];
;                     if (j4 * 4 + 1 < i) s1 -= lv[1] * xv[j4 * 4 + 1];
;                     if (j4 * 4 + 2 < i) s2 -= lv[2] * xv[j4 * 4 + 2];
;                     if (j4 * 4 + 3 < i) s3 -= lv[3] * xv[j4 * 4 + 3];
;                 }
;                 xv[i] = (s0 + s1) + (s2 + s3);
;             }
;             bf16_t* Tg = p.Tbuf + ((((size_t)b * 4 + h) * 36 + c3 * 3 + s) * 2 + dir) * 4096;
; #pragma unroll
;             for (int i = 0; i < 64; ++i) Tg[i * 64 + lane] = f2bf(xv[i]);
	v_fma_f32 v152, -v112, v35, v152
	v_fma_f32 v153, -v113, v36, v153
	v_fma_f32 v154, -v114, v37, v154
	v_fma_f32 v155, -v115, v38, v155
	ds_read_b128 v[112:115], v28 offset:31744
	s_waitcnt lgkmcnt(11)
	v_fma_f32 v152, -v116, v39, v152
	v_fma_f32 v153, -v117, v40, v153
	v_fma_f32 v154, -v118, v41, v154
	v_fma_f32 v155, -v119, v42, v155
	ds_read_b128 v[116:119], v28 offset:31760
	s_waitcnt lgkmcnt(11)
	v_fma_f32 v152, -v120, v43, v152
	v_fma_f32 v153, -v121, v44, v153
	v_fma_f32 v154, -v122, v45, v154
	v_fma_f32 v155, -v123, v46, v155
	ds_read_b128 v[120:123], v28 offset:31776
	s_waitcnt lgkmcnt(11)
	v_fma_f32 v152, -v124, v47, v152
	v_fma_f32 v153, -v125, v48, v153
	v_fma_f32 v154, -v126, v49, v154
	v_fma_f32 v155, -v127, v50, v155
	ds_read_b128 v[124:127], v28 offset:31792
	s_waitcnt lgkmcnt(11)
	v_fma_f32 v152, -v128, v51, v152
	v_fma_f32 v153, -v129, v52, v153
	v_fma_f32 v154, -v130, v53, v154
	v_fma_f32 v155, -v131, v54, v155
	ds_read_b128 v[128:131], v28 offset:31808
	s_waitcnt lgkmcnt(11)
	v_fma_f32 v152, -v132, v55, v152
	v_fma_f32 v153, -v133, v56, v153
	v_fma_f32 v154, -v134, v57, v154
	v_fma_f32 v155, -v135, v58, v155
	ds_read_b128 v[132:135], v28 offset:31824
	s_waitcnt lgkmcnt(11)
	v_fma_f32 v152, -v136, v59, v152
	v_fma_f32 v153, -v137, v60, v153
	v_fma_f32 v154, -v138, v61, v154
	v_fma_f32 v155, -v139, v62, v155
	ds_read_b128 v[136:139], v28 offset:31840
	s_waitcnt lgkmcnt(11)
	v_fma_f32 v152, -v140, v63, v152
	v_fma_f32 v153, -v141, v64, v153
	v_fma_f32 v154, -v142, v65, v154
	v_fma_f32 v155, -v143, v66, v155
	ds_read_b128 v[140:143], v28 offset:31856
	s_waitcnt lgkmcnt(11)
	v_fma_f32 v152, -v144, v67, v152
	v_fma_f32 v153, -v145, v68, v153
	v_fma_f32 v154, -v146, v69, v154
	v_fma_f32 v155, -v147, v70, v155
	ds_read_b128 v[144:147], v28 offset:31872
	s_waitcnt lgkmcnt(11)
	v_fma_f32 v152, -v100, v71, v152
	v_fma_f32 v153, -v101, v72, v153
	v_fma_f32 v154, -v102, v73, v154
	v_fma_f32 v155, -v103, v74, v155
	ds_read_b128 v[100:103], v28 offset:31888
	s_waitcnt lgkmcnt(11)
	v_fma_f32 v152, -v104, v75, v152
	v_fma_f32 v153, -v105, v76, v153
	v_fma_f32 v154, -v106, v77, v154
	v_fma_f32 v155, -v107, v78, v155
	ds_read_b128 v[104:107], v28 offset:31904
	s_waitcnt lgkmcnt(11)
	v_fma_f32 v152, -v108, v79, v152
	v_fma_f32 v153, -v109, v80, v153
	v_fma_f32 v154, -v110, v81, v154
	ds_read_b128 v[108:111], v28 offset:31920
	v_add_f32_e32 v152, v152, v153
	v_add_f32_e32 v154, v154, v155
	v_add_f32_e32 v82, v152, v154
	v_cvt_pk_bf16_f32 v160, v82, v82
	global_store_short v[8:9], v160, off offset:2432
	v_cmp_eq_u32_e64 s[56:57], 52, v156
	s_waitcnt lgkmcnt(11)
	s_nop 0
	v_cndmask_b32_e64 v148, 0, 1.0, s[56:57]
	v_fma_f32 v148, -v31, v112, v148
	v_fma_f32 v149, -v113, v32, 0
	v_fma_f32 v150, -v114, v33, 0
	v_fma_f32 v151, -v115, v34, 0
	ds_read_b128 v[112:115], v28 offset:31936
	s_waitcnt lgkmcnt(11)
	v_fma_f32 v148, -v116, v35, v148
	v_fma_f32 v149, -v117, v36, v149
	v_fma_f32 v150, -v118, v37, v150
	v_fma_f32 v151, -v119, v38, v151
	ds_read_b128 v[116:119], v28 offset:32000
	s_waitcnt lgkmcnt(11)
	v_fma_f32 v148, -v120, v39, v148
	v_fma_f32 v149, -v121, v40, v149
	v_fma_f32 v150, -v122, v41, v150
	v_fma_f32 v151, -v123, v42, v151
	ds_read_b128 v[120:123], v28 offset:32016
	s_waitcnt lgkmcnt(11)
	v_fma_f32 v148, -v124, v43, v148
	v_fma_f32 v149, -v125, v44, v149
	v_fma_f32 v150, -v126, v45, v150
	v_fma_f32 v151, -v127, v46, v151
	ds_read_b128 v[124:127], v28 offset:32032
	s_waitcnt lgkmcnt(11)
	v_fma_f32 v148, -v128, v47, v148
	v_fma_f32 v149, -v129, v48, v149
	v_fma_f32 v150, -v130, v49, v150
	v_fma_f32 v151, -v131, v50, v151
	ds_read_b128 v[128:131], v28 offset:32048
	s_waitcnt lgkmcnt(11)
	v_fma_f32 v148, -v132, v51, v148
	v_fma_f32 v149, -v133, v52, v149
	v_fma_f32 v150, -v134, v53, v150
	v_fma_f32 v151, -v135, v54, v151
	ds_read_b128 v[132:135], v28 offset:32064
	s_waitcnt lgkmcnt(11)
	v_fma_f32 v148, -v136, v55, v148
	v_fma_f32 v149, -v137, v56, v149
	v_fma_f32 v150, -v138, v57, v150
	v_fma_f32 v151, -v139, v58, v151
	ds_read_b128 v[136:139], v28 offset:32080
	s_waitcnt lgkmcnt(11)
	v_fma_f32 v148, -v140, v59, v148
	v_fma_f32 v149, -v141, v60, v149
	v_fma_f32 v150, -v142, v61, v150
	v_fma_f32 v151, -v143, v62, v151
	ds_read_b128 v[140:143], v28 offset:32096
	s_waitcnt lgkmcnt(11)
	v_fma_f32 v148, -v144, v63, v148
	v_fma_f32 v149, -v145, v64, v149
	v_fma_f32 v150, -v146, v65, v150
	v_fma_f32 v151, -v147, v66, v151
	ds_read_b128 v[144:147], v28 offset:32112
	s_waitcnt lgkmcnt(11)
	v_fma_f32 v148, -v100, v67, v148
	v_fma_f32 v149, -v101, v68, v149
	v_fma_f32 v150, -v102, v69, v150
	v_fma_f32 v151, -v103, v70, v151
	ds_read_b128 v[100:103], v28 offset:32128
	s_waitcnt lgkmcnt(11)
	v_fma_f32 v148, -v104, v71, v148
	v_fma_f32 v149, -v105, v72, v149
	v_fma_f32 v150, -v106, v73, v150
	v_fma_f32 v151, -v107, v74, v151
	ds_read_b128 v[104:107], v28 offset:32144
	s_waitcnt lgkmcnt(11)
	v_fma_f32 v148, -v108, v75, v148
	v_fma_f32 v149, -v109, v76, v149
	v_fma_f32 v150, -v110, v77, v150
	v_fma_f32 v151, -v111, v78, v151
	ds_read_b128 v[108:111], v28 offset:32160
	s_waitcnt lgkmcnt(11)
	v_fma_f32 v148, -v112, v79, v148
	v_fma_f32 v149, -v113, v80, v149
	v_fma_f32 v150, -v114, v81, v150
	v_fma_f32 v151, -v115, v82, v151
	ds_read_b128 v[112:115], v28 offset:32176
	v_add_f32_e32 v148, v148, v149
	v_add_f32_e32 v150, v150, v151
	v_add_f32_e32 v83, v148, v150
	v_cvt_pk_bf16_f32 v157, v83, v83
	global_store_short v[8:9], v157, off offset:2560
	v_cmp_eq_u32_e64 s[56:57], 53, v156
	s_waitcnt lgkmcnt(11)
	s_nop 0
	v_cndmask_b32_e64 v152, 0, 1.0, s[56:57]
	v_fma_f32 v152, -v31, v116, v152
	v_fma_f32 v153, -v117, v32, 0
	v_fma_f32 v154, -v118, v33, 0
	v_fma_f32 v155, -v119, v34, 0
	ds_read_b128 v[116:119], v28 offset:32192
	s_waitcnt lgkmcnt(11)
; #define LAS __attribute__((address_space(3)))
; __device__ __forceinline__ bf16_t f2bf(float f) { return (bf16_t)(pk2(f, f) & 0xFFFFu); }
; __device__ NOINL void g1_phase(const LAS Params* lp, int l, LAS unsigned char* lds) {
;     ...
;             for (int i = 0; i < 64; ++i) {
;                 float s0 = (i == lane) ? 1.f : 0.f, s1 = 0.f, s2 = 0.f, s3 = 0.f;
; #pragma unroll
;                 for (int j4 = 0; j4 < (i + 3) / 4; ++j4) {
;                     const f32x4 lv = *(const LAS f32x4*)(Ld + i * 64 + j4 * 4);
;                     if (j4 * 4 + 0 < i) s0 -= lv[0] * xv[j4 * 4 + 0];
;                     if (j4 * 4 + 1 < i) s1 -= lv[1] * xv[j4 * 4 + 1];
;                     if (j4 * 4 + 2 < i) s2 -= lv[2] * xv[j4 * 4 + 2];
;                     if (j4 * 4 + 3 < i) s3 -= lv[3] * xv[j4 * 4 + 3];
;                 }
;                 xv[i] = (s0 + s1) + (s2 + s3);
;             }
;             bf16_t* Tg = p.Tbuf + ((((size_t)b * 4 + h) * 36 + c3 * 3 + s) * 2 + dir) * 4096;
; #pragma unroll
;             for (int i = 0; i < 64; ++i) Tg[i * 64 + lane] = f2bf(xv[i]);
	v_fma_f32 v152, -v120, v35, v152
	v_fma_f32 v153, -v121, v36, v153
	v_fma_f32 v154, -v122, v37, v154
	v_fma_f32 v155, -v123, v38, v155
	ds_read_b128 v[120:123], v28 offset:32208
	s_waitcnt lgkmcnt(11)
	v_fma_f32 v152, -v124, v39, v152
	v_fma_f32 v153, -v125, v40, v153
	v_fma_f32 v154, -v126, v41, v154
	v_fma_f32 v155, -v127, v42, v155
	ds_read_b128 v[124:127], v28 offset:32256
	s_waitcnt lgkmcnt(11)
	v_fma_f32 v152, -v128, v43, v152
	v_fma_f32 v153, -v129, v44, v153
	v_fma_f32 v154, -v130, v45, v154
	v_fma_f32 v155, -v131, v46, v155
	ds_read_b128 v[128:131], v28 offset:32272
	s_waitcnt lgkmcnt(11)
	v_fma_f32 v152, -v132, v47, v152
	v_fma_f32 v153, -v133, v48, v153
	v_fma_f32 v154, -v134, v49, v154
	v_fma_f32 v155, -v135, v50, v155
	ds_read_b128 v[132:135], v28 offset:32288
	s_waitcnt lgkmcnt(11)
	v_fma_f32 v152, -v136, v51, v152
	v_fma_f32 v153, -v137, v52, v153
	v_fma_f32 v154, -v138, v53, v154
	v_fma_f32 v155, -v139, v54, v155
	ds_read_b128 v[136:139], v28 offset:32304
	s_waitcnt lgkmcnt(11)
	v_fma_f32 v152, -v140, v55, v152
	v_fma_f32 v153, -v141, v56, v153
	v_fma_f32 v154, -v142, v57, v154
	v_fma_f32 v155, -v143, v58, v155
	ds_read_b128 v[140:143], v28 offset:32320
	s_waitcnt lgkmcnt(11)
	v_fma_f32 v152, -v144, v59, v152
	v_fma_f32 v153, -v145, v60, v153
	v_fma_f32 v154, -v146, v61, v154
	v_fma_f32 v155, -v147, v62, v155
	ds_read_b128 v[144:147], v28 offset:32336
	s_waitcnt lgkmcnt(11)
	v_fma_f32 v152, -v100, v63, v152
	v_fma_f32 v153, -v101, v64, v153
	v_fma_f32 v154, -v102, v65, v154
	v_fma_f32 v155, -v103, v66, v155
	ds_read_b128 v[100:103], v28 offset:32352
	s_waitcnt lgkmcnt(11)
	v_fma_f32 v152, -v104, v67, v152
	v_fma_f32 v153, -v105, v68, v153
	v_fma_f32 v154, -v106, v69, v154
	v_fma_f32 v155, -v107, v70, v155
	ds_read_b128 v[104:107], v28 offset:32368
	s_waitcnt lgkmcnt(11)
	v_fma_f32 v152, -v108, v71, v152
	v_fma_f32 v153, -v109, v72, v153
	v_fma_f32 v154, -v110, v73, v154
	v_fma_f32 v155, -v111, v74, v155
	ds_read_b128 v[108:111], v28 offset:32384
	s_waitcnt lgkmcnt(11)
	v_fma_f32 v152, -v112, v75, v152
	v_fma_f32 v153, -v113, v76, v153
	v_fma_f32 v154, -v114, v77, v154
	v_fma_f32 v155, -v115, v78, v155
	ds_read_b128 v[112:115], v28 offset:32400
	s_waitcnt lgkmcnt(11)
	v_fma_f32 v152, -v116, v79, v152
	v_fma_f32 v153, -v117, v80, v153
	v_fma_f32 v154, -v118, v81, v154
	v_fma_f32 v155, -v119, v82, v155
	ds_read_b128 v[116:119], v28 offset:32416
	s_waitcnt lgkmcnt(11)
	v_fma_f32 v152, -v120, v83, v152
	ds_read_b128 v[120:123], v28 offset:32432
	v_add_f32_e32 v152, v152, v153
	v_add_f32_e32 v154, v154, v155
	v_add_f32_e32 v84, v152, v154
	v_cvt_pk_bf16_f32 v158, v84, v84
	global_store_short v[8:9], v158, off offset:2688
	v_cmp_eq_u32_e64 s[56:57], 54, v156
	s_waitcnt lgkmcnt(11)
	s_nop 0
	v_cndmask_b32_e64 v148, 0, 1.0, s[56:57]
	v_fma_f32 v148, -v31, v124, v148
	v_fma_f32 v149, -v125, v32, 0
	v_fma_f32 v150, -v126, v33, 0
	v_fma_f32 v151, -v127, v34, 0
	ds_read_b128 v[124:127], v28 offset:32448
	s_waitcnt lgkmcnt(11)
	v_fma_f32 v148, -v128, v35, v148
	v_fma_f32 v149, -v129, v36, v149
	v_fma_f32 v150, -v130, v37, v150
	v_fma_f32 v151, -v131, v38, v151
	ds_read_b128 v[128:131], v28 offset:32464
	s_waitcnt lgkmcnt(11)
	v_fma_f32 v148, -v132, v39, v148
	v_fma_f32 v149, -v133, v40, v149
	v_fma_f32 v150, -v134, v41, v150
	v_fma_f32 v151, -v135, v42, v151
	ds_read_b128 v[132:135], v28 offset:32512
	s_waitcnt lgkmcnt(11)
	v_fma_f32 v148, -v136, v43, v148
	v_fma_f32 v149, -v137, v44, v149
	v_fma_f32 v150, -v138, v45, v150
	v_fma_f32 v151, -v139, v46, v151
	ds_read_b128 v[136:139], v28 offset:32528
	s_waitcnt lgkmcnt(11)
	v_fma_f32 v148, -v140, v47, v148
	v_fma_f32 v149, -v141, v48, v149
	v_fma_f32 v150, -v142, v49, v150
	v_fma_f32 v151, -v143, v50, v151
	ds_read_b128 v[140:143], v28 offset:32544
	s_waitcnt lgkmcnt(11)
	v_fma_f32 v148, -v144, v51, v148
	v_fma_f32 v149, -v145, v52, v149
	v_fma_f32 v150, -v146, v53, v150
	v_fma_f32 v151, -v147, v54, v151
	ds_read_b128 v[144:147], v28 offset:32560
	s_waitcnt lgkmcnt(11)
	v_fma_f32 v148, -v100, v55, v148
	v_fma_f32 v149, -v101, v56, v149
	v_fma_f32 v150, -v102, v57, v150
	v_fma_f32 v151, -v103, v58, v151
	ds_read_b128 v[100:103], v28 offset:32576
	s_waitcnt lgkmcnt(11)
	v_fma_f32 v148, -v104, v59, v148
	v_fma_f32 v149, -v105, v60, v149
	v_fma_f32 v150, -v106, v61, v150
	v_fma_f32 v151, -v107, v62, v151
	ds_read_b128 v[104:107], v28 offset:32592
	s_waitcnt lgkmcnt(11)
	v_fma_f32 v148, -v108, v63, v148
	v_fma_f32 v149, -v109, v64, v149
	v_fma_f32 v150, -v110, v65, v150
	v_fma_f32 v151, -v111, v66, v151
	ds_read_b128 v[108:111], v28 offset:32608
	s_waitcnt lgkmcnt(11)
	v_fma_f32 v148, -v112, v67, v148
	v_fma_f32 v149, -v113, v68, v149
	v_fma_f32 v150, -v114, v69, v150
	v_fma_f32 v151, -v115, v70, v151
	ds_read_b128 v[112:115], v28 offset:32624
	s_waitcnt lgkmcnt(11)
	v_fma_f32 v148, -v116, v71, v148
	v_fma_f32 v149, -v117, v72, v149
	v_fma_f32 v150, -v118, v73, v150
	v_fma_f32 v151, -v119, v74, v151
	ds_read_b128 v[116:119], v28 offset:32640
	s_waitcnt lgkmcnt(11)
	v_fma_f32 v148, -v120, v75, v148
	v_fma_f32 v149, -v121, v76, v149
	v_fma_f32 v150, -v122, v77, v150
	v_fma_f32 v151, -v123, v78, v151
	ds_read_b128 v[120:123], v28 offset:32656
	s_waitcnt lgkmcnt(11)
	v_fma_f32 v148, -v124, v79, v148
	v_fma_f32 v149, -v125, v80, v149
	v_fma_f32 v150, -v126, v81, v150
	v_fma_f32 v151, -v127, v82, v151
	ds_read_b128 v[124:127], v28 offset:32672
	s_waitcnt lgkmcnt(11)
	v_fma_f32 v148, -v128, v83, v148
	v_fma_f32 v149, -v129, v84, v149
	ds_read_b128 v[128:131], v28 offset:32688
	v_add_f32_e32 v148, v148, v149
	v_add_f32_e32 v150, v150, v151
	v_add_f32_e32 v85, v148, v150
	v_cvt_pk_bf16_f32 v159, v85, v85
	global_store_short v[8:9], v159, off offset:2816
	v_cmp_eq_u32_e64 s[56:57], 55, v156
	s_waitcnt lgkmcnt(11)
; #define LAS __attribute__((address_space(3)))
; __device__ __forceinline__ bf16_t f2bf(float f) { return (bf16_t)(pk2(f, f) & 0xFFFFu); }
; __device__ NOINL void g1_phase(const LAS Params* lp, int l, LAS unsigned char* lds) {
;     ...
;             for (int i = 0; i < 64; ++i) {
;                 float s0 = (i == lane) ? 1.f : 0.f, s1 = 0.f, s2 = 0.f, s3 = 0.f;
; #pragma unroll
;                 for (int j4 = 0; j4 < (i + 3) / 4; ++j4) {
;                     const f32x4 lv = *(const LAS f32x4*)(Ld + i * 64 + j4 * 4);
;                     if (j4 * 4 + 0 < i) s0 -= lv[0] * xv[j4 * 4 + 0];
;                     if (j4 * 4 + 1 < i) s1 -= lv[1] * xv[j4 * 4 + 1];
;                     if (j4 * 4 + 2 < i) s2 -= lv[2] * xv[j4 * 4 + 2];
;                     if (j4 * 4 + 3 < i) s3 -= lv[3] * xv[j4 * 4 + 3];
;                 }
;                 xv[i] = (s0 + s1) + (s2 + s3);
;             }
;             bf16_t* Tg = p.Tbuf + ((((size_t)b * 4 + h) * 36 + c3 * 3 + s) * 2 + dir) * 4096;
; #pragma unroll
;             for (int i = 0; i < 64; ++i) Tg[i * 64 + lane] = f2bf(xv[i]);
	s_nop 0
	v_cndmask_b32_e64 v152, 0, 1.0, s[56:57]
	v_fma_f32 v152, -v31, v132, v152
	v_fma_f32 v153, -v133, v32, 0
	v_fma_f32 v154, -v134, v33, 0
	v_fma_f32 v155, -v135, v34, 0
	ds_read_b128 v[132:135], v28 offset:32704
	s_waitcnt lgkmcnt(11)
	v_fma_f32 v152, -v136, v35, v152
	v_fma_f32 v153, -v137, v36, v153
	v_fma_f32 v154, -v138, v37, v154
	v_fma_f32 v155, -v139, v38, v155
	ds_read_b128 v[136:139], v28 offset:32720
	s_waitcnt lgkmcnt(11)
	v_fma_f32 v152, -v140, v39, v152
	v_fma_f32 v153, -v141, v40, v153
	v_fma_f32 v154, -v142, v41, v154
	v_fma_f32 v155, -v143, v42, v155
	ds_read_b128 v[140:143], v28 offset:32768
	s_waitcnt lgkmcnt(11)
	v_fma_f32 v152, -v144, v43, v152
	v_fma_f32 v153, -v145, v44, v153
	v_fma_f32 v154, -v146, v45, v154
	v_fma_f32 v155, -v147, v46, v155
	ds_read_b128 v[144:147], v28 offset:32784
	s_waitcnt lgkmcnt(11)
	v_fma_f32 v152, -v100, v47, v152
	v_fma_f32 v153, -v101, v48, v153
	v_fma_f32 v154, -v102, v49, v154
	v_fma_f32 v155, -v103, v50, v155
	ds_read_b128 v[100:103], v28 offset:32800
	s_waitcnt lgkmcnt(11)
	v_fma_f32 v152, -v104, v51, v152
	v_fma_f32 v153, -v105, v52, v153
	v_fma_f32 v154, -v106, v53, v154
	v_fma_f32 v155, -v107, v54, v155
	ds_read_b128 v[104:107], v28 offset:32816
	s_waitcnt lgkmcnt(11)
	v_fma_f32 v152, -v108, v55, v152
	v_fma_f32 v153, -v109, v56, v153
	v_fma_f32 v154, -v110, v57, v154
	v_fma_f32 v155, -v111, v58, v155
	ds_read_b128 v[108:111], v28 offset:32832
	s_waitcnt lgkmcnt(11)
	v_fma_f32 v152, -v112, v59, v152
	v_fma_f32 v153, -v113, v60, v153
	v_fma_f32 v154, -v114, v61, v154
	v_fma_f32 v155, -v115, v62, v155
	ds_read_b128 v[112:115], v28 offset:32848
	s_waitcnt lgkmcnt(11)
	v_fma_f32 v152, -v116, v63, v152
	v_fma_f32 v153, -v117, v64, v153
	v_fma_f32 v154, -v118, v65, v154
	v_fma_f32 v155, -v119, v66, v155
	ds_read_b128 v[116:119], v28 offset:32864
	s_waitcnt lgkmcnt(11)
	v_fma_f32 v152, -v120, v67, v152
	v_fma_f32 v153, -v121, v68, v153
	v_fma_f32 v154, -v122, v69, v154
	v_fma_f32 v155, -v123, v70, v155
	ds_read_b128 v[120:123], v28 offset:32880
	s_waitcnt lgkmcnt(11)
	v_fma_f32 v152, -v124, v71, v152
	v_fma_f32 v153, -v125, v72, v153
	v_fma_f32 v154, -v126, v73, v154
	v_fma_f32 v155, -v127, v74, v155
	ds_read_b128 v[124:127], v28 offset:32896
	s_waitcnt lgkmcnt(11)
	v_fma_f32 v152, -v128, v75, v152
	v_fma_f32 v153, -v129, v76, v153
	v_fma_f32 v154, -v130, v77, v154
	v_fma_f32 v155, -v131, v78, v155
	ds_read_b128 v[128:131], v28 offset:32912
	s_waitcnt lgkmcnt(11)
	v_fma_f32 v152, -v132, v79, v152
	v_fma_f32 v153, -v133, v80, v153
	v_fma_f32 v154, -v134, v81, v154
	v_fma_f32 v155, -v135, v82, v155
	ds_read_b128 v[132:135], v28 offset:32928
	s_waitcnt lgkmcnt(11)
	v_fma_f32 v152, -v136, v83, v152
	v_fma_f32 v153, -v137, v84, v153
	v_fma_f32 v154, -v138, v85, v154
	ds_read_b128 v[136:139], v28 offset:32944
	v_add_f32_e32 v152, v152, v153
	v_add_f32_e32 v154, v154, v155
	v_add_f32_e32 v86, v152, v154
	v_cvt_pk_bf16_f32 v160, v86, v86
	global_store_short v[8:9], v160, off offset:2944
	v_cmp_eq_u32_e64 s[56:57], 56, v156
	s_waitcnt lgkmcnt(11)
	s_nop 0
	v_cndmask_b32_e64 v148, 0, 1.0, s[56:57]
	v_fma_f32 v148, -v31, v140, v148
	v_fma_f32 v149, -v141, v32, 0
	v_fma_f32 v150, -v142, v33, 0
	v_fma_f32 v151, -v143, v34, 0
	ds_read_b128 v[140:143], v28 offset:32960
	s_waitcnt lgkmcnt(11)
	v_fma_f32 v148, -v144, v35, v148
	v_fma_f32 v149, -v145, v36, v149
	v_fma_f32 v150, -v146, v37, v150
	v_fma_f32 v151, -v147, v38, v151
	ds_read_b128 v[144:147], v28 offset:32976
	s_waitcnt lgkmcnt(11)
	v_fma_f32 v148, -v100, v39, v148
	v_fma_f32 v149, -v101, v40, v149
	v_fma_f32 v150, -v102, v41, v150
	v_fma_f32 v151, -v103, v42, v151
	ds_read_b128 v[100:103], v28 offset:33024
	s_waitcnt lgkmcnt(11)
	v_fma_f32 v148, -v104, v43, v148
	v_fma_f32 v149, -v105, v44, v149
	v_fma_f32 v150, -v106, v45, v150
	v_fma_f32 v151, -v107, v46, v151
	ds_read_b128 v[104:107], v28 offset:33040
	s_waitcnt lgkmcnt(11)
	v_fma_f32 v148, -v108, v47, v148
	v_fma_f32 v149, -v109, v48, v149
	v_fma_f32 v150, -v110, v49, v150
	v_fma_f32 v151, -v111, v50, v151
	ds_read_b128 v[108:111], v28 offset:33056
	s_waitcnt lgkmcnt(11)
	v_fma_f32 v148, -v112, v51, v148
	v_fma_f32 v149, -v113, v52, v149
	v_fma_f32 v150, -v114, v53, v150
	v_fma_f32 v151, -v115, v54, v151
	ds_read_b128 v[112:115], v28 offset:33072
	s_waitcnt lgkmcnt(11)
	v_fma_f32 v148, -v116, v55, v148
	v_fma_f32 v149, -v117, v56, v149
	v_fma_f32 v150, -v118, v57, v150
	v_fma_f32 v151, -v119, v58, v151
	ds_read_b128 v[116:119], v28 offset:33088
	s_waitcnt lgkmcnt(11)
	v_fma_f32 v148, -v120, v59, v148
	v_fma_f32 v149, -v121, v60, v149
	v_fma_f32 v150, -v122, v61, v150
	v_fma_f32 v151, -v123, v62, v151
	ds_read_b128 v[120:123], v28 offset:33104
	s_waitcnt lgkmcnt(11)
	v_fma_f32 v148, -v124, v63, v148
	v_fma_f32 v149, -v125, v64, v149
	v_fma_f32 v150, -v126, v65, v150
	v_fma_f32 v151, -v127, v66, v151
	ds_read_b128 v[124:127], v28 offset:33120
	s_waitcnt lgkmcnt(11)
	v_fma_f32 v148, -v128, v67, v148
	v_fma_f32 v149, -v129, v68, v149
	v_fma_f32 v150, -v130, v69, v150
	v_fma_f32 v151, -v131, v70, v151
	ds_read_b128 v[128:131], v28 offset:33136
	s_waitcnt lgkmcnt(11)
	v_fma_f32 v148, -v132, v71, v148
	v_fma_f32 v149, -v133, v72, v149
	v_fma_f32 v150, -v134, v73, v150
	v_fma_f32 v151, -v135, v74, v151
	ds_read_b128 v[132:135], v28 offset:33152
	s_waitcnt lgkmcnt(11)
	v_fma_f32 v148, -v136, v75, v148
	v_fma_f32 v149, -v137, v76, v149
	v_fma_f32 v150, -v138, v77, v150
	v_fma_f32 v151, -v139, v78, v151
	ds_read_b128 v[136:139], v28 offset:33168
	s_waitcnt lgkmcnt(11)
	v_fma_f32 v148, -v140, v79, v148
	v_fma_f32 v149, -v141, v80, v149
	v_fma_f32 v150, -v142, v81, v150
	v_fma_f32 v151, -v143, v82, v151
	ds_read_b128 v[140:143], v28 offset:33184
	s_waitcnt lgkmcnt(11)
; #define LAS __attribute__((address_space(3)))
; __device__ __forceinline__ bf16_t f2bf(float f) { return (bf16_t)(pk2(f, f) & 0xFFFFu); }
; __device__ NOINL void g1_phase(const LAS Params* lp, int l, LAS unsigned char* lds) {
;     ...
;             for (int i = 0; i < 64; ++i) {
;                 float s0 = (i == lane) ? 1.f : 0.f, s1 = 0.f, s2 = 0.f, s3 = 0.f;
; #pragma unroll
;                 for (int j4 = 0; j4 < (i + 3) / 4; ++j4) {
;                     const f32x4 lv = *(const LAS f32x4*)(Ld + i * 64 + j4 * 4);
;                     if (j4 * 4 + 0 < i) s0 -= lv[0] * xv[j4 * 4 + 0];
;                     if (j4 * 4 + 1 < i) s1 -= lv[1] * xv[j4 * 4 + 1];
;                     if (j4 * 4 + 2 < i) s2 -= lv[2] * xv[j4 * 4 + 2];
;                     if (j4 * 4 + 3 < i) s3 -= lv[3] * xv[j4 * 4 + 3];
;                 }
;                 xv[i] = (s0 + s1) + (s2 + s3);
;             }
;             bf16_t* Tg = p.Tbuf + ((((size_t)b * 4 + h) * 36 + c3 * 3 + s) * 2 + dir) * 4096;
; #pragma unroll
;             for (int i = 0; i < 64; ++i) Tg[i * 64 + lane] = f2bf(xv[i]);
	v_fma_f32 v148, -v144, v83, v148
	v_fma_f32 v149, -v145, v84, v149
	v_fma_f32 v150, -v146, v85, v150
	v_fma_f32 v151, -v147, v86, v151
	ds_read_b128 v[144:147], v28 offset:33200
	v_add_f32_e32 v148, v148, v149
	v_add_f32_e32 v150, v150, v151
	v_add_f32_e32 v87, v148, v150
	v_cvt_pk_bf16_f32 v157, v87, v87
	global_store_short v[8:9], v157, off offset:3072
	v_cmp_eq_u32_e64 s[56:57], 57, v156
	s_waitcnt lgkmcnt(11)
	s_nop 0
	v_cndmask_b32_e64 v152, 0, 1.0, s[56:57]
	v_fma_f32 v152, -v31, v100, v152
	v_fma_f32 v153, -v101, v32, 0
	v_fma_f32 v154, -v102, v33, 0
	v_fma_f32 v155, -v103, v34, 0
	ds_read_b128 v[100:103], v28 offset:33216
	s_waitcnt lgkmcnt(11)
	v_fma_f32 v152, -v104, v35, v152
	v_fma_f32 v153, -v105, v36, v153
	v_fma_f32 v154, -v106, v37, v154
	v_fma_f32 v155, -v107, v38, v155
	ds_read_b128 v[104:107], v28 offset:33232
	s_waitcnt lgkmcnt(11)
	v_fma_f32 v152, -v108, v39, v152
	v_fma_f32 v153, -v109, v40, v153
	v_fma_f32 v154, -v110, v41, v154
	v_fma_f32 v155, -v111, v42, v155
	ds_read_b128 v[108:111], v28 offset:33248
	s_waitcnt lgkmcnt(11)
	v_fma_f32 v152, -v112, v43, v152
	v_fma_f32 v153, -v113, v44, v153
	v_fma_f32 v154, -v114, v45, v154
	v_fma_f32 v155, -v115, v46, v155
	ds_read_b128 v[112:115], v28 offset:33280
	s_waitcnt lgkmcnt(11)
	v_fma_f32 v152, -v116, v47, v152
	v_fma_f32 v153, -v117, v48, v153
	v_fma_f32 v154, -v118, v49, v154
	v_fma_f32 v155, -v119, v50, v155
	ds_read_b128 v[116:119], v28 offset:33296
	s_waitcnt lgkmcnt(11)
	v_fma_f32 v152, -v120, v51, v152
	v_fma_f32 v153, -v121, v52, v153
	v_fma_f32 v154, -v122, v53, v154
	v_fma_f32 v155, -v123, v54, v155
	ds_read_b128 v[120:123], v28 offset:33312
	s_waitcnt lgkmcnt(11)
	v_fma_f32 v152, -v124, v55, v152
	v_fma_f32 v153, -v125, v56, v153
	v_fma_f32 v154, -v126, v57, v154
	v_fma_f32 v155, -v127, v58, v155
	ds_read_b128 v[124:127], v28 offset:33328
	s_waitcnt lgkmcnt(11)
	v_fma_f32 v152, -v128, v59, v152
	v_fma_f32 v153, -v129, v60, v153
	v_fma_f32 v154, -v130, v61, v154
	v_fma_f32 v155, -v131, v62, v155
	ds_read_b128 v[128:131], v28 offset:33344
	s_waitcnt lgkmcnt(11)
	v_fma_f32 v152, -v132, v63, v152
	v_fma_f32 v153, -v133, v64, v153
	v_fma_f32 v154, -v134, v65, v154
	v_fma_f32 v155, -v135, v66, v155
	ds_read_b128 v[132:135], v28 offset:33360
	s_waitcnt lgkmcnt(11)
	v_fma_f32 v152, -v136, v67, v152
	v_fma_f32 v153, -v137, v68, v153
	v_fma_f32 v154, -v138, v69, v154
	v_fma_f32 v155, -v139, v70, v155
	ds_read_b128 v[136:139], v28 offset:33376
	s_waitcnt lgkmcnt(11)
	v_fma_f32 v152, -v140, v71, v152
	v_fma_f32 v153, -v141, v72, v153
	v_fma_f32 v154, -v142, v73, v154
	v_fma_f32 v155, -v143, v74, v155
	ds_read_b128 v[140:143], v28 offset:33392
	s_waitcnt lgkmcnt(11)
	v_fma_f32 v152, -v144, v75, v152
	v_fma_f32 v153, -v145, v76, v153
	v_fma_f32 v154, -v146, v77, v154
	v_fma_f32 v155, -v147, v78, v155
	ds_read_b128 v[144:147], v28 offset:33408
	s_waitcnt lgkmcnt(11)
	v_fma_f32 v152, -v100, v79, v152
	v_fma_f32 v153, -v101, v80, v153
	v_fma_f32 v154, -v102, v81, v154
	v_fma_f32 v155, -v103, v82, v155
	ds_read_b128 v[100:103], v28 offset:33424
	s_waitcnt lgkmcnt(11)
	v_fma_f32 v152, -v104, v83, v152
	v_fma_f32 v153, -v105, v84, v153
	v_fma_f32 v154, -v106, v85, v154
	v_fma_f32 v155, -v107, v86, v155
	ds_read_b128 v[104:107], v28 offset:33440
	s_waitcnt lgkmcnt(11)
	v_fma_f32 v152, -v108, v87, v152
	ds_read_b128 v[108:111], v28 offset:33456
	v_add_f32_e32 v152, v152, v153
	v_add_f32_e32 v154, v154, v155
	v_add_f32_e32 v88, v152, v154
	v_cvt_pk_bf16_f32 v158, v88, v88
	global_store_short v[8:9], v158, off offset:3200
	v_cmp_eq_u32_e64 s[56:57], 58, v156
	s_waitcnt lgkmcnt(11)
	s_nop 0
	v_cndmask_b32_e64 v148, 0, 1.0, s[56:57]
	v_fma_f32 v148, -v31, v112, v148
	v_fma_f32 v149, -v113, v32, 0
	v_fma_f32 v150, -v114, v33, 0
	v_fma_f32 v151, -v115, v34, 0
	ds_read_b128 v[112:115], v28 offset:33472
	s_waitcnt lgkmcnt(11)
	v_fma_f32 v148, -v116, v35, v148
	v_fma_f32 v149, -v117, v36, v149
	v_fma_f32 v150, -v118, v37, v150
	v_fma_f32 v151, -v119, v38, v151
	ds_read_b128 v[116:119], v28 offset:33488
	s_waitcnt lgkmcnt(11)
	v_fma_f32 v148, -v120, v39, v148
	v_fma_f32 v149, -v121, v40, v149
	v_fma_f32 v150, -v122, v41, v150
	v_fma_f32 v151, -v123, v42, v151
	ds_read_b128 v[120:123], v28 offset:33504
	s_waitcnt lgkmcnt(11)
	v_fma_f32 v148, -v124, v43, v148
	v_fma_f32 v149, -v125, v44, v149
	v_fma_f32 v150, -v126, v45, v150
	v_fma_f32 v151, -v127, v46, v151
	ds_read_b128 v[124:127], v28 offset:33536
	s_waitcnt lgkmcnt(11)
	v_fma_f32 v148, -v128, v47, v148
	v_fma_f32 v149, -v129, v48, v149
	v_fma_f32 v150, -v130, v49, v150
	v_fma_f32 v151, -v131, v50, v151
	ds_read_b128 v[128:131], v28 offset:33552
	s_waitcnt lgkmcnt(11)
	v_fma_f32 v148, -v132, v51, v148
	v_fma_f32 v149, -v133, v52, v149
	v_fma_f32 v150, -v134, v53, v150
	v_fma_f32 v151, -v135, v54, v151
	ds_read_b128 v[132:135], v28 offset:33568
	s_waitcnt lgkmcnt(11)
	v_fma_f32 v148, -v136, v55, v148
	v_fma_f32 v149, -v137, v56, v149
	v_fma_f32 v150, -v138, v57, v150
	v_fma_f32 v151, -v139, v58, v151
	ds_read_b128 v[136:139], v28 offset:33584
	s_waitcnt lgkmcnt(11)
	v_fma_f32 v148, -v140, v59, v148
	v_fma_f32 v149, -v141, v60, v149
	v_fma_f32 v150, -v142, v61, v150
	v_fma_f32 v151, -v143, v62, v151
	ds_read_b128 v[140:143], v28 offset:33600
	s_waitcnt lgkmcnt(11)
	v_fma_f32 v148, -v144, v63, v148
	v_fma_f32 v149, -v145, v64, v149
	v_fma_f32 v150, -v146, v65, v150
	v_fma_f32 v151, -v147, v66, v151
	ds_read_b128 v[144:147], v28 offset:33616
	s_waitcnt lgkmcnt(11)
	v_fma_f32 v148, -v100, v67, v148
	v_fma_f32 v149, -v101, v68, v149
	v_fma_f32 v150, -v102, v69, v150
	v_fma_f32 v151, -v103, v70, v151
	ds_read_b128 v[100:103], v28 offset:33632
	s_waitcnt lgkmcnt(11)
; #define LAS __attribute__((address_space(3)))
; __device__ __forceinline__ bf16_t f2bf(float f) { return (bf16_t)(pk2(f, f) & 0xFFFFu); }
; __device__ NOINL void g1_phase(const LAS Params* lp, int l, LAS unsigned char* lds) {
;     ...
;             for (int i = 0; i < 64; ++i) {
;                 float s0 = (i == lane) ? 1.f : 0.f, s1 = 0.f, s2 = 0.f, s3 = 0.f;
; #pragma unroll
;                 for (int j4 = 0; j4 < (i + 3) / 4; ++j4) {
;                     const f32x4 lv = *(const LAS f32x4*)(Ld + i * 64 + j4 * 4);
;                     if (j4 * 4 + 0 < i) s0 -= lv[0] * xv[j4 * 4 + 0];
;                     if (j4 * 4 + 1 < i) s1 -= lv[1] * xv[j4 * 4 + 1];
;                     if (j4 * 4 + 2 < i) s2 -= lv[2] * xv[j4 * 4 + 2];
;                     if (j4 * 4 + 3 < i) s3 -= lv[3] * xv[j4 * 4 + 3];
;                 }
;                 xv[i] = (s0 + s1) + (s2 + s3);
;             }
;             bf16_t* Tg = p.Tbuf + ((((size_t)b * 4 + h) * 36 + c3 * 3 + s) * 2 + dir) * 4096;
; #pragma unroll
;             for (int i = 0; i < 64; ++i) Tg[i * 64 + lane] = f2bf(xv[i]);
	v_fma_f32 v148, -v104, v71, v148
	v_fma_f32 v149, -v105, v72, v149
	v_fma_f32 v150, -v106, v73, v150
	v_fma_f32 v151, -v107, v74, v151
	ds_read_b128 v[104:107], v28 offset:33648
	s_waitcnt lgkmcnt(11)
	v_fma_f32 v148, -v108, v75, v148
	v_fma_f32 v149, -v109, v76, v149
	v_fma_f32 v150, -v110, v77, v150
	v_fma_f32 v151, -v111, v78, v151
	ds_read_b128 v[108:111], v28 offset:33664
	s_waitcnt lgkmcnt(11)
	v_fma_f32 v148, -v112, v79, v148
	v_fma_f32 v149, -v113, v80, v149
	v_fma_f32 v150, -v114, v81, v150
	v_fma_f32 v151, -v115, v82, v151
	ds_read_b128 v[112:115], v28 offset:33680
	s_waitcnt lgkmcnt(11)
	v_fma_f32 v148, -v116, v83, v148
	v_fma_f32 v149, -v117, v84, v149
	v_fma_f32 v150, -v118, v85, v150
	v_fma_f32 v151, -v119, v86, v151
	ds_read_b128 v[116:119], v28 offset:33696
	s_waitcnt lgkmcnt(11)
	v_fma_f32 v148, -v120, v87, v148
	v_fma_f32 v149, -v121, v88, v149
	ds_read_b128 v[120:123], v28 offset:33712
	v_add_f32_e32 v148, v148, v149
	v_add_f32_e32 v150, v150, v151
	v_add_f32_e32 v89, v148, v150
	v_cvt_pk_bf16_f32 v159, v89, v89
	global_store_short v[8:9], v159, off offset:3328
	v_cmp_eq_u32_e64 s[56:57], 59, v156
	s_waitcnt lgkmcnt(11)
	s_nop 0
	v_cndmask_b32_e64 v152, 0, 1.0, s[56:57]
	v_fma_f32 v152, -v31, v124, v152
	v_fma_f32 v153, -v125, v32, 0
	v_fma_f32 v154, -v126, v33, 0
	v_fma_f32 v155, -v127, v34, 0
	ds_read_b128 v[124:127], v28 offset:33728
	s_waitcnt lgkmcnt(11)
	v_fma_f32 v152, -v128, v35, v152
	v_fma_f32 v153, -v129, v36, v153
	v_fma_f32 v154, -v130, v37, v154
	v_fma_f32 v155, -v131, v38, v155
	ds_read_b128 v[128:131], v28 offset:33744
	s_waitcnt lgkmcnt(11)
	v_fma_f32 v152, -v132, v39, v152
	v_fma_f32 v153, -v133, v40, v153
	v_fma_f32 v154, -v134, v41, v154
	v_fma_f32 v155, -v135, v42, v155
	ds_read_b128 v[132:135], v28 offset:33760
	s_waitcnt lgkmcnt(11)
	v_fma_f32 v152, -v136, v43, v152
	v_fma_f32 v153, -v137, v44, v153
	v_fma_f32 v154, -v138, v45, v154
	v_fma_f32 v155, -v139, v46, v155
	ds_read_b128 v[136:139], v28 offset:33792
	s_waitcnt lgkmcnt(11)
	v_fma_f32 v152, -v140, v47, v152
	v_fma_f32 v153, -v141, v48, v153
	v_fma_f32 v154, -v142, v49, v154
	v_fma_f32 v155, -v143, v50, v155
	ds_read_b128 v[140:143], v28 offset:33808
	s_waitcnt lgkmcnt(11)
	v_fma_f32 v152, -v144, v51, v152
	v_fma_f32 v153, -v145, v52, v153
	v_fma_f32 v154, -v146, v53, v154
	v_fma_f32 v155, -v147, v54, v155
	ds_read_b128 v[144:147], v28 offset:33824
	s_waitcnt lgkmcnt(11)
	v_fma_f32 v152, -v100, v55, v152
	v_fma_f32 v153, -v101, v56, v153
	v_fma_f32 v154, -v102, v57, v154
	v_fma_f32 v155, -v103, v58, v155
	ds_read_b128 v[100:103], v28 offset:33840
	s_waitcnt lgkmcnt(11)
	v_fma_f32 v152, -v104, v59, v152
	v_fma_f32 v153, -v105, v60, v153
	v_fma_f32 v154, -v106, v61, v154
	v_fma_f32 v155, -v107, v62, v155
	ds_read_b128 v[104:107], v28 offset:33856
	s_waitcnt lgkmcnt(11)
	v_fma_f32 v152, -v108, v63, v152
	v_fma_f32 v153, -v109, v64, v153
	v_fma_f32 v154, -v110, v65, v154
	v_fma_f32 v155, -v111, v66, v155
	ds_read_b128 v[108:111], v28 offset:33872
	s_waitcnt lgkmcnt(11)
	v_fma_f32 v152, -v112, v67, v152
	v_fma_f32 v153, -v113, v68, v153
	v_fma_f32 v154, -v114, v69, v154
	v_fma_f32 v155, -v115, v70, v155
	ds_read_b128 v[112:115], v28 offset:33888
	s_waitcnt lgkmcnt(11)
	v_fma_f32 v152, -v116, v71, v152
	v_fma_f32 v153, -v117, v72, v153
	v_fma_f32 v154, -v118, v73, v154
	v_fma_f32 v155, -v119, v74, v155
	ds_read_b128 v[116:119], v28 offset:33904
	s_waitcnt lgkmcnt(11)
	v_fma_f32 v152, -v120, v75, v152
	v_fma_f32 v153, -v121, v76, v153
	v_fma_f32 v154, -v122, v77, v154
	v_fma_f32 v155, -v123, v78, v155
	ds_read_b128 v[120:123], v28 offset:33920
	s_waitcnt lgkmcnt(11)
	v_fma_f32 v152, -v124, v79, v152
	v_fma_f32 v153, -v125, v80, v153
	v_fma_f32 v154, -v126, v81, v154
	v_fma_f32 v155, -v127, v82, v155
	ds_read_b128 v[124:127], v28 offset:33936
	s_waitcnt lgkmcnt(11)
	v_fma_f32 v152, -v128, v83, v152
	v_fma_f32 v153, -v129, v84, v153
	v_fma_f32 v154, -v130, v85, v154
	v_fma_f32 v155, -v131, v86, v155
	ds_read_b128 v[128:131], v28 offset:33952
	s_waitcnt lgkmcnt(11)
	v_fma_f32 v152, -v132, v87, v152
	v_fma_f32 v153, -v133, v88, v153
	v_fma_f32 v154, -v134, v89, v154
	ds_read_b128 v[132:135], v28 offset:33968
	v_add_f32_e32 v152, v152, v153
	v_add_f32_e32 v154, v154, v155
	v_add_f32_e32 v90, v152, v154
	v_cvt_pk_bf16_f32 v160, v90, v90
	global_store_short v[8:9], v160, off offset:3456
	v_cmp_eq_u32_e64 s[56:57], 60, v156
	s_waitcnt lgkmcnt(11)
	s_nop 0
	v_cndmask_b32_e64 v148, 0, 1.0, s[56:57]
	v_fma_f32 v148, -v31, v136, v148
	v_fma_f32 v149, -v137, v32, 0
	v_fma_f32 v150, -v138, v33, 0
	v_fma_f32 v151, -v139, v34, 0
	ds_read_b128 v[136:139], v28 offset:33984
	s_waitcnt lgkmcnt(11)
	v_fma_f32 v148, -v140, v35, v148
	v_fma_f32 v149, -v141, v36, v149
	v_fma_f32 v150, -v142, v37, v150
	v_fma_f32 v151, -v143, v38, v151
	ds_read_b128 v[140:143], v28 offset:34000
	s_waitcnt lgkmcnt(11)
	v_fma_f32 v148, -v144, v39, v148
	v_fma_f32 v149, -v145, v40, v149
	v_fma_f32 v150, -v146, v41, v150
	v_fma_f32 v151, -v147, v42, v151
	ds_read_b128 v[144:147], v28 offset:34016
	s_waitcnt lgkmcnt(11)
	v_fma_f32 v148, -v100, v43, v148
	v_fma_f32 v149, -v101, v44, v149
	v_fma_f32 v150, -v102, v45, v150
	v_fma_f32 v151, -v103, v46, v151
	ds_read_b128 v[100:103], v28 offset:34048
	s_waitcnt lgkmcnt(11)
	v_fma_f32 v148, -v104, v47, v148
	v_fma_f32 v149, -v105, v48, v149
	v_fma_f32 v150, -v106, v49, v150
	v_fma_f32 v151, -v107, v50, v151
	ds_read_b128 v[104:107], v28 offset:34064
	s_waitcnt lgkmcnt(11)
	v_fma_f32 v148, -v108, v51, v148
	v_fma_f32 v149, -v109, v52, v149
	v_fma_f32 v150, -v110, v53, v150
	v_fma_f32 v151, -v111, v54, v151
	ds_read_b128 v[108:111], v28 offset:34080
	s_waitcnt lgkmcnt(11)
; #define LAS __attribute__((address_space(3)))
; __device__ __forceinline__ bf16_t f2bf(float f) { return (bf16_t)(pk2(f, f) & 0xFFFFu); }
; __device__ NOINL void g1_phase(const LAS Params* lp, int l, LAS unsigned char* lds) {
;     ...
;             for (int i = 0; i < 64; ++i) {
;                 float s0 = (i == lane) ? 1.f : 0.f, s1 = 0.f, s2 = 0.f, s3 = 0.f;
; #pragma unroll
;                 for (int j4 = 0; j4 < (i + 3) / 4; ++j4) {
;                     const f32x4 lv = *(const LAS f32x4*)(Ld + i * 64 + j4 * 4);
;                     if (j4 * 4 + 0 < i) s0 -= lv[0] * xv[j4 * 4 + 0];
;                     if (j4 * 4 + 1 < i) s1 -= lv[1] * xv[j4 * 4 + 1];
;                     if (j4 * 4 + 2 < i) s2 -= lv[2] * xv[j4 * 4 + 2];
;                     if (j4 * 4 + 3 < i) s3 -= lv[3] * xv[j4 * 4 + 3];
;                 }
;                 xv[i] = (s0 + s1) + (s2 + s3);
;             }
;             bf16_t* Tg = p.Tbuf + ((((size_t)b * 4 + h) * 36 + c3 * 3 + s) * 2 + dir) * 4096;
; #pragma unroll
;             for (int i = 0; i < 64; ++i) Tg[i * 64 + lane] = f2bf(xv[i]);
	v_fma_f32 v148, -v112, v55, v148
	v_fma_f32 v149, -v113, v56, v149
	v_fma_f32 v150, -v114, v57, v150
	v_fma_f32 v151, -v115, v58, v151
	ds_read_b128 v[112:115], v28 offset:34096
	s_waitcnt lgkmcnt(11)
	v_fma_f32 v148, -v116, v59, v148
	v_fma_f32 v149, -v117, v60, v149
	v_fma_f32 v150, -v118, v61, v150
	v_fma_f32 v151, -v119, v62, v151
	ds_read_b128 v[116:119], v28 offset:34112
	s_waitcnt lgkmcnt(11)
	v_fma_f32 v148, -v120, v63, v148
	v_fma_f32 v149, -v121, v64, v149
	v_fma_f32 v150, -v122, v65, v150
	v_fma_f32 v151, -v123, v66, v151
	ds_read_b128 v[120:123], v28 offset:34128
	s_waitcnt lgkmcnt(11)
	v_fma_f32 v148, -v124, v67, v148
	v_fma_f32 v149, -v125, v68, v149
	v_fma_f32 v150, -v126, v69, v150
	v_fma_f32 v151, -v127, v70, v151
	ds_read_b128 v[124:127], v28 offset:34144
	s_waitcnt lgkmcnt(11)
	v_fma_f32 v148, -v128, v71, v148
	v_fma_f32 v149, -v129, v72, v149
	v_fma_f32 v150, -v130, v73, v150
	v_fma_f32 v151, -v131, v74, v151
	ds_read_b128 v[128:131], v28 offset:34160
	s_waitcnt lgkmcnt(11)
	v_fma_f32 v148, -v132, v75, v148
	v_fma_f32 v149, -v133, v76, v149
	v_fma_f32 v150, -v134, v77, v150
	v_fma_f32 v151, -v135, v78, v151
	ds_read_b128 v[132:135], v28 offset:34176
	s_waitcnt lgkmcnt(11)
	v_fma_f32 v148, -v136, v79, v148
	v_fma_f32 v149, -v137, v80, v149
	v_fma_f32 v150, -v138, v81, v150
	v_fma_f32 v151, -v139, v82, v151
	ds_read_b128 v[136:139], v28 offset:34192
	s_waitcnt lgkmcnt(11)
	v_fma_f32 v148, -v140, v83, v148
	v_fma_f32 v149, -v141, v84, v149
	v_fma_f32 v150, -v142, v85, v150
	v_fma_f32 v151, -v143, v86, v151
	ds_read_b128 v[140:143], v28 offset:34208
	s_waitcnt lgkmcnt(11)
	v_fma_f32 v148, -v144, v87, v148
	v_fma_f32 v149, -v145, v88, v149
	v_fma_f32 v150, -v146, v89, v150
	v_fma_f32 v151, -v147, v90, v151
	ds_read_b128 v[144:147], v28 offset:34224
	v_add_f32_e32 v148, v148, v149
	v_add_f32_e32 v150, v150, v151
	v_add_f32_e32 v91, v148, v150
	v_cvt_pk_bf16_f32 v157, v91, v91
	global_store_short v[8:9], v157, off offset:3584
	v_cmp_eq_u32_e64 s[56:57], 61, v156
	s_waitcnt lgkmcnt(11)
	s_nop 0
	v_cndmask_b32_e64 v152, 0, 1.0, s[56:57]
	v_fma_f32 v152, -v31, v100, v152
	v_fma_f32 v153, -v101, v32, 0
	v_fma_f32 v154, -v102, v33, 0
	v_fma_f32 v155, -v103, v34, 0
	ds_read_b128 v[100:103], v28 offset:34240
	s_waitcnt lgkmcnt(11)
	v_fma_f32 v152, -v104, v35, v152
	v_fma_f32 v153, -v105, v36, v153
	v_fma_f32 v154, -v106, v37, v154
	v_fma_f32 v155, -v107, v38, v155
	ds_read_b128 v[104:107], v28 offset:34256
	s_waitcnt lgkmcnt(11)
	v_fma_f32 v152, -v108, v39, v152
	v_fma_f32 v153, -v109, v40, v153
	v_fma_f32 v154, -v110, v41, v154
	v_fma_f32 v155, -v111, v42, v155
	ds_read_b128 v[108:111], v28 offset:34272
	s_waitcnt lgkmcnt(11)
	v_fma_f32 v152, -v112, v43, v152
	v_fma_f32 v153, -v113, v44, v153
	v_fma_f32 v154, -v114, v45, v154
	v_fma_f32 v155, -v115, v46, v155
	ds_read_b128 v[112:115], v28 offset:34288
	s_waitcnt lgkmcnt(11)
	v_fma_f32 v152, -v116, v47, v152
	v_fma_f32 v153, -v117, v48, v153
	v_fma_f32 v154, -v118, v49, v154
	v_fma_f32 v155, -v119, v50, v155
	ds_read_b128 v[116:119], v28 offset:34304
	s_waitcnt lgkmcnt(11)
	v_fma_f32 v152, -v120, v51, v152
	v_fma_f32 v153, -v121, v52, v153
	v_fma_f32 v154, -v122, v53, v154
	v_fma_f32 v155, -v123, v54, v155
	ds_read_b128 v[120:123], v28 offset:34320
	s_waitcnt lgkmcnt(11)
	v_fma_f32 v152, -v124, v55, v152
	v_fma_f32 v153, -v125, v56, v153
	v_fma_f32 v154, -v126, v57, v154
	v_fma_f32 v155, -v127, v58, v155
	ds_read_b128 v[124:127], v28 offset:34336
	s_waitcnt lgkmcnt(11)
	v_fma_f32 v152, -v128, v59, v152
	v_fma_f32 v153, -v129, v60, v153
	v_fma_f32 v154, -v130, v61, v154
	v_fma_f32 v155, -v131, v62, v155
	ds_read_b128 v[128:131], v28 offset:34352
	s_waitcnt lgkmcnt(11)
	v_fma_f32 v152, -v132, v63, v152
	v_fma_f32 v153, -v133, v64, v153
	v_fma_f32 v154, -v134, v65, v154
	v_fma_f32 v155, -v135, v66, v155
	ds_read_b128 v[132:135], v28 offset:34368
	s_waitcnt lgkmcnt(11)
	v_fma_f32 v152, -v136, v67, v152
	v_fma_f32 v153, -v137, v68, v153
	v_fma_f32 v154, -v138, v69, v154
	v_fma_f32 v155, -v139, v70, v155
	ds_read_b128 v[136:139], v28 offset:34384
	s_waitcnt lgkmcnt(11)
	v_fma_f32 v152, -v140, v71, v152
	v_fma_f32 v153, -v141, v72, v153
	v_fma_f32 v154, -v142, v73, v154
	v_fma_f32 v155, -v143, v74, v155
	ds_read_b128 v[140:143], v28 offset:34400
	s_waitcnt lgkmcnt(11)
	v_fma_f32 v152, -v144, v75, v152
	v_fma_f32 v153, -v145, v76, v153
	v_fma_f32 v154, -v146, v77, v154
	v_fma_f32 v155, -v147, v78, v155
	ds_read_b128 v[144:147], v28 offset:34416
	s_waitcnt lgkmcnt(11)
	v_fma_f32 v152, -v100, v79, v152
	v_fma_f32 v153, -v101, v80, v153
	v_fma_f32 v154, -v102, v81, v154
	v_fma_f32 v155, -v103, v82, v155
	ds_read_b128 v[100:103], v28 offset:34432
	s_waitcnt lgkmcnt(11)
	v_fma_f32 v152, -v104, v83, v152
	v_fma_f32 v153, -v105, v84, v153
	v_fma_f32 v154, -v106, v85, v154
	v_fma_f32 v155, -v107, v86, v155
	ds_read_b128 v[104:107], v28 offset:34448
	s_waitcnt lgkmcnt(11)
	v_fma_f32 v152, -v108, v87, v152
	v_fma_f32 v153, -v109, v88, v153
	v_fma_f32 v154, -v110, v89, v154
	v_fma_f32 v155, -v111, v90, v155
	ds_read_b128 v[108:111], v28 offset:34464
	s_waitcnt lgkmcnt(11)
	v_fma_f32 v152, -v112, v91, v152
	ds_read_b128 v[112:115], v28 offset:34480
	v_add_f32_e32 v152, v152, v153
	v_add_f32_e32 v154, v154, v155
	v_add_f32_e32 v92, v152, v154
	v_cvt_pk_bf16_f32 v158, v92, v92
	global_store_short v[8:9], v158, off offset:3712
	v_cmp_eq_u32_e64 s[56:57], 62, v156
	s_waitcnt lgkmcnt(11)
	s_nop 0
	v_cndmask_b32_e64 v148, 0, 1.0, s[56:57]
	v_fma_f32 v148, -v31, v116, v148
	v_fma_f32 v149, -v117, v32, 0
	v_fma_f32 v150, -v118, v33, 0
	v_fma_f32 v151, -v119, v34, 0
	ds_read_b128 v[116:119], v28 offset:34496
	s_waitcnt lgkmcnt(11)
; #define LAS __attribute__((address_space(3)))
; __device__ __forceinline__ bf16_t f2bf(float f) { return (bf16_t)(pk2(f, f) & 0xFFFFu); }
; __device__ NOINL void g1_phase(const LAS Params* lp, int l, LAS unsigned char* lds) {
;     ...
;             float xv[64];
; #pragma unroll
;             for (int i = 0; i < 64; ++i) {
;                 float s0 = (i == lane) ? 1.f : 0.f, s1 = 0.f, s2 = 0.f, s3 = 0.f;
; #pragma unroll
;                 for (int j4 = 0; j4 < (i + 3) / 4; ++j4) {
;                     const f32x4 lv = *(const LAS f32x4*)(Ld + i * 64 + j4 * 4);
;                     if (j4 * 4 + 0 < i) s0 -= lv[0] * xv[j4 * 4 + 0];
;                     if (j4 * 4 + 1 < i) s1 -= lv[1] * xv[j4 * 4 + 1];
;                     if (j4 * 4 + 2 < i) s2 -= lv[2] * xv[j4 * 4 + 2];
;                     if (j4 * 4 + 3 < i) s3 -= lv[3] * xv[j4 * 4 + 3];
;                 }
;                 xv[i] = (s0 + s1) + (s2 + s3);
;             }
;             bf16_t* Tg = p.Tbuf + ((((size_t)b * 4 + h) * 36 + c3 * 3 + s) * 2 + dir) * 4096;
; #pragma unroll
;             for (int i = 0; i < 64; ++i) Tg[i * 64 + lane] = f2bf(xv[i]);
	v_fma_f32 v148, -v120, v35, v148
	v_fma_f32 v149, -v121, v36, v149
	v_fma_f32 v150, -v122, v37, v150
	v_fma_f32 v151, -v123, v38, v151
	ds_read_b128 v[120:123], v28 offset:34512
	s_waitcnt lgkmcnt(11)
	v_fma_f32 v148, -v124, v39, v148
	v_fma_f32 v149, -v125, v40, v149
	v_fma_f32 v150, -v126, v41, v150
	v_fma_f32 v151, -v127, v42, v151
	ds_read_b128 v[124:127], v28 offset:34528
	s_waitcnt lgkmcnt(11)
	v_fma_f32 v148, -v128, v43, v148
	v_fma_f32 v149, -v129, v44, v149
	v_fma_f32 v150, -v130, v45, v150
	v_fma_f32 v151, -v131, v46, v151
	ds_read_b128 v[128:131], v28 offset:34544
	s_waitcnt lgkmcnt(11)
	v_fma_f32 v148, -v132, v47, v148
	v_fma_f32 v149, -v133, v48, v149
	v_fma_f32 v150, -v134, v49, v150
	v_fma_f32 v151, -v135, v50, v151
	ds_read_b128 v[132:135], v28 offset:34560
	s_waitcnt lgkmcnt(11)
	v_fma_f32 v148, -v136, v51, v148
	v_fma_f32 v149, -v137, v52, v149
	v_fma_f32 v150, -v138, v53, v150
	v_fma_f32 v151, -v139, v54, v151
	ds_read_b128 v[136:139], v28 offset:34576
	s_waitcnt lgkmcnt(11)
	v_fma_f32 v148, -v140, v55, v148
	v_fma_f32 v149, -v141, v56, v149
	v_fma_f32 v150, -v142, v57, v150
	v_fma_f32 v151, -v143, v58, v151
	ds_read_b128 v[140:143], v28 offset:34592
	s_waitcnt lgkmcnt(11)
	v_fma_f32 v148, -v144, v59, v148
	v_fma_f32 v149, -v145, v60, v149
	v_fma_f32 v150, -v146, v61, v150
	v_fma_f32 v151, -v147, v62, v151
	ds_read_b128 v[144:147], v28 offset:34608
	s_waitcnt lgkmcnt(11)
	v_fma_f32 v148, -v100, v63, v148
	v_fma_f32 v149, -v101, v64, v149
	v_fma_f32 v150, -v102, v65, v150
	v_fma_f32 v151, -v103, v66, v151
	ds_read_b128 v[100:103], v28 offset:34624
	s_waitcnt lgkmcnt(11)
	v_fma_f32 v148, -v104, v67, v148
	v_fma_f32 v149, -v105, v68, v149
	v_fma_f32 v150, -v106, v69, v150
	v_fma_f32 v151, -v107, v70, v151
	ds_read_b128 v[104:107], v28 offset:34640
	s_waitcnt lgkmcnt(11)
	v_fma_f32 v148, -v108, v71, v148
	v_fma_f32 v149, -v109, v72, v149
	v_fma_f32 v150, -v110, v73, v150
	v_fma_f32 v151, -v111, v74, v151
	ds_read_b128 v[108:111], v28 offset:34656
	s_waitcnt lgkmcnt(11)
	v_fma_f32 v148, -v112, v75, v148
	v_fma_f32 v149, -v113, v76, v149
	v_fma_f32 v150, -v114, v77, v150
	v_fma_f32 v151, -v115, v78, v151
	ds_read_b128 v[112:115], v28 offset:34672
	s_waitcnt lgkmcnt(11)
	v_fma_f32 v148, -v116, v79, v148
	v_fma_f32 v149, -v117, v80, v149
	v_fma_f32 v150, -v118, v81, v150
	v_fma_f32 v151, -v119, v82, v151
	ds_read_b128 v[116:119], v28 offset:34688
	s_waitcnt lgkmcnt(11)
	v_fma_f32 v148, -v120, v83, v148
	v_fma_f32 v149, -v121, v84, v149
	v_fma_f32 v150, -v122, v85, v150
	v_fma_f32 v151, -v123, v86, v151
	ds_read_b128 v[120:123], v28 offset:34704
	s_waitcnt lgkmcnt(11)
	v_fma_f32 v148, -v124, v87, v148
	v_fma_f32 v149, -v125, v88, v149
	v_fma_f32 v150, -v126, v89, v150
	v_fma_f32 v151, -v127, v90, v151
	ds_read_b128 v[124:127], v28 offset:34720
	s_waitcnt lgkmcnt(11)
	v_fma_f32 v148, -v128, v91, v148
	v_fma_f32 v149, -v129, v92, v149
	ds_read_b128 v[128:131], v28 offset:34736
	v_add_f32_e32 v148, v148, v149
	v_add_f32_e32 v150, v150, v151
	v_add_f32_e32 v93, v148, v150
	v_cvt_pk_bf16_f32 v159, v93, v93
	global_store_short v[8:9], v159, off offset:3840
	v_cmp_eq_u32_e64 s[56:57], 63, v156
	s_waitcnt lgkmcnt(11)
	s_nop 0
	v_cndmask_b32_e64 v152, 0, 1.0, s[56:57]
	v_fma_f32 v152, -v31, v132, v152
	v_fma_f32 v153, -v133, v32, 0
	v_fma_f32 v154, -v134, v33, 0
	v_fma_f32 v155, -v135, v34, 0
	ds_read_b128 v[132:135], v28 offset:34752
	s_waitcnt lgkmcnt(11)
	v_fma_f32 v152, -v136, v35, v152
	v_fma_f32 v153, -v137, v36, v153
	v_fma_f32 v154, -v138, v37, v154
	v_fma_f32 v155, -v139, v38, v155
	ds_read_b128 v[136:139], v28 offset:34768
	s_waitcnt lgkmcnt(11)
	v_fma_f32 v152, -v140, v39, v152
	v_fma_f32 v153, -v141, v40, v153
	v_fma_f32 v154, -v142, v41, v154
	v_fma_f32 v155, -v143, v42, v155
	ds_read_b128 v[140:143], v28 offset:34784
	s_waitcnt lgkmcnt(11)
	v_fma_f32 v152, -v144, v43, v152
	v_fma_f32 v153, -v145, v44, v153
	v_fma_f32 v154, -v146, v45, v154
	v_fma_f32 v155, -v147, v46, v155
	ds_read_b128 v[144:147], v28 offset:34800
	s_waitcnt lgkmcnt(11)
	v_fma_f32 v152, -v100, v47, v152
	v_fma_f32 v153, -v101, v48, v153
	v_fma_f32 v154, -v102, v49, v154
	v_fma_f32 v155, -v103, v50, v155
	s_waitcnt lgkmcnt(10)
	v_fma_f32 v152, -v104, v51, v152
	v_fma_f32 v153, -v105, v52, v153
	v_fma_f32 v154, -v106, v53, v154
	v_fma_f32 v155, -v107, v54, v155
	s_waitcnt lgkmcnt(9)
	v_fma_f32 v152, -v108, v55, v152
	v_fma_f32 v153, -v109, v56, v153
	v_fma_f32 v154, -v110, v57, v154
	v_fma_f32 v155, -v111, v58, v155
	s_waitcnt lgkmcnt(8)
	v_fma_f32 v152, -v112, v59, v152
	v_fma_f32 v153, -v113, v60, v153
	v_fma_f32 v154, -v114, v61, v154
	v_fma_f32 v155, -v115, v62, v155
	s_waitcnt lgkmcnt(7)
	v_fma_f32 v152, -v116, v63, v152
	v_fma_f32 v153, -v117, v64, v153
	v_fma_f32 v154, -v118, v65, v154
	v_fma_f32 v155, -v119, v66, v155
	s_waitcnt lgkmcnt(6)
	v_fma_f32 v152, -v120, v67, v152
	v_fma_f32 v153, -v121, v68, v153
	v_fma_f32 v154, -v122, v69, v154
	v_fma_f32 v155, -v123, v70, v155
	s_waitcnt lgkmcnt(5)
	v_fma_f32 v152, -v124, v71, v152
	v_fma_f32 v153, -v125, v72, v153
	v_fma_f32 v154, -v126, v73, v154
	v_fma_f32 v155, -v127, v74, v155
	s_waitcnt lgkmcnt(4)
	v_fma_f32 v152, -v128, v75, v152
	v_fma_f32 v153, -v129, v76, v153
	v_fma_f32 v154, -v130, v77, v154
	v_fma_f32 v155, -v131, v78, v155
	s_waitcnt lgkmcnt(3)
	v_fma_f32 v152, -v132, v79, v152
	v_fma_f32 v153, -v133, v80, v153
	v_fma_f32 v154, -v134, v81, v154
	v_fma_f32 v155, -v135, v82, v155
	s_waitcnt lgkmcnt(2)
	v_fma_f32 v152, -v136, v83, v152
	v_fma_f32 v153, -v137, v84, v153
	v_fma_f32 v154, -v138, v85, v154
	v_fma_f32 v155, -v139, v86, v155
	s_waitcnt lgkmcnt(1)
	v_fma_f32 v152, -v140, v87, v152
	v_fma_f32 v153, -v141, v88, v153
	v_fma_f32 v154, -v142, v89, v154
	v_fma_f32 v155, -v143, v90, v155
	s_waitcnt lgkmcnt(0)
	v_fma_f32 v152, -v144, v91, v152
	v_fma_f32 v153, -v145, v92, v153
	v_fma_f32 v154, -v146, v93, v154
	v_add_f32_e32 v152, v152, v153
	v_add_f32_e32 v154, v154, v155
	v_add_f32_e32 v94, v152, v154
	v_cvt_pk_bf16_f32 v160, v94, v94
	global_store_short v[8:9], v160, off offset:3968
	s_branch .LBB0_1044
